# GEMM K-loops: scalar pointer increments and the trip compare moved from after the closing barrier to the tail of the MFMA cluster; only the branch follows the barrier
# speedup vs baseline: 1.0076x; 1.0076x over previous
; #define PG8_STAGE(bufoff, gbase, voff) do { _Pragma("unroll") for (int _i = 0; _i < 2; ++_i) \
;         __builtin_amdgcn_global_load_lds((const unsigned*)((const char*)(gbase) + (voff)[_i]), (PG8_LAS unsigned*)(lds + (bufoff) + ldsw + _i * 8192), 16, 0, 0); } while (0)
; #define PG8_LDA(dst, b, h) do { _Pragma("unroll") for (int m = 0; m < 4; ++m) _Pragma("unroll") for (int k = 0; k < 2; ++k) dst[m][k] = *(const PG8_LAS bf16x8*)(lds + PG8_SA(b, h) + aoff + m * 2048 + k * 1024); } while (0)
; #define PG8_LDB(dst, b, h) do { _Pragma("unroll") for (int n = 0; n < 2; ++n) _Pragma("unroll") for (int k = 0; k < 2; ++k) dst[n][k] = *(const PG8_LAS bf16x8*)(lds + PG8_SB(b, h) + boff + n * 2048 + k * 1024); } while (0)
; #define PG8_MMA(ai, bj, At, Bt) do { __builtin_amdgcn_s_setprio(1); _Pragma("unroll") for (int m = 0; m < 4; ++m) _Pragma("unroll") for (int n = 0; n < 2; ++n) _Pragma("unroll") for (int k = 0; k < 2; ++k) \
;         acc[ai][bj][m][n] = __builtin_amdgcn_mfma_f32_16x16x32_bf16(Bt[n][k], At[m][k], acc[ai][bj][m][n], 0, 0, 0); __builtin_amdgcn_s_setprio(0); } while (0)
; #define PG8_WAIT_V(n) asm volatile("s_waitcnt vmcnt(" #n ")" ::: "memory")
; #define PG8_WAIT_L(n) asm volatile("s_waitcnt lgkmcnt(" #n ")" ::: "memory")
; #define PG8_BAR __builtin_amdgcn_s_barrier()
; #define PG8_SCHED __builtin_amdgcn_sched_barrier(0)
; template <class Epi, class Sched, bool ALIGN_EPI = false, bool SP2 = false>
; __device__ __forceinline__ void gemm_phase(PG8_LAS unsigned char* lds, const Gemm g, const Sched& S, const Epi& E) {
;     ...
;             if constexpr (SP2) {
;             PG8_LDB(B0, 0, 0); PG8_LDB(B1, 0, 1); PG8_SCHED; PG8_LDA(At, 0, 0); PG8_STAGE(PG8_SA(1, 1), a1 + hstep, voffA);
;             PG8_WAIT_V(8); PG8_WAIT_L(0); PG8_BAR; PG8_MMA(0, 0, At, B0); PG8_MMA(0, 1, At, B1); PG8_BAR; PG8_SCHED;
;             PG8_LDA(At, 0, 1); PG8_STAGE(PG8_SB(0, 0), b2, voffB); PG8_STAGE(PG8_SB(0, 1), b2 + hstep, voffB); PG8_STAGE(PG8_SA(0, 0), a2, voffA);
;             PG8_WAIT_V(8); PG8_WAIT_L(0); PG8_BAR; PG8_MMA(1, 0, At, B0); PG8_MMA(1, 1, At, B1); PG8_BAR; PG8_SCHED;
.LBB0_201:
	ds_read_b128 v[150:153], v147
	ds_read_b128 v[154:157], v147 offset:1024
	ds_read_b128 v[158:161], v147 offset:2048
	ds_read_b128 v[162:165], v147 offset:3072
	ds_read_b128 v[166:169], v148
	ds_read_b128 v[170:173], v148 offset:1024
	ds_read_b128 v[174:177], v148 offset:2048
	ds_read_b128 v[178:181], v148 offset:3072
	s_add_u32 s10, s8, 0xfff80080
	s_addc_u32 s11, s9, -1
	s_cmp_eq_u32 s51, 28
	s_cselect_b32 s27, s19, s11
	s_cselect_b32 s26, s47, s10
	s_cselect_b32 s11, s17, s50
	s_cselect_b32 s10, s48, s49
	v_lshl_add_u64 v[214:215], s[8:9], 0, v[136:137]
	s_add_i32 m0, s25, 0xc000
	ds_read_b128 v[182:185], v149
	ds_read_b128 v[186:189], v149 offset:1024
	ds_read_b128 v[190:193], v149 offset:2048
	ds_read_b128 v[194:197], v149 offset:3072
	ds_read_b128 v[198:201], v149 offset:4096
	ds_read_b128 v[202:205], v149 offset:5120
	ds_read_b128 v[206:209], v149 offset:6144
	ds_read_b128 v[210:213], v149 offset:7168
	global_load_lds_dwordx4 v[214:215], off
	v_lshl_add_u64 v[214:215], s[8:9], 0, v[138:139]
	s_add_i32 m0, s25, 0xe000
	s_nop 0
	global_load_lds_dwordx4 v[214:215], off
	s_waitcnt vmcnt(8)
	s_waitcnt lgkmcnt(0)
	s_barrier
	s_setprio 1
	s_waitcnt lgkmcnt(0)
	v_mfma_f32_16x16x32_bf16 v[124:127], v[150:153], v[182:185], v[124:127]
	v_mfma_f32_16x16x32_bf16 v[120:123], v[158:161], v[182:185], v[120:123]
	v_mfma_f32_16x16x32_bf16 v[116:119], v[150:153], v[190:193], v[116:119]
	v_mfma_f32_16x16x32_bf16 v[108:111], v[158:161], v[190:193], v[108:111]
	v_mfma_f32_16x16x32_bf16 v[100:103], v[150:153], v[198:201], v[100:103]
	v_mfma_f32_16x16x32_bf16 v[92:95], v[158:161], v[198:201], v[92:95]
	v_mfma_f32_16x16x32_bf16 v[84:87], v[150:153], v[206:209], v[84:87]
	v_mfma_f32_16x16x32_bf16 v[76:79], v[158:161], v[206:209], v[76:79]
	v_mfma_f32_16x16x32_bf16 v[124:127], v[154:157], v[186:189], v[124:127]
	v_mfma_f32_16x16x32_bf16 v[120:123], v[162:165], v[186:189], v[120:123]
	v_mfma_f32_16x16x32_bf16 v[116:119], v[154:157], v[194:197], v[116:119]
	v_mfma_f32_16x16x32_bf16 v[108:111], v[162:165], v[194:197], v[108:111]
	v_mfma_f32_16x16x32_bf16 v[100:103], v[154:157], v[202:205], v[100:103]
	v_mfma_f32_16x16x32_bf16 v[92:95], v[162:165], v[202:205], v[92:95]
	v_mfma_f32_16x16x32_bf16 v[84:87], v[154:157], v[210:213], v[84:87]
	v_mfma_f32_16x16x32_bf16 v[76:79], v[162:165], v[210:213], v[76:79]
	s_setprio 0
	s_setprio 1
	v_mfma_f32_16x16x32_bf16 v[112:115], v[166:169], v[182:185], v[112:115]
	v_mfma_f32_16x16x32_bf16 v[104:107], v[174:177], v[182:185], v[104:107]
	v_mfma_f32_16x16x32_bf16 v[96:99], v[166:169], v[190:193], v[96:99]
	v_mfma_f32_16x16x32_bf16 v[88:91], v[174:177], v[190:193], v[88:91]
	v_mfma_f32_16x16x32_bf16 v[80:83], v[166:169], v[198:201], v[80:83]
	v_mfma_f32_16x16x32_bf16 v[72:75], v[174:177], v[198:201], v[72:75]
	v_mfma_f32_16x16x32_bf16 v[68:71], v[166:169], v[206:209], v[68:71]
	v_mfma_f32_16x16x32_bf16 v[64:67], v[174:177], v[206:209], v[64:67]
	v_mfma_f32_16x16x32_bf16 v[112:115], v[170:173], v[186:189], v[112:115]
	v_mfma_f32_16x16x32_bf16 v[104:107], v[178:181], v[186:189], v[104:107]
	v_mfma_f32_16x16x32_bf16 v[96:99], v[170:173], v[194:197], v[96:99]
	v_mfma_f32_16x16x32_bf16 v[88:91], v[178:181], v[194:197], v[88:91]
	v_mfma_f32_16x16x32_bf16 v[80:83], v[170:173], v[202:205], v[80:83]
	v_mfma_f32_16x16x32_bf16 v[72:75], v[178:181], v[202:205], v[72:75]
	v_mfma_f32_16x16x32_bf16 v[68:71], v[170:173], v[210:213], v[68:71]
	v_mfma_f32_16x16x32_bf16 v[64:67], v[178:181], v[210:213], v[64:67]
	s_setprio 0
	s_barrier
	s_add_i32 s52, s43, s30
	v_lshl_add_u64 v[214:215], s[10:11], 0, v[132:133]
	s_mov_b32 m0, s52
	ds_read_b128 v[182:185], v149 offset:16384
	ds_read_b128 v[186:189], v149 offset:17408
	ds_read_b128 v[190:193], v149 offset:18432
	ds_read_b128 v[194:197], v149 offset:19456
	ds_read_b128 v[198:201], v149 offset:20480
	ds_read_b128 v[202:205], v149 offset:21504
	ds_read_b128 v[206:209], v149 offset:22528
	ds_read_b128 v[210:213], v149 offset:23552
	global_load_lds_dwordx4 v[214:215], off
	s_add_i32 m0, s52, 0x2000
	s_add_u32 s52, s10, 0x80000
	v_lshl_add_u64 v[216:217], s[10:11], 0, v[128:129]
	s_addc_u32 s53, s11, 0
	s_add_i32 s54, s44, s30
	global_load_lds_dwordx4 v[216:217], off
	v_lshl_add_u64 v[222:223], s[52:53], 0, v[132:133]
	s_mov_b32 m0, s54
	v_lshl_add_u64 v[224:225], s[26:27], 0, v[130:131]
	global_load_lds_dwordx4 v[222:223], off
	v_lshl_add_u64 v[222:223], s[52:53], 0, v[128:129]
	s_add_i32 m0, s54, 0x2000
	s_nop 0
	global_load_lds_dwordx4 v[222:223], off
	v_lshl_add_u64 v[222:223], s[26:27], 0, v[134:135]
	s_mov_b32 m0, s25
	s_nop 0
	global_load_lds_dwordx4 v[222:223], off
	s_mov_b32 m0, s34
	s_nop 0
	global_load_lds_dwordx4 v[224:225], off
	s_waitcnt vmcnt(8)
	s_waitcnt lgkmcnt(0)
	s_barrier
; #define PG8_STAGE(bufoff, gbase, voff) do { _Pragma("unroll") for (int _i = 0; _i < 2; ++_i) \
;         __builtin_amdgcn_global_load_lds((const unsigned*)((const char*)(gbase) + (voff)[_i]), (PG8_LAS unsigned*)(lds + (bufoff) + ldsw + _i * 8192), 16, 0, 0); } while (0)
; #define PG8_LDA(dst, b, h) do { _Pragma("unroll") for (int m = 0; m < 4; ++m) _Pragma("unroll") for (int k = 0; k < 2; ++k) dst[m][k] = *(const PG8_LAS bf16x8*)(lds + PG8_SA(b, h) + aoff + m * 2048 + k * 1024); } while (0)
; #define PG8_LDB(dst, b, h) do { _Pragma("unroll") for (int n = 0; n < 2; ++n) _Pragma("unroll") for (int k = 0; k < 2; ++k) dst[n][k] = *(const PG8_LAS bf16x8*)(lds + PG8_SB(b, h) + boff + n * 2048 + k * 1024); } while (0)
; #define PG8_MMA(ai, bj, At, Bt) do { __builtin_amdgcn_s_setprio(1); _Pragma("unroll") for (int m = 0; m < 4; ++m) _Pragma("unroll") for (int n = 0; n < 2; ++n) _Pragma("unroll") for (int k = 0; k < 2; ++k) \
;         acc[ai][bj][m][n] = __builtin_amdgcn_mfma_f32_16x16x32_bf16(Bt[n][k], At[m][k], acc[ai][bj][m][n], 0, 0, 0); __builtin_amdgcn_s_setprio(0); } while (0)
; #define PG8_WAIT_V(n) asm volatile("s_waitcnt vmcnt(" #n ")" ::: "memory")
; #define PG8_WAIT_L(n) asm volatile("s_waitcnt lgkmcnt(" #n ")" ::: "memory")
; #define PG8_BAR __builtin_amdgcn_s_barrier()
; #define PG8_SCHED __builtin_amdgcn_sched_barrier(0)
; template <class Epi, class Sched, bool ALIGN_EPI = false, bool SP2 = false>
; __device__ __forceinline__ void gemm_phase(PG8_LAS unsigned char* lds, const Gemm g, const Sched& S, const Epi& E) {
;     ...
;             PG8_WAIT_V(8); PG8_WAIT_L(0); PG8_BAR; PG8_MMA(1, 0, At, B0); PG8_MMA(1, 1, At, B1); PG8_BAR; PG8_SCHED;
;             PG8_LDB(B0, 1, 0); PG8_LDB(B1, 1, 1); PG8_SCHED; PG8_LDA(At, 1, 0); PG8_STAGE(PG8_SA(0, 1), a2 + hstep, voffA);
;             PG8_WAIT_V(8); PG8_WAIT_L(0); PG8_BAR; PG8_MMA(0, 0, At, B0); PG8_MMA(0, 1, At, B1); PG8_BAR; PG8_SCHED;
	s_setprio 1
	s_waitcnt lgkmcnt(0)
	v_mfma_f32_16x16x32_bf16 v[60:63], v[150:153], v[182:185], v[60:63]
	v_mfma_f32_16x16x32_bf16 v[56:59], v[158:161], v[182:185], v[56:59]
	v_mfma_f32_16x16x32_bf16 v[52:55], v[150:153], v[190:193], v[52:55]
	v_mfma_f32_16x16x32_bf16 v[44:47], v[158:161], v[190:193], v[44:47]
	v_mfma_f32_16x16x32_bf16 v[36:39], v[150:153], v[198:201], v[36:39]
	v_mfma_f32_16x16x32_bf16 v[28:31], v[158:161], v[198:201], v[28:31]
	v_mfma_f32_16x16x32_bf16 v[20:23], v[150:153], v[206:209], v[20:23]
	v_mfma_f32_16x16x32_bf16 v[12:15], v[158:161], v[206:209], v[12:15]
	v_mfma_f32_16x16x32_bf16 v[60:63], v[154:157], v[186:189], v[60:63]
	v_mfma_f32_16x16x32_bf16 v[56:59], v[162:165], v[186:189], v[56:59]
	v_mfma_f32_16x16x32_bf16 v[52:55], v[154:157], v[194:197], v[52:55]
	v_mfma_f32_16x16x32_bf16 v[44:47], v[162:165], v[194:197], v[44:47]
	v_mfma_f32_16x16x32_bf16 v[36:39], v[154:157], v[202:205], v[36:39]
	v_mfma_f32_16x16x32_bf16 v[28:31], v[162:165], v[202:205], v[28:31]
	v_mfma_f32_16x16x32_bf16 v[20:23], v[154:157], v[210:213], v[20:23]
	v_mfma_f32_16x16x32_bf16 v[12:15], v[162:165], v[210:213], v[12:15]
	s_setprio 0
	s_setprio 1
	v_mfma_f32_16x16x32_bf16 v[48:51], v[166:169], v[182:185], v[48:51]
	v_mfma_f32_16x16x32_bf16 v[40:43], v[174:177], v[182:185], v[40:43]
	v_mfma_f32_16x16x32_bf16 v[32:35], v[166:169], v[190:193], v[32:35]
	v_mfma_f32_16x16x32_bf16 v[24:27], v[174:177], v[190:193], v[24:27]
	v_mfma_f32_16x16x32_bf16 v[16:19], v[166:169], v[198:201], v[16:19]
	v_mfma_f32_16x16x32_bf16 v[8:11], v[174:177], v[198:201], v[8:11]
	v_mfma_f32_16x16x32_bf16 v[4:7], v[166:169], v[206:209], v[4:7]
	v_mfma_f32_16x16x32_bf16 v[0:3], v[174:177], v[206:209], v[0:3]
	v_mfma_f32_16x16x32_bf16 v[48:51], v[170:173], v[186:189], v[48:51]
	v_mfma_f32_16x16x32_bf16 v[40:43], v[178:181], v[186:189], v[40:43]
	v_mfma_f32_16x16x32_bf16 v[32:35], v[170:173], v[194:197], v[32:35]
	v_mfma_f32_16x16x32_bf16 v[24:27], v[178:181], v[194:197], v[24:27]
	v_mfma_f32_16x16x32_bf16 v[16:19], v[170:173], v[202:205], v[16:19]
	v_mfma_f32_16x16x32_bf16 v[8:11], v[178:181], v[202:205], v[8:11]
	v_mfma_f32_16x16x32_bf16 v[4:7], v[170:173], v[210:213], v[4:7]
	v_mfma_f32_16x16x32_bf16 v[0:3], v[178:181], v[210:213], v[0:3]
	s_setprio 0
	s_barrier
	s_add_i32 s52, 0, 0x18000
	s_add_i32 s53, 0, 0x1c000
	v_add_u32_e32 v162, s52, v145
	v_add_u32_e32 v178, s53, v145
	ds_read_b128 v[150:153], v162
	ds_read_b128 v[154:157], v162 offset:1024
	ds_read_b128 v[158:161], v162 offset:2048
	ds_read_b128 v[162:165], v162 offset:3072
	ds_read_b128 v[166:169], v178
	ds_read_b128 v[170:173], v178 offset:1024
	ds_read_b128 v[174:177], v178 offset:2048
	ds_read_b128 v[178:181], v178 offset:3072
	s_add_u32 s26, s26, 0x80000
	s_addc_u32 s27, s27, 0
	s_mov_b32 m0, s35
	v_lshl_add_u64 v[226:227], s[26:27], 0, v[134:135]
	ds_read_b128 v[182:185], v149 offset:32768
	ds_read_b128 v[186:189], v149 offset:33792
	ds_read_b128 v[190:193], v149 offset:34816
	ds_read_b128 v[194:197], v149 offset:35840
	ds_read_b128 v[198:201], v149 offset:36864
	ds_read_b128 v[202:205], v149 offset:37888
	ds_read_b128 v[206:209], v149 offset:38912
	ds_read_b128 v[210:213], v149 offset:39936
	global_load_lds_dwordx4 v[226:227], off
	v_lshl_add_u64 v[226:227], s[26:27], 0, v[130:131]
	s_mov_b32 m0, s36
	s_nop 0
	global_load_lds_dwordx4 v[226:227], off
	s_waitcnt vmcnt(8)
	s_waitcnt lgkmcnt(0)
	s_barrier
	s_setprio 1
	s_waitcnt lgkmcnt(0)
	v_mfma_f32_16x16x32_bf16 v[124:127], v[150:153], v[182:185], v[124:127]
	v_mfma_f32_16x16x32_bf16 v[120:123], v[158:161], v[182:185], v[120:123]
	v_mfma_f32_16x16x32_bf16 v[116:119], v[150:153], v[190:193], v[116:119]
	v_mfma_f32_16x16x32_bf16 v[108:111], v[158:161], v[190:193], v[108:111]
	v_mfma_f32_16x16x32_bf16 v[100:103], v[150:153], v[198:201], v[100:103]
	v_mfma_f32_16x16x32_bf16 v[92:95], v[158:161], v[198:201], v[92:95]
	v_mfma_f32_16x16x32_bf16 v[84:87], v[150:153], v[206:209], v[84:87]
	v_mfma_f32_16x16x32_bf16 v[76:79], v[158:161], v[206:209], v[76:79]
	v_mfma_f32_16x16x32_bf16 v[124:127], v[154:157], v[186:189], v[124:127]
	v_mfma_f32_16x16x32_bf16 v[120:123], v[162:165], v[186:189], v[120:123]
	v_mfma_f32_16x16x32_bf16 v[116:119], v[154:157], v[194:197], v[116:119]
	v_mfma_f32_16x16x32_bf16 v[108:111], v[162:165], v[194:197], v[108:111]
	v_mfma_f32_16x16x32_bf16 v[100:103], v[154:157], v[202:205], v[100:103]
	v_mfma_f32_16x16x32_bf16 v[92:95], v[162:165], v[202:205], v[92:95]
	v_mfma_f32_16x16x32_bf16 v[84:87], v[154:157], v[210:213], v[84:87]
	v_mfma_f32_16x16x32_bf16 v[76:79], v[162:165], v[210:213], v[76:79]
	s_setprio 0
	s_setprio 1
	v_mfma_f32_16x16x32_bf16 v[112:115], v[166:169], v[182:185], v[112:115]
	v_mfma_f32_16x16x32_bf16 v[104:107], v[174:177], v[182:185], v[104:107]
	v_mfma_f32_16x16x32_bf16 v[96:99], v[166:169], v[190:193], v[96:99]
	v_mfma_f32_16x16x32_bf16 v[88:91], v[174:177], v[190:193], v[88:91]
	v_mfma_f32_16x16x32_bf16 v[80:83], v[166:169], v[198:201], v[80:83]
	v_mfma_f32_16x16x32_bf16 v[72:75], v[174:177], v[198:201], v[72:75]
	v_mfma_f32_16x16x32_bf16 v[68:71], v[166:169], v[206:209], v[68:71]
	v_mfma_f32_16x16x32_bf16 v[64:67], v[174:177], v[206:209], v[64:67]
	v_mfma_f32_16x16x32_bf16 v[112:115], v[170:173], v[186:189], v[112:115]
	v_mfma_f32_16x16x32_bf16 v[104:107], v[178:181], v[186:189], v[104:107]
	v_mfma_f32_16x16x32_bf16 v[96:99], v[170:173], v[194:197], v[96:99]
	v_mfma_f32_16x16x32_bf16 v[88:91], v[178:181], v[194:197], v[88:91]
	v_mfma_f32_16x16x32_bf16 v[80:83], v[170:173], v[202:205], v[80:83]
	v_mfma_f32_16x16x32_bf16 v[72:75], v[178:181], v[202:205], v[72:75]
	v_mfma_f32_16x16x32_bf16 v[68:71], v[170:173], v[210:213], v[68:71]
	v_mfma_f32_16x16x32_bf16 v[64:67], v[178:181], v[210:213], v[64:67]
	s_setprio 0
	s_barrier
; #define PG8_STAGE(bufoff, gbase, voff) do { _Pragma("unroll") for (int _i = 0; _i < 2; ++_i) \
;         __builtin_amdgcn_global_load_lds((const unsigned*)((const char*)(gbase) + (voff)[_i]), (PG8_LAS unsigned*)(lds + (bufoff) + ldsw + _i * 8192), 16, 0, 0); } while (0)
; #define PG8_LDA(dst, b, h) do { _Pragma("unroll") for (int m = 0; m < 4; ++m) _Pragma("unroll") for (int k = 0; k < 2; ++k) dst[m][k] = *(const PG8_LAS bf16x8*)(lds + PG8_SA(b, h) + aoff + m * 2048 + k * 1024); } while (0)
; #define PG8_MMA(ai, bj, At, Bt) do { __builtin_amdgcn_s_setprio(1); _Pragma("unroll") for (int m = 0; m < 4; ++m) _Pragma("unroll") for (int n = 0; n < 2; ++n) _Pragma("unroll") for (int k = 0; k < 2; ++k) \
;         acc[ai][bj][m][n] = __builtin_amdgcn_mfma_f32_16x16x32_bf16(Bt[n][k], At[m][k], acc[ai][bj][m][n], 0, 0, 0); __builtin_amdgcn_s_setprio(0); } while (0)
; #define PG8_WAIT_V(n) asm volatile("s_waitcnt vmcnt(" #n ")" ::: "memory")
; #define PG8_WAIT_L(n) asm volatile("s_waitcnt lgkmcnt(" #n ")" ::: "memory")
; #define PG8_BAR __builtin_amdgcn_s_barrier()
; #define PG8_SCHED __builtin_amdgcn_sched_barrier(0)
; template <class Epi, class Sched, bool ALIGN_EPI = false, bool SP2 = false>
; __device__ __forceinline__ void gemm_phase(PG8_LAS unsigned char* lds, const Gemm g, const Sched& S, const Epi& E) {
;     ...
;         for (int t = 0; t < nt; t += 2) {
;             const bool last = (t == nt - 2);
;             const char* a1 = cA + (size_t)(t + 1) * kstep;
;             const char* a2 = last ? nA : cA + (size_t)(t + 2) * kstep; const char* b2 = last ? nB : cB + (size_t)(t + 2) * kstep;
;     ...
;             PG8_LDA(At, 1, 1); PG8_STAGE(PG8_SB(1, 0), b3, voffB); PG8_STAGE(PG8_SB(1, 1), b3 + hstep, voffB); PG8_STAGE(PG8_SA(1, 0), a3, voffA);
;             PG8_WAIT_V(8); PG8_WAIT_L(0); PG8_BAR; PG8_MMA(1, 0, At, B0); PG8_MMA(1, 1, At, B1); PG8_BAR; PG8_SCHED;
	s_add_i32 s26, s52, s30
	v_lshl_add_u64 v[214:215], v[214:215], 0, s[12:13]
	s_mov_b32 m0, s26
	ds_read_b128 v[182:185], v149 offset:49152
	ds_read_b128 v[186:189], v149 offset:50176
	ds_read_b128 v[190:193], v149 offset:51200
	ds_read_b128 v[194:197], v149 offset:52224
	ds_read_b128 v[198:201], v149 offset:53248
	ds_read_b128 v[202:205], v149 offset:54272
	ds_read_b128 v[206:209], v149 offset:55296
	ds_read_b128 v[210:213], v149 offset:56320
	global_load_lds_dwordx4 v[214:215], off
	s_add_i32 m0, s26, 0x2000
	s_add_u32 s10, s10, 0x80080
	v_lshl_add_u64 v[214:215], v[216:217], 0, s[12:13]
	s_addc_u32 s11, s11, 0
	s_add_i32 s26, s53, s30
	global_load_lds_dwordx4 v[214:215], off
	v_lshl_add_u64 v[214:215], s[10:11], 0, v[132:133]
	s_mov_b32 m0, s26
	s_nop 0
	global_load_lds_dwordx4 v[214:215], off
	v_lshl_add_u64 v[214:215], s[10:11], 0, v[128:129]
	s_add_i32 m0, s26, 0x2000
	s_nop 0
	global_load_lds_dwordx4 v[214:215], off
	v_lshl_add_u64 v[214:215], v[222:223], 0, s[12:13]
	s_mov_b32 m0, s40
	s_nop 0
	global_load_lds_dwordx4 v[214:215], off
	v_lshl_add_u64 v[214:215], v[224:225], 0, s[12:13]
	s_mov_b32 m0, s41
	s_nop 0
	global_load_lds_dwordx4 v[214:215], off
	s_waitcnt vmcnt(8)
	s_waitcnt lgkmcnt(0)
	s_barrier
	s_setprio 1
	s_waitcnt lgkmcnt(0)
	v_mfma_f32_16x16x32_bf16 v[60:63], v[150:153], v[182:185], v[60:63]
	v_mfma_f32_16x16x32_bf16 v[56:59], v[158:161], v[182:185], v[56:59]
	v_mfma_f32_16x16x32_bf16 v[52:55], v[150:153], v[190:193], v[52:55]
	v_mfma_f32_16x16x32_bf16 v[44:47], v[158:161], v[190:193], v[44:47]
	v_mfma_f32_16x16x32_bf16 v[36:39], v[150:153], v[198:201], v[36:39]
	v_mfma_f32_16x16x32_bf16 v[28:31], v[158:161], v[198:201], v[28:31]
	v_mfma_f32_16x16x32_bf16 v[20:23], v[150:153], v[206:209], v[20:23]
	v_mfma_f32_16x16x32_bf16 v[12:15], v[158:161], v[206:209], v[12:15]
	v_mfma_f32_16x16x32_bf16 v[60:63], v[154:157], v[186:189], v[60:63]
	v_mfma_f32_16x16x32_bf16 v[56:59], v[162:165], v[186:189], v[56:59]
	v_mfma_f32_16x16x32_bf16 v[52:55], v[154:157], v[194:197], v[52:55]
	v_mfma_f32_16x16x32_bf16 v[44:47], v[162:165], v[194:197], v[44:47]
	v_mfma_f32_16x16x32_bf16 v[36:39], v[154:157], v[202:205], v[36:39]
	v_mfma_f32_16x16x32_bf16 v[28:31], v[162:165], v[202:205], v[28:31]
	v_mfma_f32_16x16x32_bf16 v[20:23], v[154:157], v[210:213], v[20:23]
	v_mfma_f32_16x16x32_bf16 v[12:15], v[162:165], v[210:213], v[12:15]
	s_setprio 0
	s_setprio 1
	v_mfma_f32_16x16x32_bf16 v[48:51], v[166:169], v[182:185], v[48:51]
	v_mfma_f32_16x16x32_bf16 v[40:43], v[174:177], v[182:185], v[40:43]
	v_mfma_f32_16x16x32_bf16 v[32:35], v[166:169], v[190:193], v[32:35]
	v_mfma_f32_16x16x32_bf16 v[24:27], v[174:177], v[190:193], v[24:27]
	v_mfma_f32_16x16x32_bf16 v[16:19], v[166:169], v[198:201], v[16:19]
	v_mfma_f32_16x16x32_bf16 v[8:11], v[174:177], v[198:201], v[8:11]
	v_mfma_f32_16x16x32_bf16 v[4:7], v[166:169], v[206:209], v[4:7]
	v_mfma_f32_16x16x32_bf16 v[0:3], v[174:177], v[206:209], v[0:3]
	v_mfma_f32_16x16x32_bf16 v[48:51], v[170:173], v[186:189], v[48:51]
	v_mfma_f32_16x16x32_bf16 v[40:43], v[178:181], v[186:189], v[40:43]
	v_mfma_f32_16x16x32_bf16 v[32:35], v[170:173], v[194:197], v[32:35]
	v_mfma_f32_16x16x32_bf16 v[24:27], v[178:181], v[194:197], v[24:27]
	v_mfma_f32_16x16x32_bf16 v[16:19], v[170:173], v[202:205], v[16:19]
	v_mfma_f32_16x16x32_bf16 v[8:11], v[178:181], v[202:205], v[8:11]
	v_mfma_f32_16x16x32_bf16 v[4:7], v[170:173], v[210:213], v[4:7]
	v_mfma_f32_16x16x32_bf16 v[0:3], v[178:181], v[210:213], v[0:3]
	s_add_i32 s51, s51, 2
	s_add_u32 s8, s8, 0x100
	s_addc_u32 s9, s9, 0
	s_add_u32 s49, s49, 0x100
	s_addc_u32 s50, s50, 0
	s_cmp_gt_u32 s51, 29
	s_setprio 0
	s_barrier
	s_cbranch_scc0 .LBB0_201
	s_and_b64 vcc, exec, s[14:15]
	s_cbranch_vccz .LBB0_204
	s_barrier

; #define PG8_STAGE(bufoff, gbase, voff) do { _Pragma("unroll") for (int _i = 0; _i < 2; ++_i) \
;         __builtin_amdgcn_global_load_lds((const unsigned*)((const char*)(gbase) + (voff)[_i]), (PG8_LAS unsigned*)(lds + (bufoff) + ldsw + _i * 8192), 16, 0, 0); } while (0)
; #define PG8_LDA(dst, b, h) do { _Pragma("unroll") for (int m = 0; m < 4; ++m) _Pragma("unroll") for (int k = 0; k < 2; ++k) dst[m][k] = *(const PG8_LAS bf16x8*)(lds + PG8_SA(b, h) + aoff + m * 2048 + k * 1024); } while (0)
; #define PG8_LDB(dst, b, h) do { _Pragma("unroll") for (int n = 0; n < 2; ++n) _Pragma("unroll") for (int k = 0; k < 2; ++k) dst[n][k] = *(const PG8_LAS bf16x8*)(lds + PG8_SB(b, h) + boff + n * 2048 + k * 1024); } while (0)
; #define PG8_MMA(ai, bj, At, Bt) do { __builtin_amdgcn_s_setprio(1); _Pragma("unroll") for (int m = 0; m < 4; ++m) _Pragma("unroll") for (int n = 0; n < 2; ++n) _Pragma("unroll") for (int k = 0; k < 2; ++k) \
;         acc[ai][bj][m][n] = __builtin_amdgcn_mfma_f32_16x16x32_bf16(Bt[n][k], At[m][k], acc[ai][bj][m][n], 0, 0, 0); __builtin_amdgcn_s_setprio(0); } while (0)
; #define PG8_WAIT_V(n) asm volatile("s_waitcnt vmcnt(" #n ")" ::: "memory")
; #define PG8_WAIT_L(n) asm volatile("s_waitcnt lgkmcnt(" #n ")" ::: "memory")
; template <class Epi, class Sched, bool ALIGN_EPI = false, bool SP2 = false>
; __device__ __forceinline__ void gemm_phase(PG8_LAS unsigned char* lds, const Gemm g, const Sched& S, const Epi& E) {
;     ...
;             const bool last = (t == nt - 2);
;             const char* a1 = cA + (size_t)(t + 1) * kstep;
;             const char* a2 = last ? nA : cA + (size_t)(t + 2) * kstep; const char* b2 = last ? nB : cB + (size_t)(t + 2) * kstep;
;             const char* a3 = a2 + kstep; const char* b3 = b2 + kstep;
;             if (last && has_next) S.a_ready(nxt);
;             if constexpr (SP2) {
;             PG8_LDB(B0, 0, 0); PG8_LDB(B1, 0, 1); PG8_SCHED; PG8_LDA(At, 0, 0); PG8_STAGE(PG8_SA(1, 1), a1 + hstep, voffA);
;             PG8_WAIT_V(8); PG8_WAIT_L(0); PG8_BAR; PG8_MMA(0, 0, At, B0); PG8_MMA(0, 1, At, B1); PG8_BAR; PG8_SCHED;
;             PG8_LDA(At, 0, 1); PG8_STAGE(PG8_SB(0, 0), b2, voffB); PG8_STAGE(PG8_SB(0, 1), b2 + hstep, voffB); PG8_STAGE(PG8_SA(0, 0), a2, voffA);
;             PG8_WAIT_V(8); PG8_WAIT_L(0); PG8_BAR; PG8_MMA(1, 0, At, B0); PG8_MMA(1, 1, At, B1); PG8_BAR; PG8_SCHED;
.LBB0_1027:
	ds_read_b128 v[104:107], v167
	ds_read_b128 v[108:111], v167 offset:1024
	ds_read_b128 v[152:155], v167 offset:2048
	ds_read_b128 v[156:159], v167 offset:3072
	ds_read_b128 v[160:163], v168
	ds_read_b128 v[170:173], v168 offset:1024
	ds_read_b128 v[174:177], v168 offset:2048
	ds_read_b128 v[178:181], v168 offset:3072
	s_add_u32 s10, s8, 0xfff80080
	s_addc_u32 s11, s9, -1
	s_cmp_eq_u32 s57, 28
	s_cselect_b32 s21, s37, s11
	s_cselect_b32 s20, s40, s10
	s_cselect_b32 s11, s41, s56
	s_cselect_b32 s10, s49, s51
	v_lshl_add_u64 v[214:215], s[8:9], 0, v[144:145]
	s_add_i32 m0, s17, 0xc000
	ds_read_b128 v[182:185], v169
	ds_read_b128 v[186:189], v169 offset:1024
	ds_read_b128 v[190:193], v169 offset:2048
	ds_read_b128 v[194:197], v169 offset:3072
	ds_read_b128 v[198:201], v169 offset:4096
	ds_read_b128 v[202:205], v169 offset:5120
	ds_read_b128 v[206:209], v169 offset:6144
	ds_read_b128 v[210:213], v169 offset:7168
	global_load_lds_dwordx4 v[214:215], off
	v_lshl_add_u64 v[214:215], s[8:9], 0, v[146:147]
	s_add_i32 m0, s17, 0xe000
	s_nop 0
	global_load_lds_dwordx4 v[214:215], off
	s_waitcnt vmcnt(8)
	s_waitcnt lgkmcnt(0)
	s_barrier
	s_setprio 1
	s_waitcnt lgkmcnt(0)
	v_mfma_f32_16x16x32_bf16 v[132:135], v[104:107], v[182:185], v[132:135]
	v_mfma_f32_16x16x32_bf16 v[128:131], v[152:155], v[182:185], v[128:131]
	v_mfma_f32_16x16x32_bf16 v[124:127], v[104:107], v[190:193], v[124:127]
	v_mfma_f32_16x16x32_bf16 v[120:123], v[152:155], v[190:193], v[120:123]
	v_mfma_f32_16x16x32_bf16 v[116:119], v[104:107], v[198:201], v[116:119]
	v_mfma_f32_16x16x32_bf16 v[112:115], v[152:155], v[198:201], v[112:115]
	v_mfma_f32_16x16x32_bf16 v[100:103], v[104:107], v[206:209], v[100:103]
	v_mfma_f32_16x16x32_bf16 v[96:99], v[152:155], v[206:209], v[96:99]
	v_mfma_f32_16x16x32_bf16 v[132:135], v[108:111], v[186:189], v[132:135]
	v_mfma_f32_16x16x32_bf16 v[128:131], v[156:159], v[186:189], v[128:131]
	v_mfma_f32_16x16x32_bf16 v[124:127], v[108:111], v[194:197], v[124:127]
	v_mfma_f32_16x16x32_bf16 v[120:123], v[156:159], v[194:197], v[120:123]
	v_mfma_f32_16x16x32_bf16 v[116:119], v[108:111], v[202:205], v[116:119]
	v_mfma_f32_16x16x32_bf16 v[112:115], v[156:159], v[202:205], v[112:115]
	v_mfma_f32_16x16x32_bf16 v[100:103], v[108:111], v[210:213], v[100:103]
	v_mfma_f32_16x16x32_bf16 v[96:99], v[156:159], v[210:213], v[96:99]
	s_setprio 0
	s_setprio 1
	v_mfma_f32_16x16x32_bf16 v[60:63], v[160:163], v[182:185], v[60:63]
	v_mfma_f32_16x16x32_bf16 v[56:59], v[174:177], v[182:185], v[56:59]
	v_mfma_f32_16x16x32_bf16 v[52:55], v[160:163], v[190:193], v[52:55]
	v_mfma_f32_16x16x32_bf16 v[48:51], v[174:177], v[190:193], v[48:51]
	v_mfma_f32_16x16x32_bf16 v[44:47], v[160:163], v[198:201], v[44:47]
	v_mfma_f32_16x16x32_bf16 v[40:43], v[174:177], v[198:201], v[40:43]
	v_mfma_f32_16x16x32_bf16 v[36:39], v[160:163], v[206:209], v[36:39]
	v_mfma_f32_16x16x32_bf16 v[32:35], v[174:177], v[206:209], v[32:35]
	v_mfma_f32_16x16x32_bf16 v[60:63], v[170:173], v[186:189], v[60:63]
	v_mfma_f32_16x16x32_bf16 v[56:59], v[178:181], v[186:189], v[56:59]
	v_mfma_f32_16x16x32_bf16 v[52:55], v[170:173], v[194:197], v[52:55]
	v_mfma_f32_16x16x32_bf16 v[48:51], v[178:181], v[194:197], v[48:51]
	v_mfma_f32_16x16x32_bf16 v[44:47], v[170:173], v[202:205], v[44:47]
	v_mfma_f32_16x16x32_bf16 v[40:43], v[178:181], v[202:205], v[40:43]
	v_mfma_f32_16x16x32_bf16 v[36:39], v[170:173], v[210:213], v[36:39]
	v_mfma_f32_16x16x32_bf16 v[32:35], v[178:181], v[210:213], v[32:35]
	s_setprio 0
	s_barrier
	s_add_i32 s58, s35, s26
	v_lshl_add_u64 v[214:215], s[10:11], 0, v[138:139]
	s_mov_b32 m0, s58
	ds_read_b128 v[182:185], v169 offset:16384
	ds_read_b128 v[186:189], v169 offset:17408
	ds_read_b128 v[190:193], v169 offset:18432
	ds_read_b128 v[194:197], v169 offset:19456
	ds_read_b128 v[198:201], v169 offset:20480
	ds_read_b128 v[202:205], v169 offset:21504
	ds_read_b128 v[206:209], v169 offset:22528
	ds_read_b128 v[210:213], v169 offset:23552
	global_load_lds_dwordx4 v[214:215], off
	s_add_i32 m0, s58, 0x2000
	s_add_u32 s58, s10, 0x80000
	v_lshl_add_u64 v[216:217], s[10:11], 0, v[142:143]
	s_addc_u32 s59, s11, 0
	s_add_i32 s60, s36, s26
	global_load_lds_dwordx4 v[216:217], off
	v_lshl_add_u64 v[222:223], s[58:59], 0, v[138:139]
	s_mov_b32 m0, s60
	v_lshl_add_u64 v[224:225], s[20:21], 0, v[140:141]
	global_load_lds_dwordx4 v[222:223], off
	v_lshl_add_u64 v[222:223], s[58:59], 0, v[142:143]
	s_add_i32 m0, s60, 0x2000
	s_nop 0
	global_load_lds_dwordx4 v[222:223], off
	v_lshl_add_u64 v[222:223], s[20:21], 0, v[136:137]
	s_mov_b32 m0, s17
	s_nop 0
	global_load_lds_dwordx4 v[222:223], off
	s_mov_b32 m0, s19
	s_nop 0
	global_load_lds_dwordx4 v[224:225], off
	s_waitcnt vmcnt(8)
	s_waitcnt lgkmcnt(0)
	s_barrier
; #define PG8_STAGE(bufoff, gbase, voff) do { _Pragma("unroll") for (int _i = 0; _i < 2; ++_i) \
;         __builtin_amdgcn_global_load_lds((const unsigned*)((const char*)(gbase) + (voff)[_i]), (PG8_LAS unsigned*)(lds + (bufoff) + ldsw + _i * 8192), 16, 0, 0); } while (0)
; #define PG8_LDA(dst, b, h) do { _Pragma("unroll") for (int m = 0; m < 4; ++m) _Pragma("unroll") for (int k = 0; k < 2; ++k) dst[m][k] = *(const PG8_LAS bf16x8*)(lds + PG8_SA(b, h) + aoff + m * 2048 + k * 1024); } while (0)
; #define PG8_LDB(dst, b, h) do { _Pragma("unroll") for (int n = 0; n < 2; ++n) _Pragma("unroll") for (int k = 0; k < 2; ++k) dst[n][k] = *(const PG8_LAS bf16x8*)(lds + PG8_SB(b, h) + boff + n * 2048 + k * 1024); } while (0)
; #define PG8_MMA(ai, bj, At, Bt) do { __builtin_amdgcn_s_setprio(1); _Pragma("unroll") for (int m = 0; m < 4; ++m) _Pragma("unroll") for (int n = 0; n < 2; ++n) _Pragma("unroll") for (int k = 0; k < 2; ++k) \
;         acc[ai][bj][m][n] = __builtin_amdgcn_mfma_f32_16x16x32_bf16(Bt[n][k], At[m][k], acc[ai][bj][m][n], 0, 0, 0); __builtin_amdgcn_s_setprio(0); } while (0)
; #define PG8_WAIT_V(n) asm volatile("s_waitcnt vmcnt(" #n ")" ::: "memory")
; #define PG8_WAIT_L(n) asm volatile("s_waitcnt lgkmcnt(" #n ")" ::: "memory")
; #define PG8_BAR __builtin_amdgcn_s_barrier()
; #define PG8_SCHED __builtin_amdgcn_sched_barrier(0)
; template <class Epi, class Sched, bool ALIGN_EPI = false, bool SP2 = false>
; __device__ __forceinline__ void gemm_phase(PG8_LAS unsigned char* lds, const Gemm g, const Sched& S, const Epi& E) {
;     ...
;             PG8_WAIT_V(8); PG8_WAIT_L(0); PG8_BAR; PG8_MMA(1, 0, At, B0); PG8_MMA(1, 1, At, B1); PG8_BAR; PG8_SCHED;
;             PG8_LDB(B0, 1, 0); PG8_LDB(B1, 1, 1); PG8_SCHED; PG8_LDA(At, 1, 0); PG8_STAGE(PG8_SA(0, 1), a2 + hstep, voffA);
;             PG8_WAIT_V(8); PG8_WAIT_L(0); PG8_BAR; PG8_MMA(0, 0, At, B0); PG8_MMA(0, 1, At, B1); PG8_BAR; PG8_SCHED;
	s_setprio 1
	s_waitcnt lgkmcnt(0)
	v_mfma_f32_16x16x32_bf16 v[92:95], v[104:107], v[182:185], v[92:95]
	v_mfma_f32_16x16x32_bf16 v[88:91], v[152:155], v[182:185], v[88:91]
	v_mfma_f32_16x16x32_bf16 v[84:87], v[104:107], v[190:193], v[84:87]
	v_mfma_f32_16x16x32_bf16 v[80:83], v[152:155], v[190:193], v[80:83]
	v_mfma_f32_16x16x32_bf16 v[76:79], v[104:107], v[198:201], v[76:79]
	v_mfma_f32_16x16x32_bf16 v[72:75], v[152:155], v[198:201], v[72:75]
	v_mfma_f32_16x16x32_bf16 v[68:71], v[104:107], v[206:209], v[68:71]
	v_mfma_f32_16x16x32_bf16 v[64:67], v[152:155], v[206:209], v[64:67]
	v_mfma_f32_16x16x32_bf16 v[92:95], v[108:111], v[186:189], v[92:95]
	v_mfma_f32_16x16x32_bf16 v[88:91], v[156:159], v[186:189], v[88:91]
	v_mfma_f32_16x16x32_bf16 v[84:87], v[108:111], v[194:197], v[84:87]
	v_mfma_f32_16x16x32_bf16 v[80:83], v[156:159], v[194:197], v[80:83]
	v_mfma_f32_16x16x32_bf16 v[76:79], v[108:111], v[202:205], v[76:79]
	v_mfma_f32_16x16x32_bf16 v[72:75], v[156:159], v[202:205], v[72:75]
	v_mfma_f32_16x16x32_bf16 v[68:71], v[108:111], v[210:213], v[68:71]
	v_mfma_f32_16x16x32_bf16 v[64:67], v[156:159], v[210:213], v[64:67]
	s_setprio 0
	s_setprio 1
	v_mfma_f32_16x16x32_bf16 v[28:31], v[160:163], v[182:185], v[28:31]
	v_mfma_f32_16x16x32_bf16 v[24:27], v[174:177], v[182:185], v[24:27]
	v_mfma_f32_16x16x32_bf16 v[20:23], v[160:163], v[190:193], v[20:23]
	v_mfma_f32_16x16x32_bf16 v[16:19], v[174:177], v[190:193], v[16:19]
	v_mfma_f32_16x16x32_bf16 v[12:15], v[160:163], v[198:201], v[12:15]
	v_mfma_f32_16x16x32_bf16 v[8:11], v[174:177], v[198:201], v[8:11]
	v_mfma_f32_16x16x32_bf16 v[4:7], v[160:163], v[206:209], v[4:7]
	v_mfma_f32_16x16x32_bf16 v[0:3], v[174:177], v[206:209], v[0:3]
	v_mfma_f32_16x16x32_bf16 v[28:31], v[170:173], v[186:189], v[28:31]
	v_mfma_f32_16x16x32_bf16 v[24:27], v[178:181], v[186:189], v[24:27]
	v_mfma_f32_16x16x32_bf16 v[20:23], v[170:173], v[194:197], v[20:23]
	v_mfma_f32_16x16x32_bf16 v[16:19], v[178:181], v[194:197], v[16:19]
	v_mfma_f32_16x16x32_bf16 v[12:15], v[170:173], v[202:205], v[12:15]
	v_mfma_f32_16x16x32_bf16 v[8:11], v[178:181], v[202:205], v[8:11]
	v_mfma_f32_16x16x32_bf16 v[4:7], v[170:173], v[210:213], v[4:7]
	v_mfma_f32_16x16x32_bf16 v[0:3], v[178:181], v[210:213], v[0:3]
	s_setprio 0
	s_barrier
	s_add_i32 s58, 0, 0x18000
	s_add_i32 s59, 0, 0x1c000
	v_add_u32_e32 v156, s58, v165
	v_add_u32_e32 v178, s59, v165
	ds_read_b128 v[104:107], v156
	ds_read_b128 v[108:111], v156 offset:1024
	ds_read_b128 v[152:155], v156 offset:2048
	ds_read_b128 v[156:159], v156 offset:3072
	ds_read_b128 v[160:163], v178
	ds_read_b128 v[170:173], v178 offset:1024
	ds_read_b128 v[174:177], v178 offset:2048
	ds_read_b128 v[178:181], v178 offset:3072
	s_add_u32 s20, s20, 0x80000
	s_addc_u32 s21, s21, 0
	s_mov_b32 m0, s27
	v_lshl_add_u64 v[226:227], s[20:21], 0, v[136:137]
	ds_read_b128 v[182:185], v169 offset:32768
	ds_read_b128 v[186:189], v169 offset:33792
	ds_read_b128 v[190:193], v169 offset:34816
	ds_read_b128 v[194:197], v169 offset:35840
	ds_read_b128 v[198:201], v169 offset:36864
	ds_read_b128 v[202:205], v169 offset:37888
	ds_read_b128 v[206:209], v169 offset:38912
	ds_read_b128 v[210:213], v169 offset:39936
	global_load_lds_dwordx4 v[226:227], off
	v_lshl_add_u64 v[226:227], s[20:21], 0, v[140:141]
	s_mov_b32 m0, s28
	s_nop 0
	global_load_lds_dwordx4 v[226:227], off
	s_waitcnt vmcnt(8)
	s_waitcnt lgkmcnt(0)
	s_barrier
	s_setprio 1
	s_waitcnt lgkmcnt(0)
	v_mfma_f32_16x16x32_bf16 v[132:135], v[104:107], v[182:185], v[132:135]
	v_mfma_f32_16x16x32_bf16 v[128:131], v[152:155], v[182:185], v[128:131]
	v_mfma_f32_16x16x32_bf16 v[124:127], v[104:107], v[190:193], v[124:127]
	v_mfma_f32_16x16x32_bf16 v[120:123], v[152:155], v[190:193], v[120:123]
	v_mfma_f32_16x16x32_bf16 v[116:119], v[104:107], v[198:201], v[116:119]
	v_mfma_f32_16x16x32_bf16 v[112:115], v[152:155], v[198:201], v[112:115]
	v_mfma_f32_16x16x32_bf16 v[100:103], v[104:107], v[206:209], v[100:103]
	v_mfma_f32_16x16x32_bf16 v[96:99], v[152:155], v[206:209], v[96:99]
	v_mfma_f32_16x16x32_bf16 v[132:135], v[108:111], v[186:189], v[132:135]
	v_mfma_f32_16x16x32_bf16 v[128:131], v[156:159], v[186:189], v[128:131]
	v_mfma_f32_16x16x32_bf16 v[124:127], v[108:111], v[194:197], v[124:127]
	v_mfma_f32_16x16x32_bf16 v[120:123], v[156:159], v[194:197], v[120:123]
	v_mfma_f32_16x16x32_bf16 v[116:119], v[108:111], v[202:205], v[116:119]
	v_mfma_f32_16x16x32_bf16 v[112:115], v[156:159], v[202:205], v[112:115]
	v_mfma_f32_16x16x32_bf16 v[100:103], v[108:111], v[210:213], v[100:103]
	v_mfma_f32_16x16x32_bf16 v[96:99], v[156:159], v[210:213], v[96:99]
	s_setprio 0
	s_setprio 1
	v_mfma_f32_16x16x32_bf16 v[60:63], v[160:163], v[182:185], v[60:63]
	v_mfma_f32_16x16x32_bf16 v[56:59], v[174:177], v[182:185], v[56:59]
	v_mfma_f32_16x16x32_bf16 v[52:55], v[160:163], v[190:193], v[52:55]
	v_mfma_f32_16x16x32_bf16 v[48:51], v[174:177], v[190:193], v[48:51]
	v_mfma_f32_16x16x32_bf16 v[44:47], v[160:163], v[198:201], v[44:47]
	v_mfma_f32_16x16x32_bf16 v[40:43], v[174:177], v[198:201], v[40:43]
	v_mfma_f32_16x16x32_bf16 v[36:39], v[160:163], v[206:209], v[36:39]
	v_mfma_f32_16x16x32_bf16 v[32:35], v[174:177], v[206:209], v[32:35]
	v_mfma_f32_16x16x32_bf16 v[60:63], v[170:173], v[186:189], v[60:63]
	v_mfma_f32_16x16x32_bf16 v[56:59], v[178:181], v[186:189], v[56:59]
	v_mfma_f32_16x16x32_bf16 v[52:55], v[170:173], v[194:197], v[52:55]
	v_mfma_f32_16x16x32_bf16 v[48:51], v[178:181], v[194:197], v[48:51]
	v_mfma_f32_16x16x32_bf16 v[44:47], v[170:173], v[202:205], v[44:47]
	v_mfma_f32_16x16x32_bf16 v[40:43], v[178:181], v[202:205], v[40:43]
	v_mfma_f32_16x16x32_bf16 v[36:39], v[170:173], v[210:213], v[36:39]
	v_mfma_f32_16x16x32_bf16 v[32:35], v[178:181], v[210:213], v[32:35]
	s_setprio 0
	s_barrier
; #define PG8_STAGE(bufoff, gbase, voff) do { _Pragma("unroll") for (int _i = 0; _i < 2; ++_i) \
;         __builtin_amdgcn_global_load_lds((const unsigned*)((const char*)(gbase) + (voff)[_i]), (PG8_LAS unsigned*)(lds + (bufoff) + ldsw + _i * 8192), 16, 0, 0); } while (0)
; #define PG8_LDA(dst, b, h) do { _Pragma("unroll") for (int m = 0; m < 4; ++m) _Pragma("unroll") for (int k = 0; k < 2; ++k) dst[m][k] = *(const PG8_LAS bf16x8*)(lds + PG8_SA(b, h) + aoff + m * 2048 + k * 1024); } while (0)
; #define PG8_MMA(ai, bj, At, Bt) do { __builtin_amdgcn_s_setprio(1); _Pragma("unroll") for (int m = 0; m < 4; ++m) _Pragma("unroll") for (int n = 0; n < 2; ++n) _Pragma("unroll") for (int k = 0; k < 2; ++k) \
;         acc[ai][bj][m][n] = __builtin_amdgcn_mfma_f32_16x16x32_bf16(Bt[n][k], At[m][k], acc[ai][bj][m][n], 0, 0, 0); __builtin_amdgcn_s_setprio(0); } while (0)
; #define PG8_WAIT_V(n) asm volatile("s_waitcnt vmcnt(" #n ")" ::: "memory")
; #define PG8_WAIT_L(n) asm volatile("s_waitcnt lgkmcnt(" #n ")" ::: "memory")
; #define PG8_BAR __builtin_amdgcn_s_barrier()
; #define PG8_SCHED __builtin_amdgcn_sched_barrier(0)
; template <class Epi, class Sched, bool ALIGN_EPI = false, bool SP2 = false>
; __device__ __forceinline__ void gemm_phase(PG8_LAS unsigned char* lds, const Gemm g, const Sched& S, const Epi& E) {
;     ...
;         for (int t = 0; t < nt; t += 2) {
;             const bool last = (t == nt - 2);
;             const char* a1 = cA + (size_t)(t + 1) * kstep;
;             const char* a2 = last ? nA : cA + (size_t)(t + 2) * kstep; const char* b2 = last ? nB : cB + (size_t)(t + 2) * kstep;
;     ...
;             PG8_LDA(At, 1, 1); PG8_STAGE(PG8_SB(1, 0), b3, voffB); PG8_STAGE(PG8_SB(1, 1), b3 + hstep, voffB); PG8_STAGE(PG8_SA(1, 0), a3, voffA);
;             PG8_WAIT_V(8); PG8_WAIT_L(0); PG8_BAR; PG8_MMA(1, 0, At, B0); PG8_MMA(1, 1, At, B1); PG8_BAR; PG8_SCHED;
	s_add_i32 s20, s58, s26
	v_lshl_add_u64 v[214:215], v[214:215], 0, s[44:45]
	s_mov_b32 m0, s20
	ds_read_b128 v[182:185], v169 offset:49152
	ds_read_b128 v[186:189], v169 offset:50176
	ds_read_b128 v[190:193], v169 offset:51200
	ds_read_b128 v[194:197], v169 offset:52224
	ds_read_b128 v[198:201], v169 offset:53248
	ds_read_b128 v[202:205], v169 offset:54272
	ds_read_b128 v[206:209], v169 offset:55296
	ds_read_b128 v[210:213], v169 offset:56320
	global_load_lds_dwordx4 v[214:215], off
	s_add_i32 m0, s20, 0x2000
	s_add_u32 s10, s10, 0x80080
	v_lshl_add_u64 v[214:215], v[216:217], 0, s[44:45]
	s_addc_u32 s11, s11, 0
	s_add_i32 s20, s59, s26
	global_load_lds_dwordx4 v[214:215], off
	v_lshl_add_u64 v[214:215], s[10:11], 0, v[138:139]
	s_mov_b32 m0, s20
	s_nop 0
	global_load_lds_dwordx4 v[214:215], off
	v_lshl_add_u64 v[214:215], s[10:11], 0, v[142:143]
	s_add_i32 m0, s20, 0x2000
	s_nop 0
	global_load_lds_dwordx4 v[214:215], off
	v_lshl_add_u64 v[214:215], v[222:223], 0, s[44:45]
	s_mov_b32 m0, s30
	s_nop 0
	global_load_lds_dwordx4 v[214:215], off
	v_lshl_add_u64 v[214:215], v[224:225], 0, s[44:45]
	s_mov_b32 m0, s31
	s_nop 0
	global_load_lds_dwordx4 v[214:215], off
	s_waitcnt vmcnt(8)
	s_waitcnt lgkmcnt(0)
	s_barrier
	s_setprio 1
	s_waitcnt lgkmcnt(0)
	v_mfma_f32_16x16x32_bf16 v[92:95], v[104:107], v[182:185], v[92:95]
	v_mfma_f32_16x16x32_bf16 v[88:91], v[152:155], v[182:185], v[88:91]
	v_mfma_f32_16x16x32_bf16 v[84:87], v[104:107], v[190:193], v[84:87]
	v_mfma_f32_16x16x32_bf16 v[80:83], v[152:155], v[190:193], v[80:83]
	v_mfma_f32_16x16x32_bf16 v[76:79], v[104:107], v[198:201], v[76:79]
	v_mfma_f32_16x16x32_bf16 v[72:75], v[152:155], v[198:201], v[72:75]
	v_mfma_f32_16x16x32_bf16 v[68:71], v[104:107], v[206:209], v[68:71]
	v_mfma_f32_16x16x32_bf16 v[64:67], v[152:155], v[206:209], v[64:67]
	v_mfma_f32_16x16x32_bf16 v[92:95], v[108:111], v[186:189], v[92:95]
	v_mfma_f32_16x16x32_bf16 v[88:91], v[156:159], v[186:189], v[88:91]
	v_mfma_f32_16x16x32_bf16 v[84:87], v[108:111], v[194:197], v[84:87]
	v_mfma_f32_16x16x32_bf16 v[80:83], v[156:159], v[194:197], v[80:83]
	v_mfma_f32_16x16x32_bf16 v[76:79], v[108:111], v[202:205], v[76:79]
	v_mfma_f32_16x16x32_bf16 v[72:75], v[156:159], v[202:205], v[72:75]
	v_mfma_f32_16x16x32_bf16 v[68:71], v[108:111], v[210:213], v[68:71]
	v_mfma_f32_16x16x32_bf16 v[64:67], v[156:159], v[210:213], v[64:67]
	s_setprio 0
	s_setprio 1
	v_mfma_f32_16x16x32_bf16 v[28:31], v[160:163], v[182:185], v[28:31]
	v_mfma_f32_16x16x32_bf16 v[24:27], v[174:177], v[182:185], v[24:27]
	v_mfma_f32_16x16x32_bf16 v[20:23], v[160:163], v[190:193], v[20:23]
	v_mfma_f32_16x16x32_bf16 v[16:19], v[174:177], v[190:193], v[16:19]
	v_mfma_f32_16x16x32_bf16 v[12:15], v[160:163], v[198:201], v[12:15]
	v_mfma_f32_16x16x32_bf16 v[8:11], v[174:177], v[198:201], v[8:11]
	v_mfma_f32_16x16x32_bf16 v[4:7], v[160:163], v[206:209], v[4:7]
	v_mfma_f32_16x16x32_bf16 v[0:3], v[174:177], v[206:209], v[0:3]
	v_mfma_f32_16x16x32_bf16 v[28:31], v[170:173], v[186:189], v[28:31]
	v_mfma_f32_16x16x32_bf16 v[24:27], v[178:181], v[186:189], v[24:27]
	v_mfma_f32_16x16x32_bf16 v[20:23], v[170:173], v[194:197], v[20:23]
	v_mfma_f32_16x16x32_bf16 v[16:19], v[178:181], v[194:197], v[16:19]
	v_mfma_f32_16x16x32_bf16 v[12:15], v[170:173], v[202:205], v[12:15]
	v_mfma_f32_16x16x32_bf16 v[8:11], v[178:181], v[202:205], v[8:11]
	v_mfma_f32_16x16x32_bf16 v[4:7], v[170:173], v[210:213], v[4:7]
	v_mfma_f32_16x16x32_bf16 v[0:3], v[178:181], v[210:213], v[0:3]
	s_add_i32 s57, s57, 2
	s_add_u32 s8, s8, 0x100
	s_addc_u32 s9, s9, 0
	s_add_u32 s51, s51, 0x100
	s_addc_u32 s56, s56, 0
	s_cmp_gt_u32 s57, 29
	s_setprio 0
	s_barrier
	s_cbranch_scc0 .LBB0_1027
	s_and_b64 vcc, exec, s[46:47]
	s_cbranch_vccz .LBB0_1030
	s_barrier

; #define PG8_STAGE(bufoff, gbase, voff) do { _Pragma("unroll") for (int _i = 0; _i < 2; ++_i) \
;         __builtin_amdgcn_global_load_lds((const unsigned*)((const char*)(gbase) + (voff)[_i]), (PG8_LAS unsigned*)(lds + (bufoff) + ldsw + _i * 8192), 16, 0, 0); } while (0)
; #define PG8_LDA(dst, b, h) do { _Pragma("unroll") for (int m = 0; m < 4; ++m) _Pragma("unroll") for (int k = 0; k < 2; ++k) dst[m][k] = *(const PG8_LAS bf16x8*)(lds + PG8_SA(b, h) + aoff + m * 2048 + k * 1024); } while (0)
; #define PG8_LDB(dst, b, h) do { _Pragma("unroll") for (int n = 0; n < 2; ++n) _Pragma("unroll") for (int k = 0; k < 2; ++k) dst[n][k] = *(const PG8_LAS bf16x8*)(lds + PG8_SB(b, h) + boff + n * 2048 + k * 1024); } while (0)
; #define PG8_MMA(ai, bj, At, Bt) do { __builtin_amdgcn_s_setprio(1); _Pragma("unroll") for (int m = 0; m < 4; ++m) _Pragma("unroll") for (int n = 0; n < 2; ++n) _Pragma("unroll") for (int k = 0; k < 2; ++k) \
;         acc[ai][bj][m][n] = __builtin_amdgcn_mfma_f32_16x16x32_bf16(Bt[n][k], At[m][k], acc[ai][bj][m][n], 0, 0, 0); __builtin_amdgcn_s_setprio(0); } while (0)
; #define PG8_WAIT_V(n) asm volatile("s_waitcnt vmcnt(" #n ")" ::: "memory")
; #define PG8_WAIT_L(n) asm volatile("s_waitcnt lgkmcnt(" #n ")" ::: "memory")
; template <class Epi, class Sched, bool ALIGN_EPI = false, bool SP2 = false>
; __device__ __forceinline__ void gemm_phase(PG8_LAS unsigned char* lds, const Gemm g, const Sched& S, const Epi& E) {
;     ...
;             const bool last = (t == nt - 2);
;             const char* a1 = cA + (size_t)(t + 1) * kstep;
;             const char* a2 = last ? nA : cA + (size_t)(t + 2) * kstep; const char* b2 = last ? nB : cB + (size_t)(t + 2) * kstep;
;             const char* a3 = a2 + kstep; const char* b3 = b2 + kstep;
;             if (last && has_next) S.a_ready(nxt);
;             if constexpr (SP2) {
;             PG8_LDB(B0, 0, 0); PG8_LDB(B1, 0, 1); PG8_SCHED; PG8_LDA(At, 0, 0); PG8_STAGE(PG8_SA(1, 1), a1 + hstep, voffA);
;             PG8_WAIT_V(8); PG8_WAIT_L(0); PG8_BAR; PG8_MMA(0, 0, At, B0); PG8_MMA(0, 1, At, B1); PG8_BAR; PG8_SCHED;
;             PG8_LDA(At, 0, 1); PG8_STAGE(PG8_SB(0, 0), b2, voffB); PG8_STAGE(PG8_SB(0, 1), b2 + hstep, voffB); PG8_STAGE(PG8_SA(0, 0), a2, voffA);
;             PG8_WAIT_V(8); PG8_WAIT_L(0); PG8_BAR; PG8_MMA(1, 0, At, B0); PG8_MMA(1, 1, At, B1); PG8_BAR; PG8_SCHED;
.LBB0_1248:
	ds_read_b128 v[152:155], v149
	ds_read_b128 v[156:159], v149 offset:1024
	ds_read_b128 v[160:163], v149 offset:2048
	ds_read_b128 v[164:167], v149 offset:3072
	ds_read_b128 v[168:171], v150
	ds_read_b128 v[172:175], v150 offset:1024
	ds_read_b128 v[176:179], v150 offset:2048
	ds_read_b128 v[180:183], v150 offset:3072
	s_add_u32 s10, s8, 0xfff80080
	s_addc_u32 s11, s9, -1
	s_cmp_eq_u32 s50, 28
	s_cselect_b32 s27, s19, s11
	s_cselect_b32 s26, s46, s10
	s_cselect_b32 s11, s17, s49
	s_cselect_b32 s10, s47, s48
	v_lshl_add_u64 v[144:145], s[8:9], 0, v[136:137]
	s_add_i32 m0, s25, 0xc000
	ds_read_b128 v[184:187], v151
	ds_read_b128 v[188:191], v151 offset:1024
	ds_read_b128 v[192:195], v151 offset:2048
	ds_read_b128 v[196:199], v151 offset:3072
	ds_read_b128 v[200:203], v151 offset:4096
	ds_read_b128 v[204:207], v151 offset:5120
	ds_read_b128 v[208:211], v151 offset:6144
	ds_read_b128 v[212:215], v151 offset:7168
	global_load_lds_dwordx4 v[144:145], off
	v_lshl_add_u64 v[144:145], s[8:9], 0, v[138:139]
	s_add_i32 m0, s25, 0xe000
	s_nop 0
	global_load_lds_dwordx4 v[144:145], off
	s_waitcnt vmcnt(8)
	s_waitcnt lgkmcnt(0)
	s_barrier
	s_setprio 1
	s_waitcnt lgkmcnt(0)
	v_mfma_f32_16x16x32_bf16 v[124:127], v[152:155], v[184:187], v[124:127]
	v_mfma_f32_16x16x32_bf16 v[120:123], v[160:163], v[184:187], v[120:123]
	v_mfma_f32_16x16x32_bf16 v[108:111], v[152:155], v[192:195], v[108:111]
	v_mfma_f32_16x16x32_bf16 v[104:107], v[160:163], v[192:195], v[104:107]
	v_mfma_f32_16x16x32_bf16 v[92:95], v[152:155], v[200:203], v[92:95]
	v_mfma_f32_16x16x32_bf16 v[88:91], v[160:163], v[200:203], v[88:91]
	v_mfma_f32_16x16x32_bf16 v[76:79], v[152:155], v[208:211], v[76:79]
	v_mfma_f32_16x16x32_bf16 v[72:75], v[160:163], v[208:211], v[72:75]
	v_mfma_f32_16x16x32_bf16 v[124:127], v[156:159], v[188:191], v[124:127]
	v_mfma_f32_16x16x32_bf16 v[120:123], v[164:167], v[188:191], v[120:123]
	v_mfma_f32_16x16x32_bf16 v[108:111], v[156:159], v[196:199], v[108:111]
	v_mfma_f32_16x16x32_bf16 v[104:107], v[164:167], v[196:199], v[104:107]
	v_mfma_f32_16x16x32_bf16 v[92:95], v[156:159], v[204:207], v[92:95]
	v_mfma_f32_16x16x32_bf16 v[88:91], v[164:167], v[204:207], v[88:91]
	v_mfma_f32_16x16x32_bf16 v[76:79], v[156:159], v[212:215], v[76:79]
	v_mfma_f32_16x16x32_bf16 v[72:75], v[164:167], v[212:215], v[72:75]
	s_setprio 0
	s_setprio 1
	v_mfma_f32_16x16x32_bf16 v[116:119], v[168:171], v[184:187], v[116:119]
	v_mfma_f32_16x16x32_bf16 v[112:115], v[176:179], v[184:187], v[112:115]
	v_mfma_f32_16x16x32_bf16 v[100:103], v[168:171], v[192:195], v[100:103]
	v_mfma_f32_16x16x32_bf16 v[96:99], v[176:179], v[192:195], v[96:99]
	v_mfma_f32_16x16x32_bf16 v[84:87], v[168:171], v[200:203], v[84:87]
	v_mfma_f32_16x16x32_bf16 v[80:83], v[176:179], v[200:203], v[80:83]
	v_mfma_f32_16x16x32_bf16 v[68:71], v[168:171], v[208:211], v[68:71]
	v_mfma_f32_16x16x32_bf16 v[64:67], v[176:179], v[208:211], v[64:67]
	v_mfma_f32_16x16x32_bf16 v[116:119], v[172:175], v[188:191], v[116:119]
	v_mfma_f32_16x16x32_bf16 v[112:115], v[180:183], v[188:191], v[112:115]
	v_mfma_f32_16x16x32_bf16 v[100:103], v[172:175], v[196:199], v[100:103]
	v_mfma_f32_16x16x32_bf16 v[96:99], v[180:183], v[196:199], v[96:99]
	v_mfma_f32_16x16x32_bf16 v[84:87], v[172:175], v[204:207], v[84:87]
	v_mfma_f32_16x16x32_bf16 v[80:83], v[180:183], v[204:207], v[80:83]
	v_mfma_f32_16x16x32_bf16 v[68:71], v[172:175], v[212:215], v[68:71]
	v_mfma_f32_16x16x32_bf16 v[64:67], v[180:183], v[212:215], v[64:67]
	s_setprio 0
	s_barrier
	s_add_i32 s51, s43, s30
	v_lshl_add_u64 v[144:145], s[10:11], 0, v[132:133]
	s_mov_b32 m0, s51
	ds_read_b128 v[184:187], v151 offset:16384
	ds_read_b128 v[188:191], v151 offset:17408
	ds_read_b128 v[192:195], v151 offset:18432
	ds_read_b128 v[196:199], v151 offset:19456
	ds_read_b128 v[200:203], v151 offset:20480
	ds_read_b128 v[204:207], v151 offset:21504
	ds_read_b128 v[208:211], v151 offset:22528
	ds_read_b128 v[212:215], v151 offset:23552
	global_load_lds_dwordx4 v[144:145], off
	s_add_i32 m0, s51, 0x2000
	s_add_u32 s52, s10, 0x80000
	v_lshl_add_u64 v[216:217], s[10:11], 0, v[128:129]
	s_addc_u32 s53, s11, 0
	s_add_i32 s51, s44, s30
	global_load_lds_dwordx4 v[216:217], off
	v_lshl_add_u64 v[222:223], s[52:53], 0, v[132:133]
	s_mov_b32 m0, s51
	v_lshl_add_u64 v[224:225], s[26:27], 0, v[130:131]
	global_load_lds_dwordx4 v[222:223], off
	v_lshl_add_u64 v[222:223], s[52:53], 0, v[128:129]
	s_add_i32 m0, s51, 0x2000
	s_nop 0
	global_load_lds_dwordx4 v[222:223], off
	v_lshl_add_u64 v[222:223], s[26:27], 0, v[134:135]
	s_mov_b32 m0, s25
	s_nop 0
	global_load_lds_dwordx4 v[222:223], off
	s_mov_b32 m0, s34
	s_nop 0
	global_load_lds_dwordx4 v[224:225], off
	s_waitcnt vmcnt(8)
	s_waitcnt lgkmcnt(0)
	s_barrier
; #define PG8_STAGE(bufoff, gbase, voff) do { _Pragma("unroll") for (int _i = 0; _i < 2; ++_i) \
;         __builtin_amdgcn_global_load_lds((const unsigned*)((const char*)(gbase) + (voff)[_i]), (PG8_LAS unsigned*)(lds + (bufoff) + ldsw + _i * 8192), 16, 0, 0); } while (0)
; #define PG8_LDA(dst, b, h) do { _Pragma("unroll") for (int m = 0; m < 4; ++m) _Pragma("unroll") for (int k = 0; k < 2; ++k) dst[m][k] = *(const PG8_LAS bf16x8*)(lds + PG8_SA(b, h) + aoff + m * 2048 + k * 1024); } while (0)
; #define PG8_LDB(dst, b, h) do { _Pragma("unroll") for (int n = 0; n < 2; ++n) _Pragma("unroll") for (int k = 0; k < 2; ++k) dst[n][k] = *(const PG8_LAS bf16x8*)(lds + PG8_SB(b, h) + boff + n * 2048 + k * 1024); } while (0)
; #define PG8_MMA(ai, bj, At, Bt) do { __builtin_amdgcn_s_setprio(1); _Pragma("unroll") for (int m = 0; m < 4; ++m) _Pragma("unroll") for (int n = 0; n < 2; ++n) _Pragma("unroll") for (int k = 0; k < 2; ++k) \
;         acc[ai][bj][m][n] = __builtin_amdgcn_mfma_f32_16x16x32_bf16(Bt[n][k], At[m][k], acc[ai][bj][m][n], 0, 0, 0); __builtin_amdgcn_s_setprio(0); } while (0)
; #define PG8_WAIT_V(n) asm volatile("s_waitcnt vmcnt(" #n ")" ::: "memory")
; #define PG8_WAIT_L(n) asm volatile("s_waitcnt lgkmcnt(" #n ")" ::: "memory")
; #define PG8_BAR __builtin_amdgcn_s_barrier()
; #define PG8_SCHED __builtin_amdgcn_sched_barrier(0)
; template <class Epi, class Sched, bool ALIGN_EPI = false, bool SP2 = false>
; __device__ __forceinline__ void gemm_phase(PG8_LAS unsigned char* lds, const Gemm g, const Sched& S, const Epi& E) {
;     ...
;             PG8_WAIT_V(8); PG8_WAIT_L(0); PG8_BAR; PG8_MMA(1, 0, At, B0); PG8_MMA(1, 1, At, B1); PG8_BAR; PG8_SCHED;
;             PG8_LDB(B0, 1, 0); PG8_LDB(B1, 1, 1); PG8_SCHED; PG8_LDA(At, 1, 0); PG8_STAGE(PG8_SA(0, 1), a2 + hstep, voffA);
;             PG8_WAIT_V(8); PG8_WAIT_L(0); PG8_BAR; PG8_MMA(0, 0, At, B0); PG8_MMA(0, 1, At, B1); PG8_BAR; PG8_SCHED;
	s_setprio 1
	s_waitcnt lgkmcnt(0)
	v_mfma_f32_16x16x32_bf16 v[60:63], v[152:155], v[184:187], v[60:63]
	v_mfma_f32_16x16x32_bf16 v[56:59], v[160:163], v[184:187], v[56:59]
	v_mfma_f32_16x16x32_bf16 v[44:47], v[152:155], v[192:195], v[44:47]
	v_mfma_f32_16x16x32_bf16 v[40:43], v[160:163], v[192:195], v[40:43]
	v_mfma_f32_16x16x32_bf16 v[28:31], v[152:155], v[200:203], v[28:31]
	v_mfma_f32_16x16x32_bf16 v[24:27], v[160:163], v[200:203], v[24:27]
	v_mfma_f32_16x16x32_bf16 v[12:15], v[152:155], v[208:211], v[12:15]
	v_mfma_f32_16x16x32_bf16 v[8:11], v[160:163], v[208:211], v[8:11]
	v_mfma_f32_16x16x32_bf16 v[60:63], v[156:159], v[188:191], v[60:63]
	v_mfma_f32_16x16x32_bf16 v[56:59], v[164:167], v[188:191], v[56:59]
	v_mfma_f32_16x16x32_bf16 v[44:47], v[156:159], v[196:199], v[44:47]
	v_mfma_f32_16x16x32_bf16 v[40:43], v[164:167], v[196:199], v[40:43]
	v_mfma_f32_16x16x32_bf16 v[28:31], v[156:159], v[204:207], v[28:31]
	v_mfma_f32_16x16x32_bf16 v[24:27], v[164:167], v[204:207], v[24:27]
	v_mfma_f32_16x16x32_bf16 v[12:15], v[156:159], v[212:215], v[12:15]
	v_mfma_f32_16x16x32_bf16 v[8:11], v[164:167], v[212:215], v[8:11]
	s_setprio 0
	s_setprio 1
	v_mfma_f32_16x16x32_bf16 v[52:55], v[168:171], v[184:187], v[52:55]
	v_mfma_f32_16x16x32_bf16 v[48:51], v[176:179], v[184:187], v[48:51]
	v_mfma_f32_16x16x32_bf16 v[36:39], v[168:171], v[192:195], v[36:39]
	v_mfma_f32_16x16x32_bf16 v[32:35], v[176:179], v[192:195], v[32:35]
	v_mfma_f32_16x16x32_bf16 v[20:23], v[168:171], v[200:203], v[20:23]
	v_mfma_f32_16x16x32_bf16 v[16:19], v[176:179], v[200:203], v[16:19]
	v_mfma_f32_16x16x32_bf16 v[4:7], v[168:171], v[208:211], v[4:7]
	v_mfma_f32_16x16x32_bf16 v[0:3], v[176:179], v[208:211], v[0:3]
	v_mfma_f32_16x16x32_bf16 v[52:55], v[172:175], v[188:191], v[52:55]
	v_mfma_f32_16x16x32_bf16 v[48:51], v[180:183], v[188:191], v[48:51]
	v_mfma_f32_16x16x32_bf16 v[36:39], v[172:175], v[196:199], v[36:39]
	v_mfma_f32_16x16x32_bf16 v[32:35], v[180:183], v[196:199], v[32:35]
	v_mfma_f32_16x16x32_bf16 v[20:23], v[172:175], v[204:207], v[20:23]
	v_mfma_f32_16x16x32_bf16 v[16:19], v[180:183], v[204:207], v[16:19]
	v_mfma_f32_16x16x32_bf16 v[4:7], v[172:175], v[212:215], v[4:7]
	v_mfma_f32_16x16x32_bf16 v[0:3], v[180:183], v[212:215], v[0:3]
	s_setprio 0
	s_barrier
	s_add_i32 s51, 0, 0x18000
	s_add_i32 s52, 0, 0x1c000
	v_add_u32_e32 v164, s51, v147
	v_add_u32_e32 v180, s52, v147
	ds_read_b128 v[152:155], v164
	ds_read_b128 v[156:159], v164 offset:1024
	ds_read_b128 v[160:163], v164 offset:2048
	ds_read_b128 v[164:167], v164 offset:3072
	ds_read_b128 v[168:171], v180
	ds_read_b128 v[172:175], v180 offset:1024
	ds_read_b128 v[176:179], v180 offset:2048
	ds_read_b128 v[180:183], v180 offset:3072
	s_add_u32 s26, s26, 0x80000
	s_addc_u32 s27, s27, 0
	s_mov_b32 m0, s35
	v_lshl_add_u64 v[226:227], s[26:27], 0, v[134:135]
	ds_read_b128 v[184:187], v151 offset:32768
	ds_read_b128 v[188:191], v151 offset:33792
	ds_read_b128 v[192:195], v151 offset:34816
	ds_read_b128 v[196:199], v151 offset:35840
	ds_read_b128 v[200:203], v151 offset:36864
	ds_read_b128 v[204:207], v151 offset:37888
	ds_read_b128 v[208:211], v151 offset:38912
	ds_read_b128 v[212:215], v151 offset:39936
	global_load_lds_dwordx4 v[226:227], off
	v_lshl_add_u64 v[226:227], s[26:27], 0, v[130:131]
	s_mov_b32 m0, s36
	s_nop 0
	global_load_lds_dwordx4 v[226:227], off
	s_waitcnt vmcnt(8)
	s_waitcnt lgkmcnt(0)
	s_barrier
	s_setprio 1
	s_waitcnt lgkmcnt(0)
	v_mfma_f32_16x16x32_bf16 v[124:127], v[152:155], v[184:187], v[124:127]
	v_mfma_f32_16x16x32_bf16 v[120:123], v[160:163], v[184:187], v[120:123]
	v_mfma_f32_16x16x32_bf16 v[108:111], v[152:155], v[192:195], v[108:111]
	v_mfma_f32_16x16x32_bf16 v[104:107], v[160:163], v[192:195], v[104:107]
	v_mfma_f32_16x16x32_bf16 v[92:95], v[152:155], v[200:203], v[92:95]
	v_mfma_f32_16x16x32_bf16 v[88:91], v[160:163], v[200:203], v[88:91]
	v_mfma_f32_16x16x32_bf16 v[76:79], v[152:155], v[208:211], v[76:79]
	v_mfma_f32_16x16x32_bf16 v[72:75], v[160:163], v[208:211], v[72:75]
	v_mfma_f32_16x16x32_bf16 v[124:127], v[156:159], v[188:191], v[124:127]
	v_mfma_f32_16x16x32_bf16 v[120:123], v[164:167], v[188:191], v[120:123]
	v_mfma_f32_16x16x32_bf16 v[108:111], v[156:159], v[196:199], v[108:111]
	v_mfma_f32_16x16x32_bf16 v[104:107], v[164:167], v[196:199], v[104:107]
	v_mfma_f32_16x16x32_bf16 v[92:95], v[156:159], v[204:207], v[92:95]
	v_mfma_f32_16x16x32_bf16 v[88:91], v[164:167], v[204:207], v[88:91]
	v_mfma_f32_16x16x32_bf16 v[76:79], v[156:159], v[212:215], v[76:79]
	v_mfma_f32_16x16x32_bf16 v[72:75], v[164:167], v[212:215], v[72:75]
	s_setprio 0
	s_setprio 1
	v_mfma_f32_16x16x32_bf16 v[116:119], v[168:171], v[184:187], v[116:119]
	v_mfma_f32_16x16x32_bf16 v[112:115], v[176:179], v[184:187], v[112:115]
	v_mfma_f32_16x16x32_bf16 v[100:103], v[168:171], v[192:195], v[100:103]
	v_mfma_f32_16x16x32_bf16 v[96:99], v[176:179], v[192:195], v[96:99]
	v_mfma_f32_16x16x32_bf16 v[84:87], v[168:171], v[200:203], v[84:87]
	v_mfma_f32_16x16x32_bf16 v[80:83], v[176:179], v[200:203], v[80:83]
	v_mfma_f32_16x16x32_bf16 v[68:71], v[168:171], v[208:211], v[68:71]
	v_mfma_f32_16x16x32_bf16 v[64:67], v[176:179], v[208:211], v[64:67]
	v_mfma_f32_16x16x32_bf16 v[116:119], v[172:175], v[188:191], v[116:119]
	v_mfma_f32_16x16x32_bf16 v[112:115], v[180:183], v[188:191], v[112:115]
	v_mfma_f32_16x16x32_bf16 v[100:103], v[172:175], v[196:199], v[100:103]
	v_mfma_f32_16x16x32_bf16 v[96:99], v[180:183], v[196:199], v[96:99]
	v_mfma_f32_16x16x32_bf16 v[84:87], v[172:175], v[204:207], v[84:87]
	v_mfma_f32_16x16x32_bf16 v[80:83], v[180:183], v[204:207], v[80:83]
	v_mfma_f32_16x16x32_bf16 v[68:71], v[172:175], v[212:215], v[68:71]
	v_mfma_f32_16x16x32_bf16 v[64:67], v[180:183], v[212:215], v[64:67]
	s_setprio 0
	s_barrier
; #define PG8_STAGE(bufoff, gbase, voff) do { _Pragma("unroll") for (int _i = 0; _i < 2; ++_i) \
;         __builtin_amdgcn_global_load_lds((const unsigned*)((const char*)(gbase) + (voff)[_i]), (PG8_LAS unsigned*)(lds + (bufoff) + ldsw + _i * 8192), 16, 0, 0); } while (0)
; #define PG8_LDA(dst, b, h) do { _Pragma("unroll") for (int m = 0; m < 4; ++m) _Pragma("unroll") for (int k = 0; k < 2; ++k) dst[m][k] = *(const PG8_LAS bf16x8*)(lds + PG8_SA(b, h) + aoff + m * 2048 + k * 1024); } while (0)
; #define PG8_MMA(ai, bj, At, Bt) do { __builtin_amdgcn_s_setprio(1); _Pragma("unroll") for (int m = 0; m < 4; ++m) _Pragma("unroll") for (int n = 0; n < 2; ++n) _Pragma("unroll") for (int k = 0; k < 2; ++k) \
;         acc[ai][bj][m][n] = __builtin_amdgcn_mfma_f32_16x16x32_bf16(Bt[n][k], At[m][k], acc[ai][bj][m][n], 0, 0, 0); __builtin_amdgcn_s_setprio(0); } while (0)
; #define PG8_WAIT_V(n) asm volatile("s_waitcnt vmcnt(" #n ")" ::: "memory")
; #define PG8_WAIT_L(n) asm volatile("s_waitcnt lgkmcnt(" #n ")" ::: "memory")
; #define PG8_BAR __builtin_amdgcn_s_barrier()
; #define PG8_SCHED __builtin_amdgcn_sched_barrier(0)
; template <class Epi, class Sched, bool ALIGN_EPI = false, bool SP2 = false>
; __device__ __forceinline__ void gemm_phase(PG8_LAS unsigned char* lds, const Gemm g, const Sched& S, const Epi& E) {
;     ...
;         for (int t = 0; t < nt; t += 2) {
;             const bool last = (t == nt - 2);
;             const char* a1 = cA + (size_t)(t + 1) * kstep;
;             const char* a2 = last ? nA : cA + (size_t)(t + 2) * kstep; const char* b2 = last ? nB : cB + (size_t)(t + 2) * kstep;
;     ...
;             PG8_LDA(At, 1, 1); PG8_STAGE(PG8_SB(1, 0), b3, voffB); PG8_STAGE(PG8_SB(1, 1), b3 + hstep, voffB); PG8_STAGE(PG8_SA(1, 0), a3, voffA);
;             PG8_WAIT_V(8); PG8_WAIT_L(0); PG8_BAR; PG8_MMA(1, 0, At, B0); PG8_MMA(1, 1, At, B1); PG8_BAR; PG8_SCHED;
	s_add_i32 s26, s51, s30
	v_lshl_add_u64 v[144:145], v[144:145], 0, s[12:13]
	s_mov_b32 m0, s26
	ds_read_b128 v[184:187], v151 offset:49152
	ds_read_b128 v[188:191], v151 offset:50176
	ds_read_b128 v[192:195], v151 offset:51200
	ds_read_b128 v[196:199], v151 offset:52224
	ds_read_b128 v[200:203], v151 offset:53248
	ds_read_b128 v[204:207], v151 offset:54272
	ds_read_b128 v[208:211], v151 offset:55296
	ds_read_b128 v[212:215], v151 offset:56320
	global_load_lds_dwordx4 v[144:145], off
	s_add_i32 m0, s26, 0x2000
	s_add_u32 s10, s10, 0x80080
	v_lshl_add_u64 v[144:145], v[216:217], 0, s[12:13]
	s_addc_u32 s11, s11, 0
	s_add_i32 s26, s52, s30
	global_load_lds_dwordx4 v[144:145], off
	v_lshl_add_u64 v[144:145], s[10:11], 0, v[132:133]
	s_mov_b32 m0, s26
	s_nop 0
	global_load_lds_dwordx4 v[144:145], off
	v_lshl_add_u64 v[144:145], s[10:11], 0, v[128:129]
	s_add_i32 m0, s26, 0x2000
	s_nop 0
	global_load_lds_dwordx4 v[144:145], off
	v_lshl_add_u64 v[144:145], v[222:223], 0, s[12:13]
	s_mov_b32 m0, s40
	s_nop 0
	global_load_lds_dwordx4 v[144:145], off
	v_lshl_add_u64 v[144:145], v[224:225], 0, s[12:13]
	s_mov_b32 m0, s41
	s_nop 0
	global_load_lds_dwordx4 v[144:145], off
	s_waitcnt vmcnt(8)
	s_waitcnt lgkmcnt(0)
	s_barrier
	s_setprio 1
	s_waitcnt lgkmcnt(0)
	v_mfma_f32_16x16x32_bf16 v[60:63], v[152:155], v[184:187], v[60:63]
	v_mfma_f32_16x16x32_bf16 v[56:59], v[160:163], v[184:187], v[56:59]
	v_mfma_f32_16x16x32_bf16 v[44:47], v[152:155], v[192:195], v[44:47]
	v_mfma_f32_16x16x32_bf16 v[40:43], v[160:163], v[192:195], v[40:43]
	v_mfma_f32_16x16x32_bf16 v[28:31], v[152:155], v[200:203], v[28:31]
	v_mfma_f32_16x16x32_bf16 v[24:27], v[160:163], v[200:203], v[24:27]
	v_mfma_f32_16x16x32_bf16 v[12:15], v[152:155], v[208:211], v[12:15]
	v_mfma_f32_16x16x32_bf16 v[8:11], v[160:163], v[208:211], v[8:11]
	v_mfma_f32_16x16x32_bf16 v[60:63], v[156:159], v[188:191], v[60:63]
	v_mfma_f32_16x16x32_bf16 v[56:59], v[164:167], v[188:191], v[56:59]
	v_mfma_f32_16x16x32_bf16 v[44:47], v[156:159], v[196:199], v[44:47]
	v_mfma_f32_16x16x32_bf16 v[40:43], v[164:167], v[196:199], v[40:43]
	v_mfma_f32_16x16x32_bf16 v[28:31], v[156:159], v[204:207], v[28:31]
	v_mfma_f32_16x16x32_bf16 v[24:27], v[164:167], v[204:207], v[24:27]
	v_mfma_f32_16x16x32_bf16 v[12:15], v[156:159], v[212:215], v[12:15]
	v_mfma_f32_16x16x32_bf16 v[8:11], v[164:167], v[212:215], v[8:11]
	s_setprio 0
	s_setprio 1
	v_mfma_f32_16x16x32_bf16 v[52:55], v[168:171], v[184:187], v[52:55]
	v_mfma_f32_16x16x32_bf16 v[48:51], v[176:179], v[184:187], v[48:51]
	v_mfma_f32_16x16x32_bf16 v[36:39], v[168:171], v[192:195], v[36:39]
	v_mfma_f32_16x16x32_bf16 v[32:35], v[176:179], v[192:195], v[32:35]
	v_mfma_f32_16x16x32_bf16 v[20:23], v[168:171], v[200:203], v[20:23]
	v_mfma_f32_16x16x32_bf16 v[16:19], v[176:179], v[200:203], v[16:19]
	v_mfma_f32_16x16x32_bf16 v[4:7], v[168:171], v[208:211], v[4:7]
	v_mfma_f32_16x16x32_bf16 v[0:3], v[176:179], v[208:211], v[0:3]
	v_mfma_f32_16x16x32_bf16 v[52:55], v[172:175], v[188:191], v[52:55]
	v_mfma_f32_16x16x32_bf16 v[48:51], v[180:183], v[188:191], v[48:51]
	v_mfma_f32_16x16x32_bf16 v[36:39], v[172:175], v[196:199], v[36:39]
	v_mfma_f32_16x16x32_bf16 v[32:35], v[180:183], v[196:199], v[32:35]
	v_mfma_f32_16x16x32_bf16 v[20:23], v[172:175], v[204:207], v[20:23]
	v_mfma_f32_16x16x32_bf16 v[16:19], v[180:183], v[204:207], v[16:19]
	v_mfma_f32_16x16x32_bf16 v[4:7], v[172:175], v[212:215], v[4:7]
	v_mfma_f32_16x16x32_bf16 v[0:3], v[180:183], v[212:215], v[0:3]
	s_add_i32 s50, s50, 2
	s_add_u32 s8, s8, 0x100
	s_addc_u32 s9, s9, 0
	s_add_u32 s48, s48, 0x100
	s_addc_u32 s49, s49, 0
	s_cmp_gt_u32 s50, 29
	s_setprio 0
	s_barrier
	s_cbranch_scc0 .LBB0_1248
	s_and_b64 vcc, exec, s[14:15]
	s_cbranch_vccz .LBB0_1251
	s_barrier

; #define PG8_STAGE(bufoff, gbase, voff) do { _Pragma("unroll") for (int _i = 0; _i < 2; ++_i) \
;         __builtin_amdgcn_global_load_lds((const unsigned*)((const char*)(gbase) + (voff)[_i]), (PG8_LAS unsigned*)(lds + (bufoff) + ldsw + _i * 8192), 16, 0, 0); } while (0)
; #define PG8_LDA(dst, b, h) do { _Pragma("unroll") for (int m = 0; m < 4; ++m) _Pragma("unroll") for (int k = 0; k < 2; ++k) dst[m][k] = *(const PG8_LAS bf16x8*)(lds + PG8_SA(b, h) + aoff + m * 2048 + k * 1024); } while (0)
; #define PG8_LDB(dst, b, h) do { _Pragma("unroll") for (int n = 0; n < 2; ++n) _Pragma("unroll") for (int k = 0; k < 2; ++k) dst[n][k] = *(const PG8_LAS bf16x8*)(lds + PG8_SB(b, h) + boff + n * 2048 + k * 1024); } while (0)
; #define PG8_MMA(ai, bj, At, Bt) do { __builtin_amdgcn_s_setprio(1); _Pragma("unroll") for (int m = 0; m < 4; ++m) _Pragma("unroll") for (int n = 0; n < 2; ++n) _Pragma("unroll") for (int k = 0; k < 2; ++k) \
;         acc[ai][bj][m][n] = __builtin_amdgcn_mfma_f32_16x16x32_bf16(Bt[n][k], At[m][k], acc[ai][bj][m][n], 0, 0, 0); __builtin_amdgcn_s_setprio(0); } while (0)
; #define PG8_WAIT_V(n) asm volatile("s_waitcnt vmcnt(" #n ")" ::: "memory")
; #define PG8_WAIT_L(n) asm volatile("s_waitcnt lgkmcnt(" #n ")" ::: "memory")
; template <class Epi, class Sched, bool ALIGN_EPI = false, bool SP2 = false>
; __device__ __forceinline__ void gemm_phase(PG8_LAS unsigned char* lds, const Gemm g, const Sched& S, const Epi& E) {
;     ...
;             const bool last = (t == nt - 2);
;             const char* a1 = cA + (size_t)(t + 1) * kstep;
;             const char* a2 = last ? nA : cA + (size_t)(t + 2) * kstep; const char* b2 = last ? nB : cB + (size_t)(t + 2) * kstep;
;             const char* a3 = a2 + kstep; const char* b3 = b2 + kstep;
;             if (last && has_next) S.a_ready(nxt);
;             if constexpr (SP2) {
;             PG8_LDB(B0, 0, 0); PG8_LDB(B1, 0, 1); PG8_SCHED; PG8_LDA(At, 0, 0); PG8_STAGE(PG8_SA(1, 1), a1 + hstep, voffA);
;             PG8_WAIT_V(8); PG8_WAIT_L(0); PG8_BAR; PG8_MMA(0, 0, At, B0); PG8_MMA(0, 1, At, B1); PG8_BAR; PG8_SCHED;
;             PG8_LDA(At, 0, 1); PG8_STAGE(PG8_SB(0, 0), b2, voffB); PG8_STAGE(PG8_SB(0, 1), b2 + hstep, voffB); PG8_STAGE(PG8_SA(0, 0), a2, voffA);
;             PG8_WAIT_V(8); PG8_WAIT_L(0); PG8_BAR; PG8_MMA(1, 0, At, B0); PG8_MMA(1, 1, At, B1); PG8_BAR; PG8_SCHED;
.LBB0_1407:
	ds_read_b128 v[150:153], v147
	ds_read_b128 v[154:157], v147 offset:1024
	ds_read_b128 v[158:161], v147 offset:2048
	ds_read_b128 v[162:165], v147 offset:3072
	ds_read_b128 v[166:169], v148
	ds_read_b128 v[170:173], v148 offset:1024
	ds_read_b128 v[174:177], v148 offset:2048
	ds_read_b128 v[178:181], v148 offset:3072
	s_add_u32 s28, s10, 0xffe00080
	s_addc_u32 s29, s11, -1
	s_cmp_eq_u32 s51, 12
	s_cselect_b32 s31, s5, s29
	s_cselect_b32 s30, s21, s28
	s_cselect_b32 s29, s23, s50
	s_cselect_b32 s28, s25, s49
	v_lshl_add_u64 v[214:215], s[10:11], 0, v[136:137]
	s_add_i32 m0, s13, 0xc000
	ds_read_b128 v[182:185], v149
	ds_read_b128 v[186:189], v149 offset:1024
	ds_read_b128 v[190:193], v149 offset:2048
	ds_read_b128 v[194:197], v149 offset:3072
	ds_read_b128 v[198:201], v149 offset:4096
	ds_read_b128 v[202:205], v149 offset:5120
	ds_read_b128 v[206:209], v149 offset:6144
	ds_read_b128 v[210:213], v149 offset:7168
	global_load_lds_dwordx4 v[214:215], off
	v_lshl_add_u64 v[214:215], s[10:11], 0, v[138:139]
	s_add_i32 m0, s13, 0xe000
	s_nop 0
	global_load_lds_dwordx4 v[214:215], off
	s_waitcnt vmcnt(8)
	s_waitcnt lgkmcnt(0)
	s_barrier
	s_setprio 1
	s_waitcnt lgkmcnt(0)
	v_mfma_f32_16x16x32_bf16 v[124:127], v[150:153], v[182:185], v[124:127]
	v_mfma_f32_16x16x32_bf16 v[120:123], v[158:161], v[182:185], v[120:123]
	v_mfma_f32_16x16x32_bf16 v[116:119], v[150:153], v[190:193], v[116:119]
	v_mfma_f32_16x16x32_bf16 v[112:115], v[158:161], v[190:193], v[112:115]
	v_mfma_f32_16x16x32_bf16 v[108:111], v[150:153], v[198:201], v[108:111]
	v_mfma_f32_16x16x32_bf16 v[104:107], v[158:161], v[198:201], v[104:107]
	v_mfma_f32_16x16x32_bf16 v[100:103], v[150:153], v[206:209], v[100:103]
	v_mfma_f32_16x16x32_bf16 v[96:99], v[158:161], v[206:209], v[96:99]
	v_mfma_f32_16x16x32_bf16 v[124:127], v[154:157], v[186:189], v[124:127]
	v_mfma_f32_16x16x32_bf16 v[120:123], v[162:165], v[186:189], v[120:123]
	v_mfma_f32_16x16x32_bf16 v[116:119], v[154:157], v[194:197], v[116:119]
	v_mfma_f32_16x16x32_bf16 v[112:115], v[162:165], v[194:197], v[112:115]
	v_mfma_f32_16x16x32_bf16 v[108:111], v[154:157], v[202:205], v[108:111]
	v_mfma_f32_16x16x32_bf16 v[104:107], v[162:165], v[202:205], v[104:107]
	v_mfma_f32_16x16x32_bf16 v[100:103], v[154:157], v[210:213], v[100:103]
	v_mfma_f32_16x16x32_bf16 v[96:99], v[162:165], v[210:213], v[96:99]
	s_setprio 0
	s_setprio 1
	v_mfma_f32_16x16x32_bf16 v[92:95], v[166:169], v[182:185], v[92:95]
	v_mfma_f32_16x16x32_bf16 v[84:87], v[174:177], v[182:185], v[84:87]
	v_mfma_f32_16x16x32_bf16 v[76:79], v[166:169], v[190:193], v[76:79]
	v_mfma_f32_16x16x32_bf16 v[72:75], v[174:177], v[190:193], v[72:75]
	v_mfma_f32_16x16x32_bf16 v[68:71], v[166:169], v[198:201], v[68:71]
	v_mfma_f32_16x16x32_bf16 v[60:63], v[174:177], v[198:201], v[60:63]
	v_mfma_f32_16x16x32_bf16 v[52:55], v[166:169], v[206:209], v[52:55]
	v_mfma_f32_16x16x32_bf16 v[48:51], v[174:177], v[206:209], v[48:51]
	v_mfma_f32_16x16x32_bf16 v[92:95], v[170:173], v[186:189], v[92:95]
	v_mfma_f32_16x16x32_bf16 v[84:87], v[178:181], v[186:189], v[84:87]
	v_mfma_f32_16x16x32_bf16 v[76:79], v[170:173], v[194:197], v[76:79]
	v_mfma_f32_16x16x32_bf16 v[72:75], v[178:181], v[194:197], v[72:75]
	v_mfma_f32_16x16x32_bf16 v[68:71], v[170:173], v[202:205], v[68:71]
	v_mfma_f32_16x16x32_bf16 v[60:63], v[178:181], v[202:205], v[60:63]
	v_mfma_f32_16x16x32_bf16 v[52:55], v[170:173], v[210:213], v[52:55]
	v_mfma_f32_16x16x32_bf16 v[48:51], v[178:181], v[210:213], v[48:51]
	s_setprio 0
	s_barrier
	s_add_i32 s52, s47, s35
	v_lshl_add_u64 v[214:215], s[28:29], 0, v[132:133]
	s_mov_b32 m0, s52
	ds_read_b128 v[182:185], v149 offset:16384
	ds_read_b128 v[186:189], v149 offset:17408
	ds_read_b128 v[190:193], v149 offset:18432
	ds_read_b128 v[194:197], v149 offset:19456
	ds_read_b128 v[198:201], v149 offset:20480
	ds_read_b128 v[202:205], v149 offset:21504
	ds_read_b128 v[206:209], v149 offset:22528
	ds_read_b128 v[210:213], v149 offset:23552
	global_load_lds_dwordx4 v[214:215], off
	s_add_i32 m0, s52, 0x2000
	s_add_u32 s52, s28, 0x200000
	v_lshl_add_u64 v[216:217], s[28:29], 0, v[128:129]
	s_addc_u32 s53, s29, 0
	s_add_i32 s54, s48, s35
	global_load_lds_dwordx4 v[216:217], off
	v_lshl_add_u64 v[222:223], s[52:53], 0, v[132:133]
	s_mov_b32 m0, s54
	v_lshl_add_u64 v[224:225], s[30:31], 0, v[130:131]
	global_load_lds_dwordx4 v[222:223], off
	v_lshl_add_u64 v[222:223], s[52:53], 0, v[128:129]
	s_add_i32 m0, s54, 0x2000
	s_nop 0
	global_load_lds_dwordx4 v[222:223], off
	v_lshl_add_u64 v[222:223], s[30:31], 0, v[134:135]
	s_mov_b32 m0, s13
	s_nop 0
	global_load_lds_dwordx4 v[222:223], off
	s_mov_b32 m0, s15
	s_nop 0
	global_load_lds_dwordx4 v[224:225], off
	s_waitcnt vmcnt(8)
	s_waitcnt lgkmcnt(0)
	s_barrier
; #define PG8_STAGE(bufoff, gbase, voff) do { _Pragma("unroll") for (int _i = 0; _i < 2; ++_i) \
;         __builtin_amdgcn_global_load_lds((const unsigned*)((const char*)(gbase) + (voff)[_i]), (PG8_LAS unsigned*)(lds + (bufoff) + ldsw + _i * 8192), 16, 0, 0); } while (0)
; #define PG8_LDA(dst, b, h) do { _Pragma("unroll") for (int m = 0; m < 4; ++m) _Pragma("unroll") for (int k = 0; k < 2; ++k) dst[m][k] = *(const PG8_LAS bf16x8*)(lds + PG8_SA(b, h) + aoff + m * 2048 + k * 1024); } while (0)
; #define PG8_LDB(dst, b, h) do { _Pragma("unroll") for (int n = 0; n < 2; ++n) _Pragma("unroll") for (int k = 0; k < 2; ++k) dst[n][k] = *(const PG8_LAS bf16x8*)(lds + PG8_SB(b, h) + boff + n * 2048 + k * 1024); } while (0)
; #define PG8_MMA(ai, bj, At, Bt) do { __builtin_amdgcn_s_setprio(1); _Pragma("unroll") for (int m = 0; m < 4; ++m) _Pragma("unroll") for (int n = 0; n < 2; ++n) _Pragma("unroll") for (int k = 0; k < 2; ++k) \
;         acc[ai][bj][m][n] = __builtin_amdgcn_mfma_f32_16x16x32_bf16(Bt[n][k], At[m][k], acc[ai][bj][m][n], 0, 0, 0); __builtin_amdgcn_s_setprio(0); } while (0)
; #define PG8_WAIT_V(n) asm volatile("s_waitcnt vmcnt(" #n ")" ::: "memory")
; #define PG8_WAIT_L(n) asm volatile("s_waitcnt lgkmcnt(" #n ")" ::: "memory")
; #define PG8_BAR __builtin_amdgcn_s_barrier()
; #define PG8_SCHED __builtin_amdgcn_sched_barrier(0)
; template <class Epi, class Sched, bool ALIGN_EPI = false, bool SP2 = false>
; __device__ __forceinline__ void gemm_phase(PG8_LAS unsigned char* lds, const Gemm g, const Sched& S, const Epi& E) {
;     ...
;             PG8_WAIT_V(8); PG8_WAIT_L(0); PG8_BAR; PG8_MMA(1, 0, At, B0); PG8_MMA(1, 1, At, B1); PG8_BAR; PG8_SCHED;
;             PG8_LDB(B0, 1, 0); PG8_LDB(B1, 1, 1); PG8_SCHED; PG8_LDA(At, 1, 0); PG8_STAGE(PG8_SA(0, 1), a2 + hstep, voffA);
;             PG8_WAIT_V(8); PG8_WAIT_L(0); PG8_BAR; PG8_MMA(0, 0, At, B0); PG8_MMA(0, 1, At, B1); PG8_BAR; PG8_SCHED;
	s_setprio 1
	s_waitcnt lgkmcnt(0)
	v_mfma_f32_16x16x32_bf16 v[88:91], v[150:153], v[182:185], v[88:91]
	v_mfma_f32_16x16x32_bf16 v[80:83], v[158:161], v[182:185], v[80:83]
	v_mfma_f32_16x16x32_bf16 v[64:67], v[150:153], v[190:193], v[64:67]
	v_mfma_f32_16x16x32_bf16 v[56:59], v[158:161], v[190:193], v[56:59]
	v_mfma_f32_16x16x32_bf16 v[44:47], v[150:153], v[198:201], v[44:47]
	v_mfma_f32_16x16x32_bf16 v[40:43], v[158:161], v[198:201], v[40:43]
	v_mfma_f32_16x16x32_bf16 v[36:39], v[150:153], v[206:209], v[36:39]
	v_mfma_f32_16x16x32_bf16 v[32:35], v[158:161], v[206:209], v[32:35]
	v_mfma_f32_16x16x32_bf16 v[88:91], v[154:157], v[186:189], v[88:91]
	v_mfma_f32_16x16x32_bf16 v[80:83], v[162:165], v[186:189], v[80:83]
	v_mfma_f32_16x16x32_bf16 v[64:67], v[154:157], v[194:197], v[64:67]
	v_mfma_f32_16x16x32_bf16 v[56:59], v[162:165], v[194:197], v[56:59]
	v_mfma_f32_16x16x32_bf16 v[44:47], v[154:157], v[202:205], v[44:47]
	v_mfma_f32_16x16x32_bf16 v[40:43], v[162:165], v[202:205], v[40:43]
	v_mfma_f32_16x16x32_bf16 v[36:39], v[154:157], v[210:213], v[36:39]
	v_mfma_f32_16x16x32_bf16 v[32:35], v[162:165], v[210:213], v[32:35]
	s_setprio 0
	s_setprio 1
	v_mfma_f32_16x16x32_bf16 v[28:31], v[166:169], v[182:185], v[28:31]
	v_mfma_f32_16x16x32_bf16 v[24:27], v[174:177], v[182:185], v[24:27]
	v_mfma_f32_16x16x32_bf16 v[20:23], v[166:169], v[190:193], v[20:23]
	v_mfma_f32_16x16x32_bf16 v[16:19], v[174:177], v[190:193], v[16:19]
	v_mfma_f32_16x16x32_bf16 v[12:15], v[166:169], v[198:201], v[12:15]
	v_mfma_f32_16x16x32_bf16 v[8:11], v[174:177], v[198:201], v[8:11]
	v_mfma_f32_16x16x32_bf16 v[4:7], v[166:169], v[206:209], v[4:7]
	v_mfma_f32_16x16x32_bf16 v[0:3], v[174:177], v[206:209], v[0:3]
	v_mfma_f32_16x16x32_bf16 v[28:31], v[170:173], v[186:189], v[28:31]
	v_mfma_f32_16x16x32_bf16 v[24:27], v[178:181], v[186:189], v[24:27]
	v_mfma_f32_16x16x32_bf16 v[20:23], v[170:173], v[194:197], v[20:23]
	v_mfma_f32_16x16x32_bf16 v[16:19], v[178:181], v[194:197], v[16:19]
	v_mfma_f32_16x16x32_bf16 v[12:15], v[170:173], v[202:205], v[12:15]
	v_mfma_f32_16x16x32_bf16 v[8:11], v[178:181], v[202:205], v[8:11]
	v_mfma_f32_16x16x32_bf16 v[4:7], v[170:173], v[210:213], v[4:7]
	v_mfma_f32_16x16x32_bf16 v[0:3], v[178:181], v[210:213], v[0:3]
	s_setprio 0
	s_barrier
	s_add_i32 s52, 0, 0x18000
	s_add_i32 s53, 0, 0x1c000
	v_add_u32_e32 v162, s52, v145
	v_add_u32_e32 v178, s53, v145
	ds_read_b128 v[150:153], v162
	ds_read_b128 v[154:157], v162 offset:1024
	ds_read_b128 v[158:161], v162 offset:2048
	ds_read_b128 v[162:165], v162 offset:3072
	ds_read_b128 v[166:169], v178
	ds_read_b128 v[170:173], v178 offset:1024
	ds_read_b128 v[174:177], v178 offset:2048
	ds_read_b128 v[178:181], v178 offset:3072
	s_add_u32 s30, s30, 0x200000
	s_addc_u32 s31, s31, 0
	s_mov_b32 m0, s37
	v_lshl_add_u64 v[226:227], s[30:31], 0, v[134:135]
	ds_read_b128 v[182:185], v149 offset:32768
	ds_read_b128 v[186:189], v149 offset:33792
	ds_read_b128 v[190:193], v149 offset:34816
	ds_read_b128 v[194:197], v149 offset:35840
	ds_read_b128 v[198:201], v149 offset:36864
	ds_read_b128 v[202:205], v149 offset:37888
	ds_read_b128 v[206:209], v149 offset:38912
	ds_read_b128 v[210:213], v149 offset:39936
	global_load_lds_dwordx4 v[226:227], off
	v_lshl_add_u64 v[226:227], s[30:31], 0, v[130:131]
	s_mov_b32 m0, s40
	s_nop 0
	global_load_lds_dwordx4 v[226:227], off
	s_waitcnt vmcnt(8)
	s_waitcnt lgkmcnt(0)
	s_barrier
	s_setprio 1
	s_waitcnt lgkmcnt(0)
	v_mfma_f32_16x16x32_bf16 v[124:127], v[150:153], v[182:185], v[124:127]
	v_mfma_f32_16x16x32_bf16 v[120:123], v[158:161], v[182:185], v[120:123]
	v_mfma_f32_16x16x32_bf16 v[116:119], v[150:153], v[190:193], v[116:119]
	v_mfma_f32_16x16x32_bf16 v[112:115], v[158:161], v[190:193], v[112:115]
	v_mfma_f32_16x16x32_bf16 v[108:111], v[150:153], v[198:201], v[108:111]
	v_mfma_f32_16x16x32_bf16 v[104:107], v[158:161], v[198:201], v[104:107]
	v_mfma_f32_16x16x32_bf16 v[100:103], v[150:153], v[206:209], v[100:103]
	v_mfma_f32_16x16x32_bf16 v[96:99], v[158:161], v[206:209], v[96:99]
	v_mfma_f32_16x16x32_bf16 v[124:127], v[154:157], v[186:189], v[124:127]
	v_mfma_f32_16x16x32_bf16 v[120:123], v[162:165], v[186:189], v[120:123]
	v_mfma_f32_16x16x32_bf16 v[116:119], v[154:157], v[194:197], v[116:119]
	v_mfma_f32_16x16x32_bf16 v[112:115], v[162:165], v[194:197], v[112:115]
	v_mfma_f32_16x16x32_bf16 v[108:111], v[154:157], v[202:205], v[108:111]
	v_mfma_f32_16x16x32_bf16 v[104:107], v[162:165], v[202:205], v[104:107]
	v_mfma_f32_16x16x32_bf16 v[100:103], v[154:157], v[210:213], v[100:103]
	v_mfma_f32_16x16x32_bf16 v[96:99], v[162:165], v[210:213], v[96:99]
	s_setprio 0
	s_setprio 1
	v_mfma_f32_16x16x32_bf16 v[92:95], v[166:169], v[182:185], v[92:95]
	v_mfma_f32_16x16x32_bf16 v[84:87], v[174:177], v[182:185], v[84:87]
	v_mfma_f32_16x16x32_bf16 v[76:79], v[166:169], v[190:193], v[76:79]
	v_mfma_f32_16x16x32_bf16 v[72:75], v[174:177], v[190:193], v[72:75]
	v_mfma_f32_16x16x32_bf16 v[68:71], v[166:169], v[198:201], v[68:71]
	v_mfma_f32_16x16x32_bf16 v[60:63], v[174:177], v[198:201], v[60:63]
	v_mfma_f32_16x16x32_bf16 v[52:55], v[166:169], v[206:209], v[52:55]
	v_mfma_f32_16x16x32_bf16 v[48:51], v[174:177], v[206:209], v[48:51]
	v_mfma_f32_16x16x32_bf16 v[92:95], v[170:173], v[186:189], v[92:95]
	v_mfma_f32_16x16x32_bf16 v[84:87], v[178:181], v[186:189], v[84:87]
	v_mfma_f32_16x16x32_bf16 v[76:79], v[170:173], v[194:197], v[76:79]
	v_mfma_f32_16x16x32_bf16 v[72:75], v[178:181], v[194:197], v[72:75]
	v_mfma_f32_16x16x32_bf16 v[68:71], v[170:173], v[202:205], v[68:71]
	v_mfma_f32_16x16x32_bf16 v[60:63], v[178:181], v[202:205], v[60:63]
	v_mfma_f32_16x16x32_bf16 v[52:55], v[170:173], v[210:213], v[52:55]
	v_mfma_f32_16x16x32_bf16 v[48:51], v[178:181], v[210:213], v[48:51]
	s_setprio 0
	s_barrier
; #define PG8_STAGE(bufoff, gbase, voff) do { _Pragma("unroll") for (int _i = 0; _i < 2; ++_i) \
;         __builtin_amdgcn_global_load_lds((const unsigned*)((const char*)(gbase) + (voff)[_i]), (PG8_LAS unsigned*)(lds + (bufoff) + ldsw + _i * 8192), 16, 0, 0); } while (0)
; #define PG8_LDA(dst, b, h) do { _Pragma("unroll") for (int m = 0; m < 4; ++m) _Pragma("unroll") for (int k = 0; k < 2; ++k) dst[m][k] = *(const PG8_LAS bf16x8*)(lds + PG8_SA(b, h) + aoff + m * 2048 + k * 1024); } while (0)
; #define PG8_MMA(ai, bj, At, Bt) do { __builtin_amdgcn_s_setprio(1); _Pragma("unroll") for (int m = 0; m < 4; ++m) _Pragma("unroll") for (int n = 0; n < 2; ++n) _Pragma("unroll") for (int k = 0; k < 2; ++k) \
;         acc[ai][bj][m][n] = __builtin_amdgcn_mfma_f32_16x16x32_bf16(Bt[n][k], At[m][k], acc[ai][bj][m][n], 0, 0, 0); __builtin_amdgcn_s_setprio(0); } while (0)
; #define PG8_WAIT_V(n) asm volatile("s_waitcnt vmcnt(" #n ")" ::: "memory")
; #define PG8_WAIT_L(n) asm volatile("s_waitcnt lgkmcnt(" #n ")" ::: "memory")
; #define PG8_BAR __builtin_amdgcn_s_barrier()
; #define PG8_SCHED __builtin_amdgcn_sched_barrier(0)
; template <class Epi, class Sched, bool ALIGN_EPI = false, bool SP2 = false>
; __device__ __forceinline__ void gemm_phase(PG8_LAS unsigned char* lds, const Gemm g, const Sched& S, const Epi& E) {
;     ...
;         for (int t = 0; t < nt; t += 2) {
;             const bool last = (t == nt - 2);
;             const char* a1 = cA + (size_t)(t + 1) * kstep;
;             const char* a2 = last ? nA : cA + (size_t)(t + 2) * kstep; const char* b2 = last ? nB : cB + (size_t)(t + 2) * kstep;
;     ...
;             PG8_LDA(At, 1, 1); PG8_STAGE(PG8_SB(1, 0), b3, voffB); PG8_STAGE(PG8_SB(1, 1), b3 + hstep, voffB); PG8_STAGE(PG8_SA(1, 0), a3, voffA);
;             PG8_WAIT_V(8); PG8_WAIT_L(0); PG8_BAR; PG8_MMA(1, 0, At, B0); PG8_MMA(1, 1, At, B1); PG8_BAR; PG8_SCHED;
	s_add_i32 s30, s52, s35
	v_lshl_add_u64 v[214:215], v[214:215], 0, s[16:17]
	s_mov_b32 m0, s30
	ds_read_b128 v[182:185], v149 offset:49152
	ds_read_b128 v[186:189], v149 offset:50176
	ds_read_b128 v[190:193], v149 offset:51200
	ds_read_b128 v[194:197], v149 offset:52224
	ds_read_b128 v[198:201], v149 offset:53248
	ds_read_b128 v[202:205], v149 offset:54272
	ds_read_b128 v[206:209], v149 offset:55296
	ds_read_b128 v[210:213], v149 offset:56320
	global_load_lds_dwordx4 v[214:215], off
	s_add_i32 m0, s30, 0x2000
	s_add_u32 s28, s28, 0x200080
	v_lshl_add_u64 v[214:215], v[216:217], 0, s[16:17]
	s_addc_u32 s29, s29, 0
	s_add_i32 s30, s53, s35
	global_load_lds_dwordx4 v[214:215], off
	v_lshl_add_u64 v[214:215], s[28:29], 0, v[132:133]
	s_mov_b32 m0, s30
	s_nop 0
	global_load_lds_dwordx4 v[214:215], off
	v_lshl_add_u64 v[214:215], s[28:29], 0, v[128:129]
	s_add_i32 m0, s30, 0x2000
	s_nop 0
	global_load_lds_dwordx4 v[214:215], off
	v_lshl_add_u64 v[214:215], v[222:223], 0, s[16:17]
	s_mov_b32 m0, s44
	s_nop 0
	global_load_lds_dwordx4 v[214:215], off
	v_lshl_add_u64 v[214:215], v[224:225], 0, s[16:17]
	s_mov_b32 m0, s45
	s_nop 0
	global_load_lds_dwordx4 v[214:215], off
	s_waitcnt vmcnt(8)
	s_waitcnt lgkmcnt(0)
	s_barrier
	s_setprio 1
	s_waitcnt lgkmcnt(0)
	v_mfma_f32_16x16x32_bf16 v[88:91], v[150:153], v[182:185], v[88:91]
	v_mfma_f32_16x16x32_bf16 v[80:83], v[158:161], v[182:185], v[80:83]
	v_mfma_f32_16x16x32_bf16 v[64:67], v[150:153], v[190:193], v[64:67]
	v_mfma_f32_16x16x32_bf16 v[56:59], v[158:161], v[190:193], v[56:59]
	v_mfma_f32_16x16x32_bf16 v[44:47], v[150:153], v[198:201], v[44:47]
	v_mfma_f32_16x16x32_bf16 v[40:43], v[158:161], v[198:201], v[40:43]
	v_mfma_f32_16x16x32_bf16 v[36:39], v[150:153], v[206:209], v[36:39]
	v_mfma_f32_16x16x32_bf16 v[32:35], v[158:161], v[206:209], v[32:35]
	v_mfma_f32_16x16x32_bf16 v[88:91], v[154:157], v[186:189], v[88:91]
	v_mfma_f32_16x16x32_bf16 v[80:83], v[162:165], v[186:189], v[80:83]
	v_mfma_f32_16x16x32_bf16 v[64:67], v[154:157], v[194:197], v[64:67]
	v_mfma_f32_16x16x32_bf16 v[56:59], v[162:165], v[194:197], v[56:59]
	v_mfma_f32_16x16x32_bf16 v[44:47], v[154:157], v[202:205], v[44:47]
	v_mfma_f32_16x16x32_bf16 v[40:43], v[162:165], v[202:205], v[40:43]
	v_mfma_f32_16x16x32_bf16 v[36:39], v[154:157], v[210:213], v[36:39]
	v_mfma_f32_16x16x32_bf16 v[32:35], v[162:165], v[210:213], v[32:35]
	s_setprio 0
	s_setprio 1
	v_mfma_f32_16x16x32_bf16 v[28:31], v[166:169], v[182:185], v[28:31]
	v_mfma_f32_16x16x32_bf16 v[24:27], v[174:177], v[182:185], v[24:27]
	v_mfma_f32_16x16x32_bf16 v[20:23], v[166:169], v[190:193], v[20:23]
	v_mfma_f32_16x16x32_bf16 v[16:19], v[174:177], v[190:193], v[16:19]
	v_mfma_f32_16x16x32_bf16 v[12:15], v[166:169], v[198:201], v[12:15]
	v_mfma_f32_16x16x32_bf16 v[8:11], v[174:177], v[198:201], v[8:11]
	v_mfma_f32_16x16x32_bf16 v[4:7], v[166:169], v[206:209], v[4:7]
	v_mfma_f32_16x16x32_bf16 v[0:3], v[174:177], v[206:209], v[0:3]
	v_mfma_f32_16x16x32_bf16 v[28:31], v[170:173], v[186:189], v[28:31]
	v_mfma_f32_16x16x32_bf16 v[24:27], v[178:181], v[186:189], v[24:27]
	v_mfma_f32_16x16x32_bf16 v[20:23], v[170:173], v[194:197], v[20:23]
	v_mfma_f32_16x16x32_bf16 v[16:19], v[178:181], v[194:197], v[16:19]
	v_mfma_f32_16x16x32_bf16 v[12:15], v[170:173], v[202:205], v[12:15]
	v_mfma_f32_16x16x32_bf16 v[8:11], v[178:181], v[202:205], v[8:11]
	v_mfma_f32_16x16x32_bf16 v[4:7], v[170:173], v[210:213], v[4:7]
	v_mfma_f32_16x16x32_bf16 v[0:3], v[178:181], v[210:213], v[0:3]
	s_add_i32 s51, s51, 2
	s_add_u32 s10, s10, 0x100
	s_addc_u32 s11, s11, 0
	s_add_u32 s49, s49, 0x100
	s_addc_u32 s50, s50, 0
	s_cmp_gt_u32 s51, 13
	s_setprio 0
	s_barrier
	s_cbranch_scc0 .LBB0_1407
	s_and_b64 vcc, exec, s[18:19]
	s_cbranch_vccz .LBB0_1410
	s_barrier

; #define PG8_STAGE(bufoff, gbase, voff) do { _Pragma("unroll") for (int _i = 0; _i < 2; ++_i) \
;         __builtin_amdgcn_global_load_lds((const unsigned*)((const char*)(gbase) + (voff)[_i]), (PG8_LAS unsigned*)(lds + (bufoff) + ldsw + _i * 8192), 16, 0, 0); } while (0)
; #define PG8_LDA(dst, b, h) do { _Pragma("unroll") for (int m = 0; m < 4; ++m) _Pragma("unroll") for (int k = 0; k < 2; ++k) dst[m][k] = *(const PG8_LAS bf16x8*)(lds + PG8_SA(b, h) + aoff + m * 2048 + k * 1024); } while (0)
; #define PG8_LDB(dst, b, h) do { _Pragma("unroll") for (int n = 0; n < 2; ++n) _Pragma("unroll") for (int k = 0; k < 2; ++k) dst[n][k] = *(const PG8_LAS bf16x8*)(lds + PG8_SB(b, h) + boff + n * 2048 + k * 1024); } while (0)
; #define PG8_MMA(ai, bj, At, Bt) do { __builtin_amdgcn_s_setprio(1); _Pragma("unroll") for (int m = 0; m < 4; ++m) _Pragma("unroll") for (int n = 0; n < 2; ++n) _Pragma("unroll") for (int k = 0; k < 2; ++k) \
;         acc[ai][bj][m][n] = __builtin_amdgcn_mfma_f32_16x16x32_bf16(Bt[n][k], At[m][k], acc[ai][bj][m][n], 0, 0, 0); __builtin_amdgcn_s_setprio(0); } while (0)
; #define PG8_WAIT_V(n) asm volatile("s_waitcnt vmcnt(" #n ")" ::: "memory")
; #define PG8_WAIT_L(n) asm volatile("s_waitcnt lgkmcnt(" #n ")" ::: "memory")
; template <class Epi, class Sched, bool ALIGN_EPI = false, bool SP2 = false>
; __device__ __forceinline__ void gemm_phase(PG8_LAS unsigned char* lds, const Gemm g, const Sched& S, const Epi& E) {
;     ...
;             const bool last = (t == nt - 2);
;             const char* a1 = cA + (size_t)(t + 1) * kstep;
;             const char* a2 = last ? nA : cA + (size_t)(t + 2) * kstep; const char* b2 = last ? nB : cB + (size_t)(t + 2) * kstep;
;             const char* a3 = a2 + kstep; const char* b3 = b2 + kstep;
;             if (last && has_next) S.a_ready(nxt);
;             if constexpr (SP2) {
;             PG8_LDB(B0, 0, 0); PG8_LDB(B1, 0, 1); PG8_SCHED; PG8_LDA(At, 0, 0); PG8_STAGE(PG8_SA(1, 1), a1 + hstep, voffA);
;             PG8_WAIT_V(8); PG8_WAIT_L(0); PG8_BAR; PG8_MMA(0, 0, At, B0); PG8_MMA(0, 1, At, B1); PG8_BAR; PG8_SCHED;
;             PG8_LDA(At, 0, 1); PG8_STAGE(PG8_SB(0, 0), b2, voffB); PG8_STAGE(PG8_SB(0, 1), b2 + hstep, voffB); PG8_STAGE(PG8_SA(0, 0), a2, voffA);
;             PG8_WAIT_V(8); PG8_WAIT_L(0); PG8_BAR; PG8_MMA(1, 0, At, B0); PG8_MMA(1, 1, At, B1); PG8_BAR; PG8_SCHED;
.LBB0_1582:
	ds_read_b128 v[154:157], v150
	ds_read_b128 v[158:161], v150 offset:1024
	ds_read_b128 v[162:165], v150 offset:2048
	ds_read_b128 v[166:169], v150 offset:3072
	ds_read_b128 v[170:173], v151
	ds_read_b128 v[174:177], v151 offset:1024
	ds_read_b128 v[178:181], v151 offset:2048
	ds_read_b128 v[182:185], v151 offset:3072
	s_add_u32 s10, s8, 0xfff80080
	s_addc_u32 s11, s9, -1
	s_cmp_eq_u32 s50, 28
	s_cselect_b32 s25, s17, s11
	s_cselect_b32 s24, s46, s10
	s_cselect_b32 s11, s15, s49
	s_cselect_b32 s10, s47, s48
	v_lshl_add_u64 v[146:147], s[8:9], 0, v[136:137]
	s_add_i32 m0, s23, 0xc000
	ds_read_b128 v[186:189], v152
	ds_read_b128 v[190:193], v152 offset:1024
	ds_read_b128 v[194:197], v152 offset:2048
	ds_read_b128 v[198:201], v152 offset:3072
	ds_read_b128 v[202:205], v152 offset:4096
	ds_read_b128 v[206:209], v152 offset:5120
	ds_read_b128 v[210:213], v152 offset:6144
	ds_read_b128 v[214:217], v152 offset:7168
	global_load_lds_dwordx4 v[146:147], off
	v_lshl_add_u64 v[146:147], s[8:9], 0, v[138:139]
	s_add_i32 m0, s23, 0xe000
	s_nop 0
	global_load_lds_dwordx4 v[146:147], off
	s_waitcnt vmcnt(8)
	s_waitcnt lgkmcnt(0)
	s_barrier
	s_setprio 1
	s_waitcnt lgkmcnt(0)
	v_mfma_f32_16x16x32_bf16 v[124:127], v[154:157], v[186:189], v[124:127]
	v_mfma_f32_16x16x32_bf16 v[120:123], v[162:165], v[186:189], v[120:123]
	v_mfma_f32_16x16x32_bf16 v[112:115], v[154:157], v[194:197], v[112:115]
	v_mfma_f32_16x16x32_bf16 v[104:107], v[162:165], v[194:197], v[104:107]
	v_mfma_f32_16x16x32_bf16 v[96:99], v[154:157], v[202:205], v[96:99]
	v_mfma_f32_16x16x32_bf16 v[88:91], v[162:165], v[202:205], v[88:91]
	v_mfma_f32_16x16x32_bf16 v[80:83], v[154:157], v[210:213], v[80:83]
	v_mfma_f32_16x16x32_bf16 v[72:75], v[162:165], v[210:213], v[72:75]
	v_mfma_f32_16x16x32_bf16 v[124:127], v[158:161], v[190:193], v[124:127]
	v_mfma_f32_16x16x32_bf16 v[120:123], v[166:169], v[190:193], v[120:123]
	v_mfma_f32_16x16x32_bf16 v[112:115], v[158:161], v[198:201], v[112:115]
	v_mfma_f32_16x16x32_bf16 v[104:107], v[166:169], v[198:201], v[104:107]
	v_mfma_f32_16x16x32_bf16 v[96:99], v[158:161], v[206:209], v[96:99]
	v_mfma_f32_16x16x32_bf16 v[88:91], v[166:169], v[206:209], v[88:91]
	v_mfma_f32_16x16x32_bf16 v[80:83], v[158:161], v[214:217], v[80:83]
	v_mfma_f32_16x16x32_bf16 v[72:75], v[166:169], v[214:217], v[72:75]
	s_setprio 0
	s_setprio 1
	v_mfma_f32_16x16x32_bf16 v[116:119], v[170:173], v[186:189], v[116:119]
	v_mfma_f32_16x16x32_bf16 v[108:111], v[178:181], v[186:189], v[108:111]
	v_mfma_f32_16x16x32_bf16 v[100:103], v[170:173], v[194:197], v[100:103]
	v_mfma_f32_16x16x32_bf16 v[92:95], v[178:181], v[194:197], v[92:95]
	v_mfma_f32_16x16x32_bf16 v[84:87], v[170:173], v[202:205], v[84:87]
	v_mfma_f32_16x16x32_bf16 v[76:79], v[178:181], v[202:205], v[76:79]
	v_mfma_f32_16x16x32_bf16 v[68:71], v[170:173], v[210:213], v[68:71]
	v_mfma_f32_16x16x32_bf16 v[64:67], v[178:181], v[210:213], v[64:67]
	v_mfma_f32_16x16x32_bf16 v[116:119], v[174:177], v[190:193], v[116:119]
	v_mfma_f32_16x16x32_bf16 v[108:111], v[182:185], v[190:193], v[108:111]
	v_mfma_f32_16x16x32_bf16 v[100:103], v[174:177], v[198:201], v[100:103]
	v_mfma_f32_16x16x32_bf16 v[92:95], v[182:185], v[198:201], v[92:95]
	v_mfma_f32_16x16x32_bf16 v[84:87], v[174:177], v[206:209], v[84:87]
	v_mfma_f32_16x16x32_bf16 v[76:79], v[182:185], v[206:209], v[76:79]
	v_mfma_f32_16x16x32_bf16 v[68:71], v[174:177], v[214:217], v[68:71]
	v_mfma_f32_16x16x32_bf16 v[64:67], v[182:185], v[214:217], v[64:67]
	s_setprio 0
	s_barrier
	s_add_i32 s51, s43, s28
	v_lshl_add_u64 v[146:147], s[10:11], 0, v[132:133]
	s_mov_b32 m0, s51
	ds_read_b128 v[186:189], v152 offset:16384
	ds_read_b128 v[190:193], v152 offset:17408
	ds_read_b128 v[194:197], v152 offset:18432
	ds_read_b128 v[198:201], v152 offset:19456
	ds_read_b128 v[202:205], v152 offset:20480
	ds_read_b128 v[206:209], v152 offset:21504
	ds_read_b128 v[210:213], v152 offset:22528
	ds_read_b128 v[214:217], v152 offset:23552
	global_load_lds_dwordx4 v[146:147], off
	s_add_i32 m0, s51, 0x2000
	s_add_u32 s52, s10, 0x80000
	v_lshl_add_u64 v[222:223], s[10:11], 0, v[128:129]
	s_addc_u32 s53, s11, 0
	s_add_i32 s51, s44, s28
	global_load_lds_dwordx4 v[222:223], off
	v_lshl_add_u64 v[224:225], s[52:53], 0, v[132:133]
	s_mov_b32 m0, s51
	v_lshl_add_u64 v[226:227], s[24:25], 0, v[130:131]
	global_load_lds_dwordx4 v[224:225], off
	v_lshl_add_u64 v[224:225], s[52:53], 0, v[128:129]
	s_add_i32 m0, s51, 0x2000
	s_nop 0
	global_load_lds_dwordx4 v[224:225], off
	v_lshl_add_u64 v[224:225], s[24:25], 0, v[134:135]
	s_mov_b32 m0, s23
	s_nop 0
	global_load_lds_dwordx4 v[224:225], off
	s_mov_b32 m0, s31
	s_nop 0
	global_load_lds_dwordx4 v[226:227], off
	s_waitcnt vmcnt(8)
	s_waitcnt lgkmcnt(0)
	s_barrier
; #define PG8_STAGE(bufoff, gbase, voff) do { _Pragma("unroll") for (int _i = 0; _i < 2; ++_i) \
;         __builtin_amdgcn_global_load_lds((const unsigned*)((const char*)(gbase) + (voff)[_i]), (PG8_LAS unsigned*)(lds + (bufoff) + ldsw + _i * 8192), 16, 0, 0); } while (0)
; #define PG8_LDA(dst, b, h) do { _Pragma("unroll") for (int m = 0; m < 4; ++m) _Pragma("unroll") for (int k = 0; k < 2; ++k) dst[m][k] = *(const PG8_LAS bf16x8*)(lds + PG8_SA(b, h) + aoff + m * 2048 + k * 1024); } while (0)
; #define PG8_LDB(dst, b, h) do { _Pragma("unroll") for (int n = 0; n < 2; ++n) _Pragma("unroll") for (int k = 0; k < 2; ++k) dst[n][k] = *(const PG8_LAS bf16x8*)(lds + PG8_SB(b, h) + boff + n * 2048 + k * 1024); } while (0)
; #define PG8_MMA(ai, bj, At, Bt) do { __builtin_amdgcn_s_setprio(1); _Pragma("unroll") for (int m = 0; m < 4; ++m) _Pragma("unroll") for (int n = 0; n < 2; ++n) _Pragma("unroll") for (int k = 0; k < 2; ++k) \
;         acc[ai][bj][m][n] = __builtin_amdgcn_mfma_f32_16x16x32_bf16(Bt[n][k], At[m][k], acc[ai][bj][m][n], 0, 0, 0); __builtin_amdgcn_s_setprio(0); } while (0)
; #define PG8_WAIT_V(n) asm volatile("s_waitcnt vmcnt(" #n ")" ::: "memory")
; #define PG8_WAIT_L(n) asm volatile("s_waitcnt lgkmcnt(" #n ")" ::: "memory")
; #define PG8_BAR __builtin_amdgcn_s_barrier()
; #define PG8_SCHED __builtin_amdgcn_sched_barrier(0)
; template <class Epi, class Sched, bool ALIGN_EPI = false, bool SP2 = false>
; __device__ __forceinline__ void gemm_phase(PG8_LAS unsigned char* lds, const Gemm g, const Sched& S, const Epi& E) {
;     ...
;             PG8_WAIT_V(8); PG8_WAIT_L(0); PG8_BAR; PG8_MMA(1, 0, At, B0); PG8_MMA(1, 1, At, B1); PG8_BAR; PG8_SCHED;
;             PG8_LDB(B0, 1, 0); PG8_LDB(B1, 1, 1); PG8_SCHED; PG8_LDA(At, 1, 0); PG8_STAGE(PG8_SA(0, 1), a2 + hstep, voffA);
;             PG8_WAIT_V(8); PG8_WAIT_L(0); PG8_BAR; PG8_MMA(0, 0, At, B0); PG8_MMA(0, 1, At, B1); PG8_BAR; PG8_SCHED;
	s_setprio 1
	s_waitcnt lgkmcnt(0)
	v_mfma_f32_16x16x32_bf16 v[60:63], v[154:157], v[186:189], v[60:63]
	v_mfma_f32_16x16x32_bf16 v[56:59], v[162:165], v[186:189], v[56:59]
	v_mfma_f32_16x16x32_bf16 v[48:51], v[154:157], v[194:197], v[48:51]
	v_mfma_f32_16x16x32_bf16 v[40:43], v[162:165], v[194:197], v[40:43]
	v_mfma_f32_16x16x32_bf16 v[32:35], v[154:157], v[202:205], v[32:35]
	v_mfma_f32_16x16x32_bf16 v[24:27], v[162:165], v[202:205], v[24:27]
	v_mfma_f32_16x16x32_bf16 v[16:19], v[154:157], v[210:213], v[16:19]
	v_mfma_f32_16x16x32_bf16 v[8:11], v[162:165], v[210:213], v[8:11]
	v_mfma_f32_16x16x32_bf16 v[60:63], v[158:161], v[190:193], v[60:63]
	v_mfma_f32_16x16x32_bf16 v[56:59], v[166:169], v[190:193], v[56:59]
	v_mfma_f32_16x16x32_bf16 v[48:51], v[158:161], v[198:201], v[48:51]
	v_mfma_f32_16x16x32_bf16 v[40:43], v[166:169], v[198:201], v[40:43]
	v_mfma_f32_16x16x32_bf16 v[32:35], v[158:161], v[206:209], v[32:35]
	v_mfma_f32_16x16x32_bf16 v[24:27], v[166:169], v[206:209], v[24:27]
	v_mfma_f32_16x16x32_bf16 v[16:19], v[158:161], v[214:217], v[16:19]
	v_mfma_f32_16x16x32_bf16 v[8:11], v[166:169], v[214:217], v[8:11]
	s_setprio 0
	s_setprio 1
	v_mfma_f32_16x16x32_bf16 v[52:55], v[170:173], v[186:189], v[52:55]
	v_mfma_f32_16x16x32_bf16 v[44:47], v[178:181], v[186:189], v[44:47]
	v_mfma_f32_16x16x32_bf16 v[36:39], v[170:173], v[194:197], v[36:39]
	v_mfma_f32_16x16x32_bf16 v[28:31], v[178:181], v[194:197], v[28:31]
	v_mfma_f32_16x16x32_bf16 v[20:23], v[170:173], v[202:205], v[20:23]
	v_mfma_f32_16x16x32_bf16 v[12:15], v[178:181], v[202:205], v[12:15]
	v_mfma_f32_16x16x32_bf16 v[4:7], v[170:173], v[210:213], v[4:7]
	v_mfma_f32_16x16x32_bf16 v[0:3], v[178:181], v[210:213], v[0:3]
	v_mfma_f32_16x16x32_bf16 v[52:55], v[174:177], v[190:193], v[52:55]
	v_mfma_f32_16x16x32_bf16 v[44:47], v[182:185], v[190:193], v[44:47]
	v_mfma_f32_16x16x32_bf16 v[36:39], v[174:177], v[198:201], v[36:39]
	v_mfma_f32_16x16x32_bf16 v[28:31], v[182:185], v[198:201], v[28:31]
	v_mfma_f32_16x16x32_bf16 v[20:23], v[174:177], v[206:209], v[20:23]
	v_mfma_f32_16x16x32_bf16 v[12:15], v[182:185], v[206:209], v[12:15]
	v_mfma_f32_16x16x32_bf16 v[4:7], v[174:177], v[214:217], v[4:7]
	v_mfma_f32_16x16x32_bf16 v[0:3], v[182:185], v[214:217], v[0:3]
	s_setprio 0
	s_barrier
	s_add_i32 s51, 0, 0x18000
	v_add_u32_e32 v144, s51, v148
	s_add_i32 s52, 0, 0x1c000
	ds_read_b128 v[154:157], v144
	ds_read_b128 v[158:161], v144 offset:1024
	ds_read_b128 v[162:165], v144 offset:2048
	ds_read_b128 v[166:169], v144 offset:3072
	v_add_u32_e32 v144, s52, v148
	ds_read_b128 v[170:173], v144
	ds_read_b128 v[174:177], v144 offset:1024
	ds_read_b128 v[178:181], v144 offset:2048
	ds_read_b128 v[182:185], v144 offset:3072
	s_add_u32 s24, s24, 0x80000
	s_addc_u32 s25, s25, 0
	s_mov_b32 m0, s33
	v_lshl_add_u64 v[228:229], s[24:25], 0, v[134:135]
	ds_read_b128 v[186:189], v152 offset:32768
	ds_read_b128 v[190:193], v152 offset:33792
	ds_read_b128 v[194:197], v152 offset:34816
	ds_read_b128 v[198:201], v152 offset:35840
	ds_read_b128 v[202:205], v152 offset:36864
	ds_read_b128 v[206:209], v152 offset:37888
	ds_read_b128 v[210:213], v152 offset:38912
	ds_read_b128 v[214:217], v152 offset:39936
	global_load_lds_dwordx4 v[228:229], off
	v_lshl_add_u64 v[228:229], s[24:25], 0, v[130:131]
	s_mov_b32 m0, s34
	s_nop 0
	global_load_lds_dwordx4 v[228:229], off
	s_waitcnt vmcnt(8)
	s_waitcnt lgkmcnt(0)
	s_barrier
	s_setprio 1
	s_waitcnt lgkmcnt(0)
	v_mfma_f32_16x16x32_bf16 v[124:127], v[154:157], v[186:189], v[124:127]
	v_mfma_f32_16x16x32_bf16 v[120:123], v[162:165], v[186:189], v[120:123]
	v_mfma_f32_16x16x32_bf16 v[112:115], v[154:157], v[194:197], v[112:115]
	v_mfma_f32_16x16x32_bf16 v[104:107], v[162:165], v[194:197], v[104:107]
	v_mfma_f32_16x16x32_bf16 v[96:99], v[154:157], v[202:205], v[96:99]
	v_mfma_f32_16x16x32_bf16 v[88:91], v[162:165], v[202:205], v[88:91]
	v_mfma_f32_16x16x32_bf16 v[80:83], v[154:157], v[210:213], v[80:83]
	v_mfma_f32_16x16x32_bf16 v[72:75], v[162:165], v[210:213], v[72:75]
	v_mfma_f32_16x16x32_bf16 v[124:127], v[158:161], v[190:193], v[124:127]
	v_mfma_f32_16x16x32_bf16 v[120:123], v[166:169], v[190:193], v[120:123]
	v_mfma_f32_16x16x32_bf16 v[112:115], v[158:161], v[198:201], v[112:115]
	v_mfma_f32_16x16x32_bf16 v[104:107], v[166:169], v[198:201], v[104:107]
	v_mfma_f32_16x16x32_bf16 v[96:99], v[158:161], v[206:209], v[96:99]
	v_mfma_f32_16x16x32_bf16 v[88:91], v[166:169], v[206:209], v[88:91]
	v_mfma_f32_16x16x32_bf16 v[80:83], v[158:161], v[214:217], v[80:83]
	v_mfma_f32_16x16x32_bf16 v[72:75], v[166:169], v[214:217], v[72:75]
	s_setprio 0
	s_setprio 1
	v_mfma_f32_16x16x32_bf16 v[116:119], v[170:173], v[186:189], v[116:119]
	v_mfma_f32_16x16x32_bf16 v[108:111], v[178:181], v[186:189], v[108:111]
	v_mfma_f32_16x16x32_bf16 v[100:103], v[170:173], v[194:197], v[100:103]
	v_mfma_f32_16x16x32_bf16 v[92:95], v[178:181], v[194:197], v[92:95]
	v_mfma_f32_16x16x32_bf16 v[84:87], v[170:173], v[202:205], v[84:87]
	v_mfma_f32_16x16x32_bf16 v[76:79], v[178:181], v[202:205], v[76:79]
	v_mfma_f32_16x16x32_bf16 v[68:71], v[170:173], v[210:213], v[68:71]
	v_mfma_f32_16x16x32_bf16 v[64:67], v[178:181], v[210:213], v[64:67]
	v_mfma_f32_16x16x32_bf16 v[116:119], v[174:177], v[190:193], v[116:119]
	v_mfma_f32_16x16x32_bf16 v[108:111], v[182:185], v[190:193], v[108:111]
	v_mfma_f32_16x16x32_bf16 v[100:103], v[174:177], v[198:201], v[100:103]
	v_mfma_f32_16x16x32_bf16 v[92:95], v[182:185], v[198:201], v[92:95]
	v_mfma_f32_16x16x32_bf16 v[84:87], v[174:177], v[206:209], v[84:87]
	v_mfma_f32_16x16x32_bf16 v[76:79], v[182:185], v[206:209], v[76:79]
	v_mfma_f32_16x16x32_bf16 v[68:71], v[174:177], v[214:217], v[68:71]
	v_mfma_f32_16x16x32_bf16 v[64:67], v[182:185], v[214:217], v[64:67]
	s_setprio 0
	s_barrier
; #define PG8_STAGE(bufoff, gbase, voff) do { _Pragma("unroll") for (int _i = 0; _i < 2; ++_i) \
;         __builtin_amdgcn_global_load_lds((const unsigned*)((const char*)(gbase) + (voff)[_i]), (PG8_LAS unsigned*)(lds + (bufoff) + ldsw + _i * 8192), 16, 0, 0); } while (0)
; #define PG8_LDA(dst, b, h) do { _Pragma("unroll") for (int m = 0; m < 4; ++m) _Pragma("unroll") for (int k = 0; k < 2; ++k) dst[m][k] = *(const PG8_LAS bf16x8*)(lds + PG8_SA(b, h) + aoff + m * 2048 + k * 1024); } while (0)
; #define PG8_MMA(ai, bj, At, Bt) do { __builtin_amdgcn_s_setprio(1); _Pragma("unroll") for (int m = 0; m < 4; ++m) _Pragma("unroll") for (int n = 0; n < 2; ++n) _Pragma("unroll") for (int k = 0; k < 2; ++k) \
;         acc[ai][bj][m][n] = __builtin_amdgcn_mfma_f32_16x16x32_bf16(Bt[n][k], At[m][k], acc[ai][bj][m][n], 0, 0, 0); __builtin_amdgcn_s_setprio(0); } while (0)
; #define PG8_WAIT_V(n) asm volatile("s_waitcnt vmcnt(" #n ")" ::: "memory")
; #define PG8_WAIT_L(n) asm volatile("s_waitcnt lgkmcnt(" #n ")" ::: "memory")
; #define PG8_BAR __builtin_amdgcn_s_barrier()
; #define PG8_SCHED __builtin_amdgcn_sched_barrier(0)
; template <class Epi, class Sched, bool ALIGN_EPI = false, bool SP2 = false>
; __device__ __forceinline__ void gemm_phase(PG8_LAS unsigned char* lds, const Gemm g, const Sched& S, const Epi& E) {
;     ...
;         for (int t = 0; t < nt; t += 2) {
;             const bool last = (t == nt - 2);
;             const char* a1 = cA + (size_t)(t + 1) * kstep;
;             const char* a2 = last ? nA : cA + (size_t)(t + 2) * kstep; const char* b2 = last ? nB : cB + (size_t)(t + 2) * kstep;
;     ...
;             PG8_LDA(At, 1, 1); PG8_STAGE(PG8_SB(1, 0), b3, voffB); PG8_STAGE(PG8_SB(1, 1), b3 + hstep, voffB); PG8_STAGE(PG8_SA(1, 0), a3, voffA);
;             PG8_WAIT_V(8); PG8_WAIT_L(0); PG8_BAR; PG8_MMA(1, 0, At, B0); PG8_MMA(1, 1, At, B1); PG8_BAR; PG8_SCHED;
	s_add_i32 s24, s51, s28
	v_lshl_add_u64 v[146:147], v[146:147], 0, s[4:5]
	s_mov_b32 m0, s24
	ds_read_b128 v[186:189], v152 offset:49152
	ds_read_b128 v[190:193], v152 offset:50176
	ds_read_b128 v[194:197], v152 offset:51200
	ds_read_b128 v[198:201], v152 offset:52224
	ds_read_b128 v[202:205], v152 offset:53248
	ds_read_b128 v[206:209], v152 offset:54272
	ds_read_b128 v[210:213], v152 offset:55296
	ds_read_b128 v[214:217], v152 offset:56320
	global_load_lds_dwordx4 v[146:147], off
	s_add_i32 m0, s24, 0x2000
	s_add_u32 s10, s10, 0x80080
	v_lshl_add_u64 v[146:147], v[222:223], 0, s[4:5]
	s_addc_u32 s11, s11, 0
	s_add_i32 s24, s52, s28
	global_load_lds_dwordx4 v[146:147], off
	v_lshl_add_u64 v[146:147], s[10:11], 0, v[132:133]
	s_mov_b32 m0, s24
	s_nop 0
	global_load_lds_dwordx4 v[146:147], off
	v_lshl_add_u64 v[146:147], s[10:11], 0, v[128:129]
	s_add_i32 m0, s24, 0x2000
	s_nop 0
	global_load_lds_dwordx4 v[146:147], off
	v_lshl_add_u64 v[146:147], v[224:225], 0, s[4:5]
	s_mov_b32 m0, s40
	s_nop 0
	global_load_lds_dwordx4 v[146:147], off
	v_lshl_add_u64 v[146:147], v[226:227], 0, s[4:5]
	s_mov_b32 m0, s41
	s_nop 0
	global_load_lds_dwordx4 v[146:147], off
	s_waitcnt vmcnt(8)
	s_waitcnt lgkmcnt(0)
	s_barrier
	s_setprio 1
	s_waitcnt lgkmcnt(0)
	v_mfma_f32_16x16x32_bf16 v[60:63], v[154:157], v[186:189], v[60:63]
	v_mfma_f32_16x16x32_bf16 v[56:59], v[162:165], v[186:189], v[56:59]
	v_mfma_f32_16x16x32_bf16 v[48:51], v[154:157], v[194:197], v[48:51]
	v_mfma_f32_16x16x32_bf16 v[40:43], v[162:165], v[194:197], v[40:43]
	v_mfma_f32_16x16x32_bf16 v[32:35], v[154:157], v[202:205], v[32:35]
	v_mfma_f32_16x16x32_bf16 v[24:27], v[162:165], v[202:205], v[24:27]
	v_mfma_f32_16x16x32_bf16 v[16:19], v[154:157], v[210:213], v[16:19]
	v_mfma_f32_16x16x32_bf16 v[8:11], v[162:165], v[210:213], v[8:11]
	v_mfma_f32_16x16x32_bf16 v[60:63], v[158:161], v[190:193], v[60:63]
	v_mfma_f32_16x16x32_bf16 v[56:59], v[166:169], v[190:193], v[56:59]
	v_mfma_f32_16x16x32_bf16 v[48:51], v[158:161], v[198:201], v[48:51]
	v_mfma_f32_16x16x32_bf16 v[40:43], v[166:169], v[198:201], v[40:43]
	v_mfma_f32_16x16x32_bf16 v[32:35], v[158:161], v[206:209], v[32:35]
	v_mfma_f32_16x16x32_bf16 v[24:27], v[166:169], v[206:209], v[24:27]
	v_mfma_f32_16x16x32_bf16 v[16:19], v[158:161], v[214:217], v[16:19]
	v_mfma_f32_16x16x32_bf16 v[8:11], v[166:169], v[214:217], v[8:11]
	s_setprio 0
	s_setprio 1
	v_mfma_f32_16x16x32_bf16 v[52:55], v[170:173], v[186:189], v[52:55]
	v_mfma_f32_16x16x32_bf16 v[44:47], v[178:181], v[186:189], v[44:47]
	v_mfma_f32_16x16x32_bf16 v[36:39], v[170:173], v[194:197], v[36:39]
	v_mfma_f32_16x16x32_bf16 v[28:31], v[178:181], v[194:197], v[28:31]
	v_mfma_f32_16x16x32_bf16 v[20:23], v[170:173], v[202:205], v[20:23]
	v_mfma_f32_16x16x32_bf16 v[12:15], v[178:181], v[202:205], v[12:15]
	v_mfma_f32_16x16x32_bf16 v[4:7], v[170:173], v[210:213], v[4:7]
	v_mfma_f32_16x16x32_bf16 v[0:3], v[178:181], v[210:213], v[0:3]
	v_mfma_f32_16x16x32_bf16 v[52:55], v[174:177], v[190:193], v[52:55]
	v_mfma_f32_16x16x32_bf16 v[44:47], v[182:185], v[190:193], v[44:47]
	v_mfma_f32_16x16x32_bf16 v[36:39], v[174:177], v[198:201], v[36:39]
	v_mfma_f32_16x16x32_bf16 v[28:31], v[182:185], v[198:201], v[28:31]
	v_mfma_f32_16x16x32_bf16 v[20:23], v[174:177], v[206:209], v[20:23]
	v_mfma_f32_16x16x32_bf16 v[12:15], v[182:185], v[206:209], v[12:15]
	v_mfma_f32_16x16x32_bf16 v[4:7], v[174:177], v[214:217], v[4:7]
	v_mfma_f32_16x16x32_bf16 v[0:3], v[182:185], v[214:217], v[0:3]
	s_add_i32 s50, s50, 2
	s_add_u32 s8, s8, 0x100
	s_addc_u32 s9, s9, 0
	s_add_u32 s48, s48, 0x100
	s_addc_u32 s49, s49, 0
	s_cmp_gt_u32 s50, 29
	s_setprio 0
	s_barrier
	s_cbranch_scc0 .LBB0_1582
	s_and_b64 vcc, exec, s[12:13]
	s_cbranch_vccz .LBB0_1585
	s_barrier

; #define PG8_STAGE(bufoff, gbase, voff) do { _Pragma("unroll") for (int _i = 0; _i < 2; ++_i) \
;         __builtin_amdgcn_global_load_lds((const unsigned*)((const char*)(gbase) + (voff)[_i]), (PG8_LAS unsigned*)(lds + (bufoff) + ldsw + _i * 8192), 16, 0, 0); } while (0)
; #define PG8_LDA(dst, b, h) do { _Pragma("unroll") for (int m = 0; m < 4; ++m) _Pragma("unroll") for (int k = 0; k < 2; ++k) dst[m][k] = *(const PG8_LAS bf16x8*)(lds + PG8_SA(b, h) + aoff + m * 2048 + k * 1024); } while (0)
; #define PG8_LDB(dst, b, h) do { _Pragma("unroll") for (int n = 0; n < 2; ++n) _Pragma("unroll") for (int k = 0; k < 2; ++k) dst[n][k] = *(const PG8_LAS bf16x8*)(lds + PG8_SB(b, h) + boff + n * 2048 + k * 1024); } while (0)
; #define PG8_MMA(ai, bj, At, Bt) do { __builtin_amdgcn_s_setprio(1); _Pragma("unroll") for (int m = 0; m < 4; ++m) _Pragma("unroll") for (int n = 0; n < 2; ++n) _Pragma("unroll") for (int k = 0; k < 2; ++k) \
;         acc[ai][bj][m][n] = __builtin_amdgcn_mfma_f32_16x16x32_bf16(Bt[n][k], At[m][k], acc[ai][bj][m][n], 0, 0, 0); __builtin_amdgcn_s_setprio(0); } while (0)
; #define PG8_WAIT_V(n) asm volatile("s_waitcnt vmcnt(" #n ")" ::: "memory")
; #define PG8_WAIT_L(n) asm volatile("s_waitcnt lgkmcnt(" #n ")" ::: "memory")
; template <class Epi, class Sched, bool ALIGN_EPI = false, bool SP2 = false>
; __device__ __forceinline__ void gemm_phase(PG8_LAS unsigned char* lds, const Gemm g, const Sched& S, const Epi& E) {
;     ...
;             const bool last = (t == nt - 2);
;             const char* a1 = cA + (size_t)(t + 1) * kstep;
;             const char* a2 = last ? nA : cA + (size_t)(t + 2) * kstep; const char* b2 = last ? nB : cB + (size_t)(t + 2) * kstep;
;             const char* a3 = a2 + kstep; const char* b3 = b2 + kstep;
;             if (last && has_next) S.a_ready(nxt);
;             if constexpr (SP2) {
;             PG8_LDB(B0, 0, 0); PG8_LDB(B1, 0, 1); PG8_SCHED; PG8_LDA(At, 0, 0); PG8_STAGE(PG8_SA(1, 1), a1 + hstep, voffA);
;             PG8_WAIT_V(8); PG8_WAIT_L(0); PG8_BAR; PG8_MMA(0, 0, At, B0); PG8_MMA(0, 1, At, B1); PG8_BAR; PG8_SCHED;
;             PG8_LDA(At, 0, 1); PG8_STAGE(PG8_SB(0, 0), b2, voffB); PG8_STAGE(PG8_SB(0, 1), b2 + hstep, voffB); PG8_STAGE(PG8_SA(0, 0), a2, voffA);
;             PG8_WAIT_V(8); PG8_WAIT_L(0); PG8_BAR; PG8_MMA(1, 0, At, B0); PG8_MMA(1, 1, At, B1); PG8_BAR; PG8_SCHED;
.LBB0_2053:
	ds_read_b128 v[112:115], v165
	ds_read_b128 v[120:123], v165 offset:1024
	ds_read_b128 v[152:155], v165 offset:2048
	ds_read_b128 v[156:159], v165 offset:3072
	ds_read_b128 v[168:171], v166
	ds_read_b128 v[172:175], v166 offset:1024
	ds_read_b128 v[176:179], v166 offset:2048
	ds_read_b128 v[180:183], v166 offset:3072
	s_add_u32 s10, s8, 0xfff80080
	s_addc_u32 s11, s9, -1
	s_cmp_eq_u32 s57, 28
	s_cselect_b32 s21, s37, s11
	s_cselect_b32 s20, s40, s10
	s_cselect_b32 s11, s41, s56
	s_cselect_b32 s10, s49, s51
	v_lshl_add_u64 v[160:161], s[8:9], 0, v[144:145]
	s_add_i32 m0, s17, 0xc000
	ds_read_b128 v[184:187], v167
	ds_read_b128 v[188:191], v167 offset:1024
	ds_read_b128 v[192:195], v167 offset:2048
	ds_read_b128 v[196:199], v167 offset:3072
	ds_read_b128 v[200:203], v167 offset:4096
	ds_read_b128 v[204:207], v167 offset:5120
	ds_read_b128 v[208:211], v167 offset:6144
	ds_read_b128 v[212:215], v167 offset:7168
	global_load_lds_dwordx4 v[160:161], off
	v_lshl_add_u64 v[160:161], s[8:9], 0, v[146:147]
	s_add_i32 m0, s17, 0xe000
	s_nop 0
	global_load_lds_dwordx4 v[160:161], off
	s_waitcnt vmcnt(8)
	s_waitcnt lgkmcnt(0)
	s_barrier
	s_setprio 1
	s_waitcnt lgkmcnt(0)
	v_mfma_f32_16x16x32_bf16 v[132:135], v[112:115], v[184:187], v[132:135]
	v_mfma_f32_16x16x32_bf16 v[128:131], v[152:155], v[184:187], v[128:131]
	v_mfma_f32_16x16x32_bf16 v[124:127], v[112:115], v[192:195], v[124:127]
	v_mfma_f32_16x16x32_bf16 v[116:119], v[152:155], v[192:195], v[116:119]
	v_mfma_f32_16x16x32_bf16 v[108:111], v[112:115], v[200:203], v[108:111]
	v_mfma_f32_16x16x32_bf16 v[104:107], v[152:155], v[200:203], v[104:107]
	v_mfma_f32_16x16x32_bf16 v[100:103], v[112:115], v[208:211], v[100:103]
	v_mfma_f32_16x16x32_bf16 v[96:99], v[152:155], v[208:211], v[96:99]
	v_mfma_f32_16x16x32_bf16 v[132:135], v[120:123], v[188:191], v[132:135]
	v_mfma_f32_16x16x32_bf16 v[128:131], v[156:159], v[188:191], v[128:131]
	v_mfma_f32_16x16x32_bf16 v[124:127], v[120:123], v[196:199], v[124:127]
	v_mfma_f32_16x16x32_bf16 v[116:119], v[156:159], v[196:199], v[116:119]
	v_mfma_f32_16x16x32_bf16 v[108:111], v[120:123], v[204:207], v[108:111]
	v_mfma_f32_16x16x32_bf16 v[104:107], v[156:159], v[204:207], v[104:107]
	v_mfma_f32_16x16x32_bf16 v[100:103], v[120:123], v[212:215], v[100:103]
	v_mfma_f32_16x16x32_bf16 v[96:99], v[156:159], v[212:215], v[96:99]
	s_setprio 0
	s_setprio 1
	v_mfma_f32_16x16x32_bf16 v[60:63], v[168:171], v[184:187], v[60:63]
	v_mfma_f32_16x16x32_bf16 v[56:59], v[176:179], v[184:187], v[56:59]
	v_mfma_f32_16x16x32_bf16 v[52:55], v[168:171], v[192:195], v[52:55]
	v_mfma_f32_16x16x32_bf16 v[48:51], v[176:179], v[192:195], v[48:51]
	v_mfma_f32_16x16x32_bf16 v[44:47], v[168:171], v[200:203], v[44:47]
	v_mfma_f32_16x16x32_bf16 v[40:43], v[176:179], v[200:203], v[40:43]
	v_mfma_f32_16x16x32_bf16 v[36:39], v[168:171], v[208:211], v[36:39]
	v_mfma_f32_16x16x32_bf16 v[32:35], v[176:179], v[208:211], v[32:35]
	v_mfma_f32_16x16x32_bf16 v[60:63], v[172:175], v[188:191], v[60:63]
	v_mfma_f32_16x16x32_bf16 v[56:59], v[180:183], v[188:191], v[56:59]
	v_mfma_f32_16x16x32_bf16 v[52:55], v[172:175], v[196:199], v[52:55]
	v_mfma_f32_16x16x32_bf16 v[48:51], v[180:183], v[196:199], v[48:51]
	v_mfma_f32_16x16x32_bf16 v[44:47], v[172:175], v[204:207], v[44:47]
	v_mfma_f32_16x16x32_bf16 v[40:43], v[180:183], v[204:207], v[40:43]
	v_mfma_f32_16x16x32_bf16 v[36:39], v[172:175], v[212:215], v[36:39]
	v_mfma_f32_16x16x32_bf16 v[32:35], v[180:183], v[212:215], v[32:35]
	s_setprio 0
	s_barrier
	s_add_i32 s58, s35, s26
	v_lshl_add_u64 v[160:161], s[10:11], 0, v[138:139]
	s_mov_b32 m0, s58
	ds_read_b128 v[184:187], v167 offset:16384
	ds_read_b128 v[188:191], v167 offset:17408
	ds_read_b128 v[192:195], v167 offset:18432
	ds_read_b128 v[196:199], v167 offset:19456
	ds_read_b128 v[200:203], v167 offset:20480
	ds_read_b128 v[204:207], v167 offset:21504
	ds_read_b128 v[208:211], v167 offset:22528
	ds_read_b128 v[212:215], v167 offset:23552
	global_load_lds_dwordx4 v[160:161], off
	s_add_i32 m0, s58, 0x2000
	s_add_u32 s58, s10, 0x80000
	v_lshl_add_u64 v[216:217], s[10:11], 0, v[142:143]
	s_addc_u32 s59, s11, 0
	s_add_i32 s60, s36, s26
	global_load_lds_dwordx4 v[216:217], off
	v_lshl_add_u64 v[222:223], s[58:59], 0, v[138:139]
	s_mov_b32 m0, s60
	v_lshl_add_u64 v[224:225], s[20:21], 0, v[140:141]
	global_load_lds_dwordx4 v[222:223], off
	v_lshl_add_u64 v[222:223], s[58:59], 0, v[142:143]
	s_add_i32 m0, s60, 0x2000
	s_nop 0
	global_load_lds_dwordx4 v[222:223], off
	v_lshl_add_u64 v[222:223], s[20:21], 0, v[136:137]
	s_mov_b32 m0, s17
	s_nop 0
	global_load_lds_dwordx4 v[222:223], off
	s_mov_b32 m0, s19
	s_nop 0
	global_load_lds_dwordx4 v[224:225], off
	s_waitcnt vmcnt(8)
	s_waitcnt lgkmcnt(0)
	s_barrier
; #define PG8_STAGE(bufoff, gbase, voff) do { _Pragma("unroll") for (int _i = 0; _i < 2; ++_i) \
;         __builtin_amdgcn_global_load_lds((const unsigned*)((const char*)(gbase) + (voff)[_i]), (PG8_LAS unsigned*)(lds + (bufoff) + ldsw + _i * 8192), 16, 0, 0); } while (0)
; #define PG8_LDA(dst, b, h) do { _Pragma("unroll") for (int m = 0; m < 4; ++m) _Pragma("unroll") for (int k = 0; k < 2; ++k) dst[m][k] = *(const PG8_LAS bf16x8*)(lds + PG8_SA(b, h) + aoff + m * 2048 + k * 1024); } while (0)
; #define PG8_LDB(dst, b, h) do { _Pragma("unroll") for (int n = 0; n < 2; ++n) _Pragma("unroll") for (int k = 0; k < 2; ++k) dst[n][k] = *(const PG8_LAS bf16x8*)(lds + PG8_SB(b, h) + boff + n * 2048 + k * 1024); } while (0)
; #define PG8_MMA(ai, bj, At, Bt) do { __builtin_amdgcn_s_setprio(1); _Pragma("unroll") for (int m = 0; m < 4; ++m) _Pragma("unroll") for (int n = 0; n < 2; ++n) _Pragma("unroll") for (int k = 0; k < 2; ++k) \
;         acc[ai][bj][m][n] = __builtin_amdgcn_mfma_f32_16x16x32_bf16(Bt[n][k], At[m][k], acc[ai][bj][m][n], 0, 0, 0); __builtin_amdgcn_s_setprio(0); } while (0)
; #define PG8_WAIT_V(n) asm volatile("s_waitcnt vmcnt(" #n ")" ::: "memory")
; #define PG8_WAIT_L(n) asm volatile("s_waitcnt lgkmcnt(" #n ")" ::: "memory")
; #define PG8_BAR __builtin_amdgcn_s_barrier()
; #define PG8_SCHED __builtin_amdgcn_sched_barrier(0)
; template <class Epi, class Sched, bool ALIGN_EPI = false, bool SP2 = false>
; __device__ __forceinline__ void gemm_phase(PG8_LAS unsigned char* lds, const Gemm g, const Sched& S, const Epi& E) {
;     ...
;             PG8_WAIT_V(8); PG8_WAIT_L(0); PG8_BAR; PG8_MMA(1, 0, At, B0); PG8_MMA(1, 1, At, B1); PG8_BAR; PG8_SCHED;
;             PG8_LDB(B0, 1, 0); PG8_LDB(B1, 1, 1); PG8_SCHED; PG8_LDA(At, 1, 0); PG8_STAGE(PG8_SA(0, 1), a2 + hstep, voffA);
;             PG8_WAIT_V(8); PG8_WAIT_L(0); PG8_BAR; PG8_MMA(0, 0, At, B0); PG8_MMA(0, 1, At, B1); PG8_BAR; PG8_SCHED;
	s_setprio 1
	s_waitcnt lgkmcnt(0)
	v_mfma_f32_16x16x32_bf16 v[92:95], v[112:115], v[184:187], v[92:95]
	v_mfma_f32_16x16x32_bf16 v[88:91], v[152:155], v[184:187], v[88:91]
	v_mfma_f32_16x16x32_bf16 v[84:87], v[112:115], v[192:195], v[84:87]
	v_mfma_f32_16x16x32_bf16 v[80:83], v[152:155], v[192:195], v[80:83]
	v_mfma_f32_16x16x32_bf16 v[76:79], v[112:115], v[200:203], v[76:79]
	v_mfma_f32_16x16x32_bf16 v[72:75], v[152:155], v[200:203], v[72:75]
	v_mfma_f32_16x16x32_bf16 v[68:71], v[112:115], v[208:211], v[68:71]
	v_mfma_f32_16x16x32_bf16 v[64:67], v[152:155], v[208:211], v[64:67]
	v_mfma_f32_16x16x32_bf16 v[92:95], v[120:123], v[188:191], v[92:95]
	v_mfma_f32_16x16x32_bf16 v[88:91], v[156:159], v[188:191], v[88:91]
	v_mfma_f32_16x16x32_bf16 v[84:87], v[120:123], v[196:199], v[84:87]
	v_mfma_f32_16x16x32_bf16 v[80:83], v[156:159], v[196:199], v[80:83]
	v_mfma_f32_16x16x32_bf16 v[76:79], v[120:123], v[204:207], v[76:79]
	v_mfma_f32_16x16x32_bf16 v[72:75], v[156:159], v[204:207], v[72:75]
	v_mfma_f32_16x16x32_bf16 v[68:71], v[120:123], v[212:215], v[68:71]
	v_mfma_f32_16x16x32_bf16 v[64:67], v[156:159], v[212:215], v[64:67]
	s_setprio 0
	s_setprio 1
	v_mfma_f32_16x16x32_bf16 v[28:31], v[168:171], v[184:187], v[28:31]
	v_mfma_f32_16x16x32_bf16 v[24:27], v[176:179], v[184:187], v[24:27]
	v_mfma_f32_16x16x32_bf16 v[20:23], v[168:171], v[192:195], v[20:23]
	v_mfma_f32_16x16x32_bf16 v[16:19], v[176:179], v[192:195], v[16:19]
	v_mfma_f32_16x16x32_bf16 v[12:15], v[168:171], v[200:203], v[12:15]
	v_mfma_f32_16x16x32_bf16 v[8:11], v[176:179], v[200:203], v[8:11]
	v_mfma_f32_16x16x32_bf16 v[4:7], v[168:171], v[208:211], v[4:7]
	v_mfma_f32_16x16x32_bf16 v[0:3], v[176:179], v[208:211], v[0:3]
	v_mfma_f32_16x16x32_bf16 v[28:31], v[172:175], v[188:191], v[28:31]
	v_mfma_f32_16x16x32_bf16 v[24:27], v[180:183], v[188:191], v[24:27]
	v_mfma_f32_16x16x32_bf16 v[20:23], v[172:175], v[196:199], v[20:23]
	v_mfma_f32_16x16x32_bf16 v[16:19], v[180:183], v[196:199], v[16:19]
	v_mfma_f32_16x16x32_bf16 v[12:15], v[172:175], v[204:207], v[12:15]
	v_mfma_f32_16x16x32_bf16 v[8:11], v[180:183], v[204:207], v[8:11]
	v_mfma_f32_16x16x32_bf16 v[4:7], v[172:175], v[212:215], v[4:7]
	v_mfma_f32_16x16x32_bf16 v[0:3], v[180:183], v[212:215], v[0:3]
	s_setprio 0
	s_barrier
	s_add_i32 s58, 0, 0x18000
	s_add_i32 s59, 0, 0x1c000
	v_add_u32_e32 v156, s58, v163
	v_add_u32_e32 v180, s59, v163
	ds_read_b128 v[112:115], v156
	ds_read_b128 v[120:123], v156 offset:1024
	ds_read_b128 v[152:155], v156 offset:2048
	ds_read_b128 v[156:159], v156 offset:3072
	ds_read_b128 v[168:171], v180
	ds_read_b128 v[172:175], v180 offset:1024
	ds_read_b128 v[176:179], v180 offset:2048
	ds_read_b128 v[180:183], v180 offset:3072
	s_add_u32 s20, s20, 0x80000
	s_addc_u32 s21, s21, 0
	s_mov_b32 m0, s27
	v_lshl_add_u64 v[226:227], s[20:21], 0, v[136:137]
	ds_read_b128 v[184:187], v167 offset:32768
	ds_read_b128 v[188:191], v167 offset:33792
	ds_read_b128 v[192:195], v167 offset:34816
	ds_read_b128 v[196:199], v167 offset:35840
	ds_read_b128 v[200:203], v167 offset:36864
	ds_read_b128 v[204:207], v167 offset:37888
	ds_read_b128 v[208:211], v167 offset:38912
	ds_read_b128 v[212:215], v167 offset:39936
	global_load_lds_dwordx4 v[226:227], off
	v_lshl_add_u64 v[226:227], s[20:21], 0, v[140:141]
	s_mov_b32 m0, s28
	s_nop 0
	global_load_lds_dwordx4 v[226:227], off
	s_waitcnt vmcnt(8)
	s_waitcnt lgkmcnt(0)
	s_barrier
	s_setprio 1
	s_waitcnt lgkmcnt(0)
	v_mfma_f32_16x16x32_bf16 v[132:135], v[112:115], v[184:187], v[132:135]
	v_mfma_f32_16x16x32_bf16 v[128:131], v[152:155], v[184:187], v[128:131]
	v_mfma_f32_16x16x32_bf16 v[124:127], v[112:115], v[192:195], v[124:127]
	v_mfma_f32_16x16x32_bf16 v[116:119], v[152:155], v[192:195], v[116:119]
	v_mfma_f32_16x16x32_bf16 v[108:111], v[112:115], v[200:203], v[108:111]
	v_mfma_f32_16x16x32_bf16 v[104:107], v[152:155], v[200:203], v[104:107]
	v_mfma_f32_16x16x32_bf16 v[100:103], v[112:115], v[208:211], v[100:103]
	v_mfma_f32_16x16x32_bf16 v[96:99], v[152:155], v[208:211], v[96:99]
	v_mfma_f32_16x16x32_bf16 v[132:135], v[120:123], v[188:191], v[132:135]
	v_mfma_f32_16x16x32_bf16 v[128:131], v[156:159], v[188:191], v[128:131]
	v_mfma_f32_16x16x32_bf16 v[124:127], v[120:123], v[196:199], v[124:127]
	v_mfma_f32_16x16x32_bf16 v[116:119], v[156:159], v[196:199], v[116:119]
	v_mfma_f32_16x16x32_bf16 v[108:111], v[120:123], v[204:207], v[108:111]
	v_mfma_f32_16x16x32_bf16 v[104:107], v[156:159], v[204:207], v[104:107]
	v_mfma_f32_16x16x32_bf16 v[100:103], v[120:123], v[212:215], v[100:103]
	v_mfma_f32_16x16x32_bf16 v[96:99], v[156:159], v[212:215], v[96:99]
	s_setprio 0
	s_setprio 1
	v_mfma_f32_16x16x32_bf16 v[60:63], v[168:171], v[184:187], v[60:63]
	v_mfma_f32_16x16x32_bf16 v[56:59], v[176:179], v[184:187], v[56:59]
	v_mfma_f32_16x16x32_bf16 v[52:55], v[168:171], v[192:195], v[52:55]
	v_mfma_f32_16x16x32_bf16 v[48:51], v[176:179], v[192:195], v[48:51]
	v_mfma_f32_16x16x32_bf16 v[44:47], v[168:171], v[200:203], v[44:47]
	v_mfma_f32_16x16x32_bf16 v[40:43], v[176:179], v[200:203], v[40:43]
	v_mfma_f32_16x16x32_bf16 v[36:39], v[168:171], v[208:211], v[36:39]
	v_mfma_f32_16x16x32_bf16 v[32:35], v[176:179], v[208:211], v[32:35]
	v_mfma_f32_16x16x32_bf16 v[60:63], v[172:175], v[188:191], v[60:63]
	v_mfma_f32_16x16x32_bf16 v[56:59], v[180:183], v[188:191], v[56:59]
	v_mfma_f32_16x16x32_bf16 v[52:55], v[172:175], v[196:199], v[52:55]
	v_mfma_f32_16x16x32_bf16 v[48:51], v[180:183], v[196:199], v[48:51]
	v_mfma_f32_16x16x32_bf16 v[44:47], v[172:175], v[204:207], v[44:47]
	v_mfma_f32_16x16x32_bf16 v[40:43], v[180:183], v[204:207], v[40:43]
	v_mfma_f32_16x16x32_bf16 v[36:39], v[172:175], v[212:215], v[36:39]
	v_mfma_f32_16x16x32_bf16 v[32:35], v[180:183], v[212:215], v[32:35]
	s_setprio 0
	s_barrier
; #define PG8_STAGE(bufoff, gbase, voff) do { _Pragma("unroll") for (int _i = 0; _i < 2; ++_i) \
;         __builtin_amdgcn_global_load_lds((const unsigned*)((const char*)(gbase) + (voff)[_i]), (PG8_LAS unsigned*)(lds + (bufoff) + ldsw + _i * 8192), 16, 0, 0); } while (0)
; #define PG8_LDA(dst, b, h) do { _Pragma("unroll") for (int m = 0; m < 4; ++m) _Pragma("unroll") for (int k = 0; k < 2; ++k) dst[m][k] = *(const PG8_LAS bf16x8*)(lds + PG8_SA(b, h) + aoff + m * 2048 + k * 1024); } while (0)
; #define PG8_MMA(ai, bj, At, Bt) do { __builtin_amdgcn_s_setprio(1); _Pragma("unroll") for (int m = 0; m < 4; ++m) _Pragma("unroll") for (int n = 0; n < 2; ++n) _Pragma("unroll") for (int k = 0; k < 2; ++k) \
;         acc[ai][bj][m][n] = __builtin_amdgcn_mfma_f32_16x16x32_bf16(Bt[n][k], At[m][k], acc[ai][bj][m][n], 0, 0, 0); __builtin_amdgcn_s_setprio(0); } while (0)
; #define PG8_WAIT_V(n) asm volatile("s_waitcnt vmcnt(" #n ")" ::: "memory")
; #define PG8_WAIT_L(n) asm volatile("s_waitcnt lgkmcnt(" #n ")" ::: "memory")
; #define PG8_BAR __builtin_amdgcn_s_barrier()
; #define PG8_SCHED __builtin_amdgcn_sched_barrier(0)
; template <class Epi, class Sched, bool ALIGN_EPI = false, bool SP2 = false>
; __device__ __forceinline__ void gemm_phase(PG8_LAS unsigned char* lds, const Gemm g, const Sched& S, const Epi& E) {
;     ...
;         for (int t = 0; t < nt; t += 2) {
;             const bool last = (t == nt - 2);
;             const char* a1 = cA + (size_t)(t + 1) * kstep;
;             const char* a2 = last ? nA : cA + (size_t)(t + 2) * kstep; const char* b2 = last ? nB : cB + (size_t)(t + 2) * kstep;
;     ...
;             PG8_LDA(At, 1, 1); PG8_STAGE(PG8_SB(1, 0), b3, voffB); PG8_STAGE(PG8_SB(1, 1), b3 + hstep, voffB); PG8_STAGE(PG8_SA(1, 0), a3, voffA);
;             PG8_WAIT_V(8); PG8_WAIT_L(0); PG8_BAR; PG8_MMA(1, 0, At, B0); PG8_MMA(1, 1, At, B1); PG8_BAR; PG8_SCHED;
	s_add_i32 s20, s58, s26
	v_lshl_add_u64 v[160:161], v[160:161], 0, s[44:45]
	s_mov_b32 m0, s20
	ds_read_b128 v[184:187], v167 offset:49152
	ds_read_b128 v[188:191], v167 offset:50176
	ds_read_b128 v[192:195], v167 offset:51200
	ds_read_b128 v[196:199], v167 offset:52224
	ds_read_b128 v[200:203], v167 offset:53248
	ds_read_b128 v[204:207], v167 offset:54272
	ds_read_b128 v[208:211], v167 offset:55296
	ds_read_b128 v[212:215], v167 offset:56320
	global_load_lds_dwordx4 v[160:161], off
	s_add_i32 m0, s20, 0x2000
	s_add_u32 s10, s10, 0x80080
	v_lshl_add_u64 v[160:161], v[216:217], 0, s[44:45]
	s_addc_u32 s11, s11, 0
	s_add_i32 s20, s59, s26
	global_load_lds_dwordx4 v[160:161], off
	v_lshl_add_u64 v[160:161], s[10:11], 0, v[138:139]
	s_mov_b32 m0, s20
	s_nop 0
	global_load_lds_dwordx4 v[160:161], off
	v_lshl_add_u64 v[160:161], s[10:11], 0, v[142:143]
	s_add_i32 m0, s20, 0x2000
	s_nop 0
	global_load_lds_dwordx4 v[160:161], off
	v_lshl_add_u64 v[160:161], v[222:223], 0, s[44:45]
	s_mov_b32 m0, s30
	s_nop 0
	global_load_lds_dwordx4 v[160:161], off
	v_lshl_add_u64 v[160:161], v[224:225], 0, s[44:45]
	s_mov_b32 m0, s31
	s_nop 0
	global_load_lds_dwordx4 v[160:161], off
	s_waitcnt vmcnt(8)
	s_waitcnt lgkmcnt(0)
	s_barrier
	s_setprio 1
	s_waitcnt lgkmcnt(0)
	v_mfma_f32_16x16x32_bf16 v[92:95], v[112:115], v[184:187], v[92:95]
	v_mfma_f32_16x16x32_bf16 v[88:91], v[152:155], v[184:187], v[88:91]
	v_mfma_f32_16x16x32_bf16 v[84:87], v[112:115], v[192:195], v[84:87]
	v_mfma_f32_16x16x32_bf16 v[80:83], v[152:155], v[192:195], v[80:83]
	v_mfma_f32_16x16x32_bf16 v[76:79], v[112:115], v[200:203], v[76:79]
	v_mfma_f32_16x16x32_bf16 v[72:75], v[152:155], v[200:203], v[72:75]
	v_mfma_f32_16x16x32_bf16 v[68:71], v[112:115], v[208:211], v[68:71]
	v_mfma_f32_16x16x32_bf16 v[64:67], v[152:155], v[208:211], v[64:67]
	v_mfma_f32_16x16x32_bf16 v[92:95], v[120:123], v[188:191], v[92:95]
	v_mfma_f32_16x16x32_bf16 v[88:91], v[156:159], v[188:191], v[88:91]
	v_mfma_f32_16x16x32_bf16 v[84:87], v[120:123], v[196:199], v[84:87]
	v_mfma_f32_16x16x32_bf16 v[80:83], v[156:159], v[196:199], v[80:83]
	v_mfma_f32_16x16x32_bf16 v[76:79], v[120:123], v[204:207], v[76:79]
	v_mfma_f32_16x16x32_bf16 v[72:75], v[156:159], v[204:207], v[72:75]
	v_mfma_f32_16x16x32_bf16 v[68:71], v[120:123], v[212:215], v[68:71]
	v_mfma_f32_16x16x32_bf16 v[64:67], v[156:159], v[212:215], v[64:67]
	s_setprio 0
	s_setprio 1
	v_mfma_f32_16x16x32_bf16 v[28:31], v[168:171], v[184:187], v[28:31]
	v_mfma_f32_16x16x32_bf16 v[24:27], v[176:179], v[184:187], v[24:27]
	v_mfma_f32_16x16x32_bf16 v[20:23], v[168:171], v[192:195], v[20:23]
	v_mfma_f32_16x16x32_bf16 v[16:19], v[176:179], v[192:195], v[16:19]
	v_mfma_f32_16x16x32_bf16 v[12:15], v[168:171], v[200:203], v[12:15]
	v_mfma_f32_16x16x32_bf16 v[8:11], v[176:179], v[200:203], v[8:11]
	v_mfma_f32_16x16x32_bf16 v[4:7], v[168:171], v[208:211], v[4:7]
	v_mfma_f32_16x16x32_bf16 v[0:3], v[176:179], v[208:211], v[0:3]
	v_mfma_f32_16x16x32_bf16 v[28:31], v[172:175], v[188:191], v[28:31]
	v_mfma_f32_16x16x32_bf16 v[24:27], v[180:183], v[188:191], v[24:27]
	v_mfma_f32_16x16x32_bf16 v[20:23], v[172:175], v[196:199], v[20:23]
	v_mfma_f32_16x16x32_bf16 v[16:19], v[180:183], v[196:199], v[16:19]
	v_mfma_f32_16x16x32_bf16 v[12:15], v[172:175], v[204:207], v[12:15]
	v_mfma_f32_16x16x32_bf16 v[8:11], v[180:183], v[204:207], v[8:11]
	v_mfma_f32_16x16x32_bf16 v[4:7], v[172:175], v[212:215], v[4:7]
	v_mfma_f32_16x16x32_bf16 v[0:3], v[180:183], v[212:215], v[0:3]
	s_add_i32 s57, s57, 2
	s_add_u32 s8, s8, 0x100
	s_addc_u32 s9, s9, 0
	s_add_u32 s51, s51, 0x100
	s_addc_u32 s56, s56, 0
	s_cmp_gt_u32 s57, 29
	s_setprio 0
	s_barrier
	s_cbranch_scc0 .LBB0_2053
	s_and_b64 vcc, exec, s[46:47]
	s_cbranch_vccz .LBB0_2056
	s_barrier

; #define PG8_STAGE(bufoff, gbase, voff) do { _Pragma("unroll") for (int _i = 0; _i < 2; ++_i) \
;         __builtin_amdgcn_global_load_lds((const unsigned*)((const char*)(gbase) + (voff)[_i]), (PG8_LAS unsigned*)(lds + (bufoff) + ldsw + _i * 8192), 16, 0, 0); } while (0)
; #define PG8_LDA(dst, b, h) do { _Pragma("unroll") for (int m = 0; m < 4; ++m) _Pragma("unroll") for (int k = 0; k < 2; ++k) dst[m][k] = *(const PG8_LAS bf16x8*)(lds + PG8_SA(b, h) + aoff + m * 2048 + k * 1024); } while (0)
; #define PG8_LDB(dst, b, h) do { _Pragma("unroll") for (int n = 0; n < 2; ++n) _Pragma("unroll") for (int k = 0; k < 2; ++k) dst[n][k] = *(const PG8_LAS bf16x8*)(lds + PG8_SB(b, h) + boff + n * 2048 + k * 1024); } while (0)
; #define PG8_MMA(ai, bj, At, Bt) do { __builtin_amdgcn_s_setprio(1); _Pragma("unroll") for (int m = 0; m < 4; ++m) _Pragma("unroll") for (int n = 0; n < 2; ++n) _Pragma("unroll") for (int k = 0; k < 2; ++k) \
;         acc[ai][bj][m][n] = __builtin_amdgcn_mfma_f32_16x16x32_bf16(Bt[n][k], At[m][k], acc[ai][bj][m][n], 0, 0, 0); __builtin_amdgcn_s_setprio(0); } while (0)
; #define PG8_WAIT_V(n) asm volatile("s_waitcnt vmcnt(" #n ")" ::: "memory")
; #define PG8_WAIT_L(n) asm volatile("s_waitcnt lgkmcnt(" #n ")" ::: "memory")
; template <class Epi, class Sched, bool ALIGN_EPI = false, bool SP2 = false>
; __device__ __forceinline__ void gemm_phase(PG8_LAS unsigned char* lds, const Gemm g, const Sched& S, const Epi& E) {
;     ...
;             const bool last = (t == nt - 2);
;             const char* a1 = cA + (size_t)(t + 1) * kstep;
;             const char* a2 = last ? nA : cA + (size_t)(t + 2) * kstep; const char* b2 = last ? nB : cB + (size_t)(t + 2) * kstep;
;             const char* a3 = a2 + kstep; const char* b3 = b2 + kstep;
;             if (last && has_next) S.a_ready(nxt);
;             if constexpr (SP2) {
;             PG8_LDB(B0, 0, 0); PG8_LDB(B1, 0, 1); PG8_SCHED; PG8_LDA(At, 0, 0); PG8_STAGE(PG8_SA(1, 1), a1 + hstep, voffA);
;             PG8_WAIT_V(8); PG8_WAIT_L(0); PG8_BAR; PG8_MMA(0, 0, At, B0); PG8_MMA(0, 1, At, B1); PG8_BAR; PG8_SCHED;
;             PG8_LDA(At, 0, 1); PG8_STAGE(PG8_SB(0, 0), b2, voffB); PG8_STAGE(PG8_SB(0, 1), b2 + hstep, voffB); PG8_STAGE(PG8_SA(0, 0), a2, voffA);
;             PG8_WAIT_V(8); PG8_WAIT_L(0); PG8_BAR; PG8_MMA(1, 0, At, B0); PG8_MMA(1, 1, At, B1); PG8_BAR; PG8_SCHED;
.LBB0_2248:
	ds_read_b128 v[152:155], v149
	ds_read_b128 v[156:159], v149 offset:1024
	ds_read_b128 v[160:163], v149 offset:2048
	ds_read_b128 v[164:167], v149 offset:3072
	ds_read_b128 v[168:171], v150
	ds_read_b128 v[172:175], v150 offset:1024
	ds_read_b128 v[176:179], v150 offset:2048
	ds_read_b128 v[180:183], v150 offset:3072
	s_add_u32 s10, s8, 0xfff80080
	s_addc_u32 s11, s9, -1
	s_cmp_eq_u32 s49, 28
	s_cselect_b32 s27, s19, s11
	s_cselect_b32 s26, s45, s10
	s_cselect_b32 s11, s17, s48
	s_cselect_b32 s10, s46, s47
	v_lshl_add_u64 v[144:145], s[8:9], 0, v[136:137]
	s_add_i32 m0, s25, 0xc000
	ds_read_b128 v[184:187], v151
	ds_read_b128 v[188:191], v151 offset:1024
	ds_read_b128 v[192:195], v151 offset:2048
	ds_read_b128 v[196:199], v151 offset:3072
	ds_read_b128 v[200:203], v151 offset:4096
	ds_read_b128 v[204:207], v151 offset:5120
	ds_read_b128 v[208:211], v151 offset:6144
	ds_read_b128 v[212:215], v151 offset:7168
	global_load_lds_dwordx4 v[144:145], off
	v_lshl_add_u64 v[144:145], s[8:9], 0, v[138:139]
	s_add_i32 m0, s25, 0xe000
	s_nop 0
	global_load_lds_dwordx4 v[144:145], off
	s_waitcnt vmcnt(8)
	s_waitcnt lgkmcnt(0)
	s_barrier
	s_setprio 1
	s_waitcnt lgkmcnt(0)
	v_mfma_f32_16x16x32_bf16 v[124:127], v[152:155], v[184:187], v[124:127]
	v_mfma_f32_16x16x32_bf16 v[120:123], v[160:163], v[184:187], v[120:123]
	v_mfma_f32_16x16x32_bf16 v[108:111], v[152:155], v[192:195], v[108:111]
	v_mfma_f32_16x16x32_bf16 v[104:107], v[160:163], v[192:195], v[104:107]
	v_mfma_f32_16x16x32_bf16 v[92:95], v[152:155], v[200:203], v[92:95]
	v_mfma_f32_16x16x32_bf16 v[88:91], v[160:163], v[200:203], v[88:91]
	v_mfma_f32_16x16x32_bf16 v[76:79], v[152:155], v[208:211], v[76:79]
	v_mfma_f32_16x16x32_bf16 v[72:75], v[160:163], v[208:211], v[72:75]
	v_mfma_f32_16x16x32_bf16 v[124:127], v[156:159], v[188:191], v[124:127]
	v_mfma_f32_16x16x32_bf16 v[120:123], v[164:167], v[188:191], v[120:123]
	v_mfma_f32_16x16x32_bf16 v[108:111], v[156:159], v[196:199], v[108:111]
	v_mfma_f32_16x16x32_bf16 v[104:107], v[164:167], v[196:199], v[104:107]
	v_mfma_f32_16x16x32_bf16 v[92:95], v[156:159], v[204:207], v[92:95]
	v_mfma_f32_16x16x32_bf16 v[88:91], v[164:167], v[204:207], v[88:91]
	v_mfma_f32_16x16x32_bf16 v[76:79], v[156:159], v[212:215], v[76:79]
	v_mfma_f32_16x16x32_bf16 v[72:75], v[164:167], v[212:215], v[72:75]
	s_setprio 0
	s_setprio 1
	v_mfma_f32_16x16x32_bf16 v[116:119], v[168:171], v[184:187], v[116:119]
	v_mfma_f32_16x16x32_bf16 v[112:115], v[176:179], v[184:187], v[112:115]
	v_mfma_f32_16x16x32_bf16 v[100:103], v[168:171], v[192:195], v[100:103]
	v_mfma_f32_16x16x32_bf16 v[96:99], v[176:179], v[192:195], v[96:99]
	v_mfma_f32_16x16x32_bf16 v[84:87], v[168:171], v[200:203], v[84:87]
	v_mfma_f32_16x16x32_bf16 v[80:83], v[176:179], v[200:203], v[80:83]
	v_mfma_f32_16x16x32_bf16 v[68:71], v[168:171], v[208:211], v[68:71]
	v_mfma_f32_16x16x32_bf16 v[64:67], v[176:179], v[208:211], v[64:67]
	v_mfma_f32_16x16x32_bf16 v[116:119], v[172:175], v[188:191], v[116:119]
	v_mfma_f32_16x16x32_bf16 v[112:115], v[180:183], v[188:191], v[112:115]
	v_mfma_f32_16x16x32_bf16 v[100:103], v[172:175], v[196:199], v[100:103]
	v_mfma_f32_16x16x32_bf16 v[96:99], v[180:183], v[196:199], v[96:99]
	v_mfma_f32_16x16x32_bf16 v[84:87], v[172:175], v[204:207], v[84:87]
	v_mfma_f32_16x16x32_bf16 v[80:83], v[180:183], v[204:207], v[80:83]
	v_mfma_f32_16x16x32_bf16 v[68:71], v[172:175], v[212:215], v[68:71]
	v_mfma_f32_16x16x32_bf16 v[64:67], v[180:183], v[212:215], v[64:67]
	s_setprio 0
	s_barrier
	s_add_i32 s50, s42, s31
	v_lshl_add_u64 v[144:145], s[10:11], 0, v[130:131]
	s_mov_b32 m0, s50
	ds_read_b128 v[184:187], v151 offset:16384
	ds_read_b128 v[188:191], v151 offset:17408
	ds_read_b128 v[192:195], v151 offset:18432
	ds_read_b128 v[196:199], v151 offset:19456
	ds_read_b128 v[200:203], v151 offset:20480
	ds_read_b128 v[204:207], v151 offset:21504
	ds_read_b128 v[208:211], v151 offset:22528
	ds_read_b128 v[212:215], v151 offset:23552
	global_load_lds_dwordx4 v[144:145], off
	s_add_i32 m0, s50, 0x2000
	s_add_u32 s50, s10, 0x80000
	v_lshl_add_u64 v[216:217], s[10:11], 0, v[134:135]
	s_addc_u32 s51, s11, 0
	s_add_i32 s52, s43, s31
	global_load_lds_dwordx4 v[216:217], off
	v_lshl_add_u64 v[222:223], s[50:51], 0, v[130:131]
	s_mov_b32 m0, s52
	v_lshl_add_u64 v[224:225], s[26:27], 0, v[132:133]
	global_load_lds_dwordx4 v[222:223], off
	v_lshl_add_u64 v[222:223], s[50:51], 0, v[134:135]
	s_add_i32 m0, s52, 0x2000
	s_nop 0
	global_load_lds_dwordx4 v[222:223], off
	v_lshl_add_u64 v[222:223], s[26:27], 0, v[128:129]
	s_mov_b32 m0, s25
	s_nop 0
	global_load_lds_dwordx4 v[222:223], off
	s_mov_b32 m0, s33
	s_nop 0
	global_load_lds_dwordx4 v[224:225], off
	s_waitcnt vmcnt(8)
	s_waitcnt lgkmcnt(0)
	s_barrier
; #define PG8_STAGE(bufoff, gbase, voff) do { _Pragma("unroll") for (int _i = 0; _i < 2; ++_i) \
;         __builtin_amdgcn_global_load_lds((const unsigned*)((const char*)(gbase) + (voff)[_i]), (PG8_LAS unsigned*)(lds + (bufoff) + ldsw + _i * 8192), 16, 0, 0); } while (0)
; #define PG8_LDA(dst, b, h) do { _Pragma("unroll") for (int m = 0; m < 4; ++m) _Pragma("unroll") for (int k = 0; k < 2; ++k) dst[m][k] = *(const PG8_LAS bf16x8*)(lds + PG8_SA(b, h) + aoff + m * 2048 + k * 1024); } while (0)
; #define PG8_LDB(dst, b, h) do { _Pragma("unroll") for (int n = 0; n < 2; ++n) _Pragma("unroll") for (int k = 0; k < 2; ++k) dst[n][k] = *(const PG8_LAS bf16x8*)(lds + PG8_SB(b, h) + boff + n * 2048 + k * 1024); } while (0)
; #define PG8_MMA(ai, bj, At, Bt) do { __builtin_amdgcn_s_setprio(1); _Pragma("unroll") for (int m = 0; m < 4; ++m) _Pragma("unroll") for (int n = 0; n < 2; ++n) _Pragma("unroll") for (int k = 0; k < 2; ++k) \
;         acc[ai][bj][m][n] = __builtin_amdgcn_mfma_f32_16x16x32_bf16(Bt[n][k], At[m][k], acc[ai][bj][m][n], 0, 0, 0); __builtin_amdgcn_s_setprio(0); } while (0)
; #define PG8_WAIT_V(n) asm volatile("s_waitcnt vmcnt(" #n ")" ::: "memory")
; #define PG8_WAIT_L(n) asm volatile("s_waitcnt lgkmcnt(" #n ")" ::: "memory")
; #define PG8_BAR __builtin_amdgcn_s_barrier()
; #define PG8_SCHED __builtin_amdgcn_sched_barrier(0)
; template <class Epi, class Sched, bool ALIGN_EPI = false, bool SP2 = false>
; __device__ __forceinline__ void gemm_phase(PG8_LAS unsigned char* lds, const Gemm g, const Sched& S, const Epi& E) {
;     ...
;             PG8_WAIT_V(8); PG8_WAIT_L(0); PG8_BAR; PG8_MMA(1, 0, At, B0); PG8_MMA(1, 1, At, B1); PG8_BAR; PG8_SCHED;
;             PG8_LDB(B0, 1, 0); PG8_LDB(B1, 1, 1); PG8_SCHED; PG8_LDA(At, 1, 0); PG8_STAGE(PG8_SA(0, 1), a2 + hstep, voffA);
;             PG8_WAIT_V(8); PG8_WAIT_L(0); PG8_BAR; PG8_MMA(0, 0, At, B0); PG8_MMA(0, 1, At, B1); PG8_BAR; PG8_SCHED;
	s_setprio 1
	s_waitcnt lgkmcnt(0)
	v_mfma_f32_16x16x32_bf16 v[60:63], v[152:155], v[184:187], v[60:63]
	v_mfma_f32_16x16x32_bf16 v[56:59], v[160:163], v[184:187], v[56:59]
	v_mfma_f32_16x16x32_bf16 v[44:47], v[152:155], v[192:195], v[44:47]
	v_mfma_f32_16x16x32_bf16 v[40:43], v[160:163], v[192:195], v[40:43]
	v_mfma_f32_16x16x32_bf16 v[28:31], v[152:155], v[200:203], v[28:31]
	v_mfma_f32_16x16x32_bf16 v[24:27], v[160:163], v[200:203], v[24:27]
	v_mfma_f32_16x16x32_bf16 v[12:15], v[152:155], v[208:211], v[12:15]
	v_mfma_f32_16x16x32_bf16 v[8:11], v[160:163], v[208:211], v[8:11]
	v_mfma_f32_16x16x32_bf16 v[60:63], v[156:159], v[188:191], v[60:63]
	v_mfma_f32_16x16x32_bf16 v[56:59], v[164:167], v[188:191], v[56:59]
	v_mfma_f32_16x16x32_bf16 v[44:47], v[156:159], v[196:199], v[44:47]
	v_mfma_f32_16x16x32_bf16 v[40:43], v[164:167], v[196:199], v[40:43]
	v_mfma_f32_16x16x32_bf16 v[28:31], v[156:159], v[204:207], v[28:31]
	v_mfma_f32_16x16x32_bf16 v[24:27], v[164:167], v[204:207], v[24:27]
	v_mfma_f32_16x16x32_bf16 v[12:15], v[156:159], v[212:215], v[12:15]
	v_mfma_f32_16x16x32_bf16 v[8:11], v[164:167], v[212:215], v[8:11]
	s_setprio 0
	s_setprio 1
	v_mfma_f32_16x16x32_bf16 v[52:55], v[168:171], v[184:187], v[52:55]
	v_mfma_f32_16x16x32_bf16 v[48:51], v[176:179], v[184:187], v[48:51]
	v_mfma_f32_16x16x32_bf16 v[36:39], v[168:171], v[192:195], v[36:39]
	v_mfma_f32_16x16x32_bf16 v[32:35], v[176:179], v[192:195], v[32:35]
	v_mfma_f32_16x16x32_bf16 v[20:23], v[168:171], v[200:203], v[20:23]
	v_mfma_f32_16x16x32_bf16 v[16:19], v[176:179], v[200:203], v[16:19]
	v_mfma_f32_16x16x32_bf16 v[4:7], v[168:171], v[208:211], v[4:7]
	v_mfma_f32_16x16x32_bf16 v[0:3], v[176:179], v[208:211], v[0:3]
	v_mfma_f32_16x16x32_bf16 v[52:55], v[172:175], v[188:191], v[52:55]
	v_mfma_f32_16x16x32_bf16 v[48:51], v[180:183], v[188:191], v[48:51]
	v_mfma_f32_16x16x32_bf16 v[36:39], v[172:175], v[196:199], v[36:39]
	v_mfma_f32_16x16x32_bf16 v[32:35], v[180:183], v[196:199], v[32:35]
	v_mfma_f32_16x16x32_bf16 v[20:23], v[172:175], v[204:207], v[20:23]
	v_mfma_f32_16x16x32_bf16 v[16:19], v[180:183], v[204:207], v[16:19]
	v_mfma_f32_16x16x32_bf16 v[4:7], v[172:175], v[212:215], v[4:7]
	v_mfma_f32_16x16x32_bf16 v[0:3], v[180:183], v[212:215], v[0:3]
	s_setprio 0
	s_barrier
	s_add_i32 s50, 0, 0x18000
	s_add_i32 s51, 0, 0x1c000
	v_add_u32_e32 v164, s50, v147
	v_add_u32_e32 v180, s51, v147
	ds_read_b128 v[152:155], v164
	ds_read_b128 v[156:159], v164 offset:1024
	ds_read_b128 v[160:163], v164 offset:2048
	ds_read_b128 v[164:167], v164 offset:3072
	ds_read_b128 v[168:171], v180
	ds_read_b128 v[172:175], v180 offset:1024
	ds_read_b128 v[176:179], v180 offset:2048
	ds_read_b128 v[180:183], v180 offset:3072
	s_add_u32 s26, s26, 0x80000
	s_addc_u32 s27, s27, 0
	s_mov_b32 m0, s34
	v_lshl_add_u64 v[226:227], s[26:27], 0, v[128:129]
	ds_read_b128 v[184:187], v151 offset:32768
	ds_read_b128 v[188:191], v151 offset:33792
	ds_read_b128 v[192:195], v151 offset:34816
	ds_read_b128 v[196:199], v151 offset:35840
	ds_read_b128 v[200:203], v151 offset:36864
	ds_read_b128 v[204:207], v151 offset:37888
	ds_read_b128 v[208:211], v151 offset:38912
	ds_read_b128 v[212:215], v151 offset:39936
	global_load_lds_dwordx4 v[226:227], off
	v_lshl_add_u64 v[226:227], s[26:27], 0, v[132:133]
	s_mov_b32 m0, s35
	s_nop 0
	global_load_lds_dwordx4 v[226:227], off
	s_waitcnt vmcnt(8)
	s_waitcnt lgkmcnt(0)
	s_barrier
	s_setprio 1
	s_waitcnt lgkmcnt(0)
	v_mfma_f32_16x16x32_bf16 v[124:127], v[152:155], v[184:187], v[124:127]
	v_mfma_f32_16x16x32_bf16 v[120:123], v[160:163], v[184:187], v[120:123]
	v_mfma_f32_16x16x32_bf16 v[108:111], v[152:155], v[192:195], v[108:111]
	v_mfma_f32_16x16x32_bf16 v[104:107], v[160:163], v[192:195], v[104:107]
	v_mfma_f32_16x16x32_bf16 v[92:95], v[152:155], v[200:203], v[92:95]
	v_mfma_f32_16x16x32_bf16 v[88:91], v[160:163], v[200:203], v[88:91]
	v_mfma_f32_16x16x32_bf16 v[76:79], v[152:155], v[208:211], v[76:79]
	v_mfma_f32_16x16x32_bf16 v[72:75], v[160:163], v[208:211], v[72:75]
	v_mfma_f32_16x16x32_bf16 v[124:127], v[156:159], v[188:191], v[124:127]
	v_mfma_f32_16x16x32_bf16 v[120:123], v[164:167], v[188:191], v[120:123]
	v_mfma_f32_16x16x32_bf16 v[108:111], v[156:159], v[196:199], v[108:111]
	v_mfma_f32_16x16x32_bf16 v[104:107], v[164:167], v[196:199], v[104:107]
	v_mfma_f32_16x16x32_bf16 v[92:95], v[156:159], v[204:207], v[92:95]
	v_mfma_f32_16x16x32_bf16 v[88:91], v[164:167], v[204:207], v[88:91]
	v_mfma_f32_16x16x32_bf16 v[76:79], v[156:159], v[212:215], v[76:79]
	v_mfma_f32_16x16x32_bf16 v[72:75], v[164:167], v[212:215], v[72:75]
	s_setprio 0
	s_setprio 1
	v_mfma_f32_16x16x32_bf16 v[116:119], v[168:171], v[184:187], v[116:119]
	v_mfma_f32_16x16x32_bf16 v[112:115], v[176:179], v[184:187], v[112:115]
	v_mfma_f32_16x16x32_bf16 v[100:103], v[168:171], v[192:195], v[100:103]
	v_mfma_f32_16x16x32_bf16 v[96:99], v[176:179], v[192:195], v[96:99]
	v_mfma_f32_16x16x32_bf16 v[84:87], v[168:171], v[200:203], v[84:87]
	v_mfma_f32_16x16x32_bf16 v[80:83], v[176:179], v[200:203], v[80:83]
	v_mfma_f32_16x16x32_bf16 v[68:71], v[168:171], v[208:211], v[68:71]
	v_mfma_f32_16x16x32_bf16 v[64:67], v[176:179], v[208:211], v[64:67]
	v_mfma_f32_16x16x32_bf16 v[116:119], v[172:175], v[188:191], v[116:119]
	v_mfma_f32_16x16x32_bf16 v[112:115], v[180:183], v[188:191], v[112:115]
	v_mfma_f32_16x16x32_bf16 v[100:103], v[172:175], v[196:199], v[100:103]
	v_mfma_f32_16x16x32_bf16 v[96:99], v[180:183], v[196:199], v[96:99]
	v_mfma_f32_16x16x32_bf16 v[84:87], v[172:175], v[204:207], v[84:87]
	v_mfma_f32_16x16x32_bf16 v[80:83], v[180:183], v[204:207], v[80:83]
	v_mfma_f32_16x16x32_bf16 v[68:71], v[172:175], v[212:215], v[68:71]
	v_mfma_f32_16x16x32_bf16 v[64:67], v[180:183], v[212:215], v[64:67]
	s_setprio 0
	s_barrier
; #define PG8_STAGE(bufoff, gbase, voff) do { _Pragma("unroll") for (int _i = 0; _i < 2; ++_i) \
;         __builtin_amdgcn_global_load_lds((const unsigned*)((const char*)(gbase) + (voff)[_i]), (PG8_LAS unsigned*)(lds + (bufoff) + ldsw + _i * 8192), 16, 0, 0); } while (0)
; #define PG8_LDA(dst, b, h) do { _Pragma("unroll") for (int m = 0; m < 4; ++m) _Pragma("unroll") for (int k = 0; k < 2; ++k) dst[m][k] = *(const PG8_LAS bf16x8*)(lds + PG8_SA(b, h) + aoff + m * 2048 + k * 1024); } while (0)
; #define PG8_MMA(ai, bj, At, Bt) do { __builtin_amdgcn_s_setprio(1); _Pragma("unroll") for (int m = 0; m < 4; ++m) _Pragma("unroll") for (int n = 0; n < 2; ++n) _Pragma("unroll") for (int k = 0; k < 2; ++k) \
;         acc[ai][bj][m][n] = __builtin_amdgcn_mfma_f32_16x16x32_bf16(Bt[n][k], At[m][k], acc[ai][bj][m][n], 0, 0, 0); __builtin_amdgcn_s_setprio(0); } while (0)
; #define PG8_WAIT_V(n) asm volatile("s_waitcnt vmcnt(" #n ")" ::: "memory")
; #define PG8_WAIT_L(n) asm volatile("s_waitcnt lgkmcnt(" #n ")" ::: "memory")
; #define PG8_BAR __builtin_amdgcn_s_barrier()
; #define PG8_SCHED __builtin_amdgcn_sched_barrier(0)
; template <class Epi, class Sched, bool ALIGN_EPI = false, bool SP2 = false>
; __device__ __forceinline__ void gemm_phase(PG8_LAS unsigned char* lds, const Gemm g, const Sched& S, const Epi& E) {
;     ...
;         for (int t = 0; t < nt; t += 2) {
;             const bool last = (t == nt - 2);
;             const char* a1 = cA + (size_t)(t + 1) * kstep;
;             const char* a2 = last ? nA : cA + (size_t)(t + 2) * kstep; const char* b2 = last ? nB : cB + (size_t)(t + 2) * kstep;
;     ...
;             PG8_LDA(At, 1, 1); PG8_STAGE(PG8_SB(1, 0), b3, voffB); PG8_STAGE(PG8_SB(1, 1), b3 + hstep, voffB); PG8_STAGE(PG8_SA(1, 0), a3, voffA);
;             PG8_WAIT_V(8); PG8_WAIT_L(0); PG8_BAR; PG8_MMA(1, 0, At, B0); PG8_MMA(1, 1, At, B1); PG8_BAR; PG8_SCHED;
	s_add_i32 s26, s50, s31
	v_lshl_add_u64 v[144:145], v[144:145], 0, s[12:13]
	s_mov_b32 m0, s26
	ds_read_b128 v[184:187], v151 offset:49152
	ds_read_b128 v[188:191], v151 offset:50176
	ds_read_b128 v[192:195], v151 offset:51200
	ds_read_b128 v[196:199], v151 offset:52224
	ds_read_b128 v[200:203], v151 offset:53248
	ds_read_b128 v[204:207], v151 offset:54272
	ds_read_b128 v[208:211], v151 offset:55296
	ds_read_b128 v[212:215], v151 offset:56320
	global_load_lds_dwordx4 v[144:145], off
	s_add_i32 m0, s26, 0x2000
	s_add_u32 s10, s10, 0x80080
	v_lshl_add_u64 v[144:145], v[216:217], 0, s[12:13]
	s_addc_u32 s11, s11, 0
	s_add_i32 s26, s51, s31
	global_load_lds_dwordx4 v[144:145], off
	v_lshl_add_u64 v[144:145], s[10:11], 0, v[130:131]
	s_mov_b32 m0, s26
	s_nop 0
	global_load_lds_dwordx4 v[144:145], off
	v_lshl_add_u64 v[144:145], s[10:11], 0, v[134:135]
	s_add_i32 m0, s26, 0x2000
	s_nop 0
	global_load_lds_dwordx4 v[144:145], off
	v_lshl_add_u64 v[144:145], v[222:223], 0, s[12:13]
	s_mov_b32 m0, s37
	s_nop 0
	global_load_lds_dwordx4 v[144:145], off
	v_lshl_add_u64 v[144:145], v[224:225], 0, s[12:13]
	s_mov_b32 m0, s40
	s_nop 0
	global_load_lds_dwordx4 v[144:145], off
	s_waitcnt vmcnt(8)
	s_waitcnt lgkmcnt(0)
	s_barrier
	s_setprio 1
	s_waitcnt lgkmcnt(0)
	v_mfma_f32_16x16x32_bf16 v[60:63], v[152:155], v[184:187], v[60:63]
	v_mfma_f32_16x16x32_bf16 v[56:59], v[160:163], v[184:187], v[56:59]
	v_mfma_f32_16x16x32_bf16 v[44:47], v[152:155], v[192:195], v[44:47]
	v_mfma_f32_16x16x32_bf16 v[40:43], v[160:163], v[192:195], v[40:43]
	v_mfma_f32_16x16x32_bf16 v[28:31], v[152:155], v[200:203], v[28:31]
	v_mfma_f32_16x16x32_bf16 v[24:27], v[160:163], v[200:203], v[24:27]
	v_mfma_f32_16x16x32_bf16 v[12:15], v[152:155], v[208:211], v[12:15]
	v_mfma_f32_16x16x32_bf16 v[8:11], v[160:163], v[208:211], v[8:11]
	v_mfma_f32_16x16x32_bf16 v[60:63], v[156:159], v[188:191], v[60:63]
	v_mfma_f32_16x16x32_bf16 v[56:59], v[164:167], v[188:191], v[56:59]
	v_mfma_f32_16x16x32_bf16 v[44:47], v[156:159], v[196:199], v[44:47]
	v_mfma_f32_16x16x32_bf16 v[40:43], v[164:167], v[196:199], v[40:43]
	v_mfma_f32_16x16x32_bf16 v[28:31], v[156:159], v[204:207], v[28:31]
	v_mfma_f32_16x16x32_bf16 v[24:27], v[164:167], v[204:207], v[24:27]
	v_mfma_f32_16x16x32_bf16 v[12:15], v[156:159], v[212:215], v[12:15]
	v_mfma_f32_16x16x32_bf16 v[8:11], v[164:167], v[212:215], v[8:11]
	s_setprio 0
	s_setprio 1
	v_mfma_f32_16x16x32_bf16 v[52:55], v[168:171], v[184:187], v[52:55]
	v_mfma_f32_16x16x32_bf16 v[48:51], v[176:179], v[184:187], v[48:51]
	v_mfma_f32_16x16x32_bf16 v[36:39], v[168:171], v[192:195], v[36:39]
	v_mfma_f32_16x16x32_bf16 v[32:35], v[176:179], v[192:195], v[32:35]
	v_mfma_f32_16x16x32_bf16 v[20:23], v[168:171], v[200:203], v[20:23]
	v_mfma_f32_16x16x32_bf16 v[16:19], v[176:179], v[200:203], v[16:19]
	v_mfma_f32_16x16x32_bf16 v[4:7], v[168:171], v[208:211], v[4:7]
	v_mfma_f32_16x16x32_bf16 v[0:3], v[176:179], v[208:211], v[0:3]
	v_mfma_f32_16x16x32_bf16 v[52:55], v[172:175], v[188:191], v[52:55]
	v_mfma_f32_16x16x32_bf16 v[48:51], v[180:183], v[188:191], v[48:51]
	v_mfma_f32_16x16x32_bf16 v[36:39], v[172:175], v[196:199], v[36:39]
	v_mfma_f32_16x16x32_bf16 v[32:35], v[180:183], v[196:199], v[32:35]
	v_mfma_f32_16x16x32_bf16 v[20:23], v[172:175], v[204:207], v[20:23]
	v_mfma_f32_16x16x32_bf16 v[16:19], v[180:183], v[204:207], v[16:19]
	v_mfma_f32_16x16x32_bf16 v[4:7], v[172:175], v[212:215], v[4:7]
	v_mfma_f32_16x16x32_bf16 v[0:3], v[180:183], v[212:215], v[0:3]
	s_add_i32 s49, s49, 2
	s_add_u32 s8, s8, 0x100
	s_addc_u32 s9, s9, 0
	s_add_u32 s47, s47, 0x100
	s_addc_u32 s48, s48, 0
	s_cmp_gt_u32 s49, 29
	s_setprio 0
	s_barrier
	s_cbranch_scc0 .LBB0_2248
	s_and_b64 vcc, exec, s[14:15]
	s_cbranch_vccz .LBB0_2251
	s_barrier
